# GLA pass A / pass C: the full vmcnt drains at item boundaries (they only waited for the previous item's result stores) are dropped
# speedup vs baseline: 1.0056x; 1.0056x over previous
; DEVINL int tidx() { int t = threadIdx.x; asm volatile("" : "+v"(t)); return t; }
; DEVINL void gla_passC(const Params& p, char* smem, int item) {
;   const ChunkInfo ci = chunk_info(item);
;   const int tid = tidx(), lane = tid & 63, w = tid >> 6;
;   const u16* qk = (const u16*)(p.ws + OFF_QK);
;   const u16* vT = (const u16*)(p.ws + OFF_VT);
;   const u16* SpT = (const u16*)(p.ws + OFF_SPT) + (size_t)item * 8192;
;   const u16* gbuf = (const u16*)(p.ws + OFF_GB);
;   u16 qraw[16], kraw16[16];
; #pragma unroll
;   for (int i = 0; i < 16; ++i) {
;     const int t = 16 * w + i;
;     qraw[i] = qk[(size_t)(ci.r0 + t) * 512 + ci.h * 64 + lane];
;     kraw16[i] = qk[(size_t)(ci.r0 + t) * 512 + 256 + ci.h * 64 + lane];
;   }
;   bf16x8 bvv[2][2], bss[2][2];
; #pragma unroll
;   for (int ks = 0; ks < 2; ++ks) {
;     const int kb = ks * 32 + 8 * (lane >> 4);
; #pragma unroll
;     for (int nf = 0; nf < 2; ++nf) {
;       const int dv = 32 * w + nf * 16 + (lane & 15);
;       bvv[ks][nf] = *(const bf16x8*)(vT + (size_t)(ci.h * 128 + dv) * LDT + ci.r0 + kb);
;       bss[ks][nf] = *(const bf16x8*)(SpT + dv * 64 + kb);
;     }
;   }
.LBB0_393:
	s_or_b64 exec, exec, s[0:1]
	v_mov_b32_e32 v143, v0
	v_and_b32_e32 v36, 3, v4
	v_ashrrev_i32_e32 v150, 6, v143
	v_lshlrev_b32_e32 v59, 4, v150
	v_add_u32_e32 v4, v59, v52
	v_ashrrev_i32_e32 v5, 31, v4
	v_lshlrev_b64 v[6:7], 10, v[4:5]
	v_and_b32_e32 v149, 63, v143
	v_lshl_add_u64 v[6:7], s[94:95], 0, v[6:7]
	v_lshlrev_b32_e32 v54, 7, v36
	v_mov_b32_e32 v55, v2
	v_lshl_add_u64 v[6:7], v[6:7], 0, v[54:55]
	v_lshlrev_b32_e32 v8, 1, v149
	v_mov_b32_e32 v9, v2
	v_lshl_add_u64 v[86:87], v[6:7], 0, v[8:9]
	v_add_u32_e32 v6, 1, v4
	v_ashrrev_i32_e32 v7, 31, v6
	v_lshlrev_b64 v[6:7], 10, v[6:7]
	v_lshl_add_u64 v[6:7], s[94:95], 0, v[6:7]
	v_lshl_add_u64 v[6:7], v[6:7], 0, v[54:55]
	v_lshl_add_u64 v[76:77], v[6:7], 0, v[8:9]
	v_add_u32_e32 v6, 2, v4
	v_ashrrev_i32_e32 v7, 31, v6
	v_lshlrev_b64 v[6:7], 10, v[6:7]
	v_lshl_add_u64 v[6:7], s[94:95], 0, v[6:7]
	v_lshl_add_u64 v[6:7], v[6:7], 0, v[54:55]
	v_lshl_add_u64 v[64:65], v[6:7], 0, v[8:9]
	v_add_u32_e32 v6, 3, v4
	v_ashrrev_i32_e32 v7, 31, v6
	v_lshlrev_b64 v[6:7], 10, v[6:7]
	v_lshl_add_u64 v[6:7], s[94:95], 0, v[6:7]
	v_lshl_add_u64 v[6:7], v[6:7], 0, v[54:55]
	v_lshl_add_u64 v[40:41], v[6:7], 0, v[8:9]
	v_add_u32_e32 v6, 4, v4
	v_ashrrev_i32_e32 v7, 31, v6
	v_lshlrev_b64 v[6:7], 10, v[6:7]
	v_lshl_add_u64 v[6:7], s[94:95], 0, v[6:7]
	v_lshl_add_u64 v[6:7], v[6:7], 0, v[54:55]
	v_lshl_add_u64 v[42:43], v[6:7], 0, v[8:9]
	v_add_u32_e32 v6, 5, v4
	v_ashrrev_i32_e32 v7, 31, v6
	v_lshlrev_b64 v[6:7], 10, v[6:7]
	v_lshl_add_u64 v[6:7], s[94:95], 0, v[6:7]
	v_lshl_add_u64 v[6:7], v[6:7], 0, v[54:55]
	v_lshl_add_u64 v[60:61], v[6:7], 0, v[8:9]
	v_add_u32_e32 v6, 6, v4
	v_ashrrev_i32_e32 v7, 31, v6
	v_lshlrev_b64 v[6:7], 10, v[6:7]
	v_lshl_add_u64 v[6:7], s[94:95], 0, v[6:7]
	v_lshl_add_u64 v[6:7], v[6:7], 0, v[54:55]
	v_lshl_add_u64 v[62:63], v[6:7], 0, v[8:9]
	v_add_u32_e32 v6, 7, v4
	v_ashrrev_i32_e32 v7, 31, v6
	v_lshlrev_b64 v[6:7], 10, v[6:7]
	v_lshl_add_u64 v[6:7], s[94:95], 0, v[6:7]
	v_lshl_add_u64 v[6:7], v[6:7], 0, v[54:55]
	v_lshl_add_u64 v[66:67], v[6:7], 0, v[8:9]
	v_add_u32_e32 v6, 8, v4
	v_ashrrev_i32_e32 v7, 31, v6
	v_lshlrev_b64 v[6:7], 10, v[6:7]
	v_lshl_add_u64 v[6:7], s[94:95], 0, v[6:7]
	v_lshl_add_u64 v[6:7], v[6:7], 0, v[54:55]
	v_lshl_add_u64 v[68:69], v[6:7], 0, v[8:9]
	v_add_u32_e32 v6, 9, v4
	v_ashrrev_i32_e32 v7, 31, v6
	v_lshlrev_b64 v[6:7], 10, v[6:7]
	v_lshl_add_u64 v[6:7], s[94:95], 0, v[6:7]
	v_lshl_add_u64 v[6:7], v[6:7], 0, v[54:55]
	v_lshl_add_u64 v[70:71], v[6:7], 0, v[8:9]
	v_add_u32_e32 v6, 10, v4
	v_ashrrev_i32_e32 v7, 31, v6
	v_lshlrev_b64 v[6:7], 10, v[6:7]
	v_lshl_add_u64 v[6:7], s[94:95], 0, v[6:7]
	v_lshl_add_u64 v[6:7], v[6:7], 0, v[54:55]
	v_lshl_add_u64 v[72:73], v[6:7], 0, v[8:9]
	v_add_u32_e32 v6, 11, v4
	v_ashrrev_i32_e32 v7, 31, v6
	v_lshlrev_b64 v[6:7], 10, v[6:7]
	v_lshl_add_u64 v[6:7], s[94:95], 0, v[6:7]
	v_lshl_add_u64 v[6:7], v[6:7], 0, v[54:55]
	v_lshl_add_u64 v[74:75], v[6:7], 0, v[8:9]
	v_add_u32_e32 v6, 12, v4
	v_ashrrev_i32_e32 v7, 31, v6
	v_lshlrev_b64 v[6:7], 10, v[6:7]
	v_lshl_add_u64 v[6:7], s[94:95], 0, v[6:7]
	v_lshl_add_u64 v[6:7], v[6:7], 0, v[54:55]
	v_lshl_add_u64 v[78:79], v[6:7], 0, v[8:9]
	v_add_u32_e32 v6, 13, v4
	v_ashrrev_i32_e32 v7, 31, v6
	v_lshlrev_b64 v[6:7], 10, v[6:7]
	v_lshl_add_u64 v[6:7], s[94:95], 0, v[6:7]
	v_lshl_add_u64 v[6:7], v[6:7], 0, v[54:55]
	v_lshl_add_u64 v[80:81], v[6:7], 0, v[8:9]
	v_add_u32_e32 v6, 14, v4
	v_add_u32_e32 v4, 15, v4
	v_ashrrev_i32_e32 v7, 31, v6
	v_ashrrev_i32_e32 v5, 31, v4
	v_lshlrev_b64 v[6:7], 10, v[6:7]
	v_lshlrev_b64 v[4:5], 10, v[4:5]
	v_lshl_add_u64 v[6:7], s[94:95], 0, v[6:7]
	v_lshl_add_u64 v[4:5], s[94:95], 0, v[4:5]
	v_lshlrev_b32_e32 v56, 5, v150
	v_and_b32_e32 v148, 15, v143
	v_lshl_add_u64 v[6:7], v[6:7], 0, v[54:55]
	v_lshl_add_u64 v[4:5], v[4:5], 0, v[54:55]
	v_or_b32_e32 v58, v56, v148
	v_lshl_add_u64 v[82:83], v[6:7], 0, v[8:9]
	v_lshl_add_u64 v[84:85], v[4:5], 0, v[8:9]
	v_lshlrev_b32_e32 v8, 6, v58
	v_ashrrev_i32_e32 v9, 31, v8
	v_readlane_b32 s0, v194, 35
	v_and_b32_e32 v38, 48, v143
	v_lshlrev_b64 v[8:9], 1, v[8:9]
	v_ashrrev_i32_e32 v53, 31, v52
	v_readlane_b32 s1, v194, 36
	v_or_b32_e32 v8, v8, v38
	v_mov_b32_e32 v39, v2
	v_lshl_add_u64 v[4:5], v[52:53], 1, s[0:1]
	v_lshl_add_u64 v[20:21], v[48:49], 0, v[8:9]
	v_or_b32_e32 v8, 16, v58
	v_add_u32_e32 v6, v58, v54
	v_lshl_add_u64 v[4:5], v[4:5], 0, v[38:39]
	v_add_u32_e32 v9, v8, v54
	v_lshrrev_b32_e32 v37, 2, v143
	v_mad_i64_i32 v[6:7], s[0:1], v6, s88, v[4:5]
	v_mad_i64_i32 v[22:23], s[0:1], v9, s88, v[4:5]
	v_lshlrev_b32_e32 v4, 6, v8
	v_and_b32_e32 v55, 12, v37
	v_lshlrev_b32_e32 v36, 8, v36
	v_mov_b32_e32 v37, v2
	v_ashrrev_i32_e32 v5, 31, v4
	v_add_u32_e32 v88, v55, v52
	v_ashrrev_i32_e32 v57, 31, v56
	v_lshl_add_u64 v[36:37], s[92:93], 0, v[36:37]
	v_lshlrev_b64 v[4:5], 1, v[4:5]
	v_lshl_add_u64 v[90:91], v[56:57], 1, v[36:37]
	v_lshlrev_b32_e32 v36, 1, v148
	v_mov_b32_e32 v37, v2
	v_ashrrev_i32_e32 v89, 31, v88
	v_or_b32_e32 v4, v4, v38
	v_lshl_add_u64 v[90:91], v[90:91], 0, v[36:37]
	v_lshlrev_b64 v[106:107], 10, v[88:89]
	v_lshl_add_u64 v[24:25], v[48:49], 0, v[4:5]
	v_lshl_add_u64 v[106:107], v[90:91], 0, v[106:107]
	global_load_dwordx4 v[12:15], v[6:7], off
	global_load_dwordx4 v[16:19], v[20:21], off
	global_load_dwordx4 v[28:31], v[22:23], off
	global_load_dwordx4 v[32:35], v[24:25], off
	global_load_dwordx4 v[8:11], v[6:7], off offset:64
	s_nop 0
	global_load_dwordx4 v[4:7], v[20:21], off offset:64
	s_nop 0
	global_load_dwordx4 v[20:23], v[22:23], off offset:64
	s_nop 0
	global_load_dwordx4 v[24:27], v[24:25], off offset:64
	s_nop 0
	global_load_ushort v147, v[106:107], off
; DEVINL void gla_passC(const Params& p, char* smem, int item) {
;     ...
;   u16 qraw[16], kraw16[16];
; #pragma unroll
;   for (int i = 0; i < 16; ++i) {
;     const int t = 16 * w + i;
;     qraw[i] = qk[(size_t)(ci.r0 + t) * 512 + ci.h * 64 + lane];
;     kraw16[i] = qk[(size_t)(ci.r0 + t) * 512 + 256 + ci.h * 64 + lane];
;   }
;   bf16x8 bvv[2][2], bss[2][2];
; #pragma unroll
;   for (int ks = 0; ks < 2; ++ks) {
;     const int kb = ks * 32 + 8 * (lane >> 4);
; #pragma unroll
;     for (int nf = 0; nf < 2; ++nf) {
;       const int dv = 32 * w + nf * 16 + (lane & 15);
;       bvv[ks][nf] = *(const bf16x8*)(vT + (size_t)(ci.h * 128 + dv) * LDT + ci.r0 + kb);
;       bss[ks][nf] = *(const bf16x8*)(SpT + dv * 64 + kb);
;     }
;   }
;   u16 graw[4][2][4];
; #pragma unroll
;   for (int mf = 0; mf < 4; ++mf) {
;     const int t0 = mf * 16 + (lane >> 4) * 4;
; #pragma unroll
;     for (int nf = 0; nf < 2; ++nf)
; #pragma unroll
;       for (int j = 0; j < 4; ++j)
;         graw[mf][nf][j] = gbuf[(size_t)(ci.r0 + t0 + j) * 512 + ci.h * 128 + 32 * w + nf * 16 + (lane & 15)];
;   }
;   float bcum[16];
;   {
;     const float* bc = (const float*)(p.ws + OFF_BCUM) + (size_t)item * 4096;
; #pragma unroll
;     for (int i = 0; i < 16; ++i) bcum[i] = bc[(16 * w + i) * 64 + lane];
;   }
;   __syncthreads();
	global_load_ushort v146, v[106:107], off offset:1024
	global_load_ushort v145, v[106:107], off offset:2048
	global_load_ushort v144, v[106:107], off offset:3072
	global_load_ushort v142, v[106:107], off offset:32
	global_load_ushort v141, v[106:107], off offset:1056
	global_load_ushort v140, v[106:107], off offset:2080
	global_load_ushort v139, v[106:107], off offset:3104
	v_add_u32_e32 v106, 16, v88
	v_add_u32_e32 v108, 17, v88
	v_add_u32_e32 v110, 18, v88
	v_add_u32_e32 v112, 19, v88
	v_ashrrev_i32_e32 v107, 31, v106
	v_ashrrev_i32_e32 v109, 31, v108
	v_ashrrev_i32_e32 v111, 31, v110
	v_ashrrev_i32_e32 v113, 31, v112
	v_lshlrev_b64 v[106:107], 10, v[106:107]
	v_lshlrev_b64 v[108:109], 10, v[108:109]
	v_lshlrev_b64 v[110:111], 10, v[110:111]
	v_lshlrev_b64 v[112:113], 10, v[112:113]
	v_lshl_add_u64 v[106:107], v[90:91], 0, v[106:107]
	v_lshl_add_u64 v[108:109], v[90:91], 0, v[108:109]
	v_lshl_add_u64 v[110:111], v[90:91], 0, v[110:111]
	v_lshl_add_u64 v[112:113], v[90:91], 0, v[112:113]
	global_load_ushort v138, v[106:107], off
	global_load_ushort v137, v[108:109], off
	global_load_ushort v136, v[110:111], off
	global_load_ushort v135, v[112:113], off
	global_load_ushort v134, v[106:107], off offset:32
	global_load_ushort v133, v[108:109], off offset:32
	global_load_ushort v132, v[110:111], off offset:32
	global_load_ushort v131, v[112:113], off offset:32
	v_add_u32_e32 v106, 32, v88
	v_ashrrev_i32_e32 v107, 31, v106
	v_lshlrev_b64 v[106:107], 10, v[106:107]
	v_lshl_add_u64 v[152:153], v[90:91], 0, v[106:107]
	v_add_u32_e32 v106, 33, v88
	v_ashrrev_i32_e32 v107, 31, v106
	v_lshlrev_b64 v[106:107], 10, v[106:107]
	v_lshl_add_u64 v[154:155], v[90:91], 0, v[106:107]
	v_add_u32_e32 v106, 34, v88
	v_ashrrev_i32_e32 v107, 31, v106
	v_lshlrev_b64 v[106:107], 10, v[106:107]
	v_lshl_add_u64 v[156:157], v[90:91], 0, v[106:107]
	v_add_u32_e32 v106, 35, v88
	v_lshl_or_b32 v160, v150, 10, v149
	v_ashrrev_i32_e32 v107, 31, v106
	v_ashrrev_i32_e32 v161, 31, v160
	v_lshlrev_b64 v[106:107], 10, v[106:107]
	v_lshl_add_u64 v[160:161], v[160:161], 2, v[48:49]
	s_mov_b32 s0, 0x4be0000
	v_lshl_add_u64 v[158:159], v[90:91], 0, v[106:107]
	v_add_co_u32_e32 v160, vcc, s0, v160
	global_load_ushort v113, v[152:153], off
	global_load_ushort v111, v[154:155], off
	global_load_ushort v109, v[156:157], off
	global_load_ushort v107, v[158:159], off
	v_addc_co_u32_e32 v161, vcc, 0, v161, vcc
	global_load_ushort v151, v[86:87], off
	global_load_dword v162, v[160:161], off
	global_load_ushort v112, v[152:153], off offset:32
	global_load_ushort v110, v[154:155], off offset:32
	global_load_ushort v163, v[86:87], off offset:512
	global_load_ushort v108, v[156:157], off offset:32
	global_load_ushort v106, v[158:159], off offset:32
	v_add_u32_e32 v86, 48, v88
	v_ashrrev_i32_e32 v87, 31, v86
	v_lshlrev_b64 v[86:87], 10, v[86:87]
	v_lshl_add_u64 v[152:153], v[90:91], 0, v[86:87]
	v_add_u32_e32 v86, 49, v88
	v_ashrrev_i32_e32 v87, 31, v86
	v_lshlrev_b64 v[86:87], 10, v[86:87]
	v_lshl_add_u64 v[154:155], v[90:91], 0, v[86:87]
	global_load_ushort v89, v[152:153], off
	global_load_ushort v86, v[154:155], off
	global_load_ushort v158, v[76:77], off
	global_load_dword v159, v[160:161], off offset:256
	v_add_u32_e32 v156, 50, v88
	v_ashrrev_i32_e32 v157, 31, v156
	v_lshlrev_b64 v[156:157], 10, v[156:157]
	v_lshl_add_u64 v[156:157], v[90:91], 0, v[156:157]
	global_load_ushort v164, v[76:77], off offset:512
	global_load_ushort v87, v[156:157], off
	v_add_u32_e32 v76, 51, v88
	v_ashrrev_i32_e32 v77, 31, v76
	v_lshlrev_b64 v[76:77], 10, v[76:77]
	v_lshl_add_u64 v[90:91], v[90:91], 0, v[76:77]
	global_load_ushort v77, v[90:91], off
	global_load_ushort v76, v[152:153], off offset:32
	global_load_ushort v57, v[154:155], off offset:32
	global_load_ushort v53, v[156:157], off offset:32
	global_load_ushort v47, v[90:91], off offset:32
	global_load_dword v88, v[160:161], off offset:512
	s_nop 0
	global_load_dword v90, v[160:161], off offset:768
	global_load_dword v91, v[160:161], off offset:1024
	global_load_ushort v152, v[64:65], off
	global_load_dword v153, v[160:161], off offset:1280
	s_nop 0
	global_load_ushort v64, v[64:65], off offset:512
	s_nop 0
	global_load_dword v65, v[160:161], off offset:1536
	global_load_dword v154, v[160:161], off offset:1792
	global_load_dword v155, v[160:161], off offset:2048
	global_load_dword v156, v[160:161], off offset:2304
	global_load_dword v157, v[160:161], off offset:2560
	global_load_dword v165, v[160:161], off offset:2816
	global_load_dword v166, v[160:161], off offset:3072
	global_load_dword v167, v[160:161], off offset:3328
	global_load_dword v39, v[160:161], off offset:3584
	global_load_dword v37, v[160:161], off offset:3840
	s_nop 0
	global_load_ushort v160, v[40:41], off
	global_load_ushort v161, v[40:41], off offset:512
	global_load_ushort v168, v[42:43], off
	s_nop 0
	global_load_ushort v42, v[42:43], off offset:512
	s_nop 0
	global_load_ushort v43, v[60:61], off
	s_nop 0
	global_load_ushort v60, v[60:61], off offset:512
	s_nop 0
	global_load_ushort v61, v[62:63], off
	s_nop 0
	global_load_ushort v62, v[62:63], off offset:512
	s_nop 0
	global_load_ushort v63, v[66:67], off
	s_nop 0
	global_load_ushort v66, v[66:67], off offset:512
	s_nop 0
	global_load_ushort v67, v[68:69], off
	s_nop 0
	global_load_ushort v68, v[68:69], off offset:512
	s_nop 0
	global_load_ushort v69, v[70:71], off
	s_nop 0
	global_load_ushort v70, v[70:71], off offset:512
	s_nop 0
	global_load_ushort v71, v[72:73], off
	s_nop 0
	global_load_ushort v72, v[72:73], off offset:512
	s_nop 0
	global_load_ushort v73, v[74:75], off
	s_nop 0
	global_load_ushort v74, v[74:75], off offset:512
	s_nop 0
	global_load_ushort v75, v[78:79], off
	s_nop 0
	global_load_ushort v78, v[78:79], off offset:512
	s_nop 0
	global_load_ushort v79, v[80:81], off
	s_nop 0
	global_load_ushort v80, v[80:81], off offset:512
	s_nop 0
	global_load_ushort v81, v[82:83], off
	s_nop 0
	global_load_ushort v82, v[82:83], off offset:512
	s_nop 0
	global_load_ushort v41, v[84:85], off
	global_load_ushort v40, v[84:85], off offset:512
	v_cmp_lt_i32_e32 vcc, v59, v45
	s_movk_i32 s0, 0x480
	s_waitcnt vmcnt(63) expcnt(7) lgkmcnt(15)
	s_barrier
; DEVINL u16 f2bf(float f) { return (u16)((__float_as_uint(f) + 0x8000u) >> 16); }
; DEVINL float bf2f(u16 h) { return __uint_as_float(((unsigned)h) << 16); }
; DEVINL void gla_passC(const Params& p, char* smem, int item) {
;     ...
; #pragma unroll
;   for (int i = 0; i < 16; ++i) {
;     const int t = 16 * w + i;
;     const float qv = (t < ci.T) ? bf2f(qraw[i]) : 0.f, kv = (t < ci.T) ? bf2f(kraw16[i]) : 0.f;
;     const float bt = bcum[i];
;     Qd[t * 72 + lane] = f2bf(qv * __expf(bt));
;     Ki[t * 72 + lane] = f2bf(kv * __expf(-bt));
;   }
	s_movk_i32 s34, 0x90
	s_waitcnt vmcnt(36)
	v_lshlrev_b32_e32 v64, 16, v64
	v_lshlrev_b32_e32 v83, 16, v151
	v_mul_f32_e32 v84, 0x3fb8aa3b, v162
	v_exp_f32_e32 v84, v84
	v_cndmask_b32_e32 v83, 0, v83, vcc
	v_lshlrev_b32_e32 v85, 16, v163
	v_cndmask_b32_e32 v85, 0, v85, vcc
	v_mul_f32_e32 v83, v83, v84
	v_mul_lo_u32 v84, v150, s0
	v_mul_f32_e32 v150, 0xbfb8aa3b, v162
	v_exp_f32_e32 v150, v150
	v_or_b32_e32 v84, v84, v149
	v_add_u32_e32 v83, 0x8000, v83
	v_lshlrev_b32_e32 v84, 1, v84
	ds_write_b16_d16_hi v84, v83 offset:22016
	v_mul_f32_e32 v83, v85, v150
	v_add_u32_e32 v83, 0x8000, v83
	ds_write_b16_d16_hi v84, v83 offset:31232
	v_mul_f32_e32 v85, 0x3fb8aa3b, v159
	v_exp_f32_e32 v85, v85
	v_or_b32_e32 v83, 1, v59
	v_cmp_lt_i32_e32 vcc, v83, v45
	v_lshlrev_b32_e32 v84, 16, v158
	s_movk_i32 s0, 0x48
	v_cndmask_b32_e32 v84, 0, v84, vcc
	v_mul_f32_e32 v84, v84, v85
	v_mul_f32_e32 v85, 0xbfb8aa3b, v159
	v_exp_f32_e32 v85, v85
	v_lshlrev_b32_e32 v150, 16, v164
	v_mul_lo_u32 v83, v83, s0
	v_cndmask_b32_e32 v150, 0, v150, vcc
	v_add_u32_e32 v84, 0x8000, v84
	v_add_lshl_u32 v83, v83, v149, 1
	ds_write_b16_d16_hi v83, v84 offset:22016
	v_mul_f32_e32 v84, v150, v85
	v_mul_f32_e32 v85, 0x3fb8aa3b, v88
	v_mul_f32_e32 v88, 0xbfb8aa3b, v88
	v_add_u32_e32 v84, 0x8000, v84
	v_exp_f32_e32 v85, v85
	v_exp_f32_e32 v88, v88
	ds_write_b16_d16_hi v83, v84 offset:31232
	v_or_b32_e32 v84, 2, v59
	v_cmp_lt_i32_e32 vcc, v84, v45
	v_lshlrev_b32_e32 v84, 16, v152
	s_waitcnt vmcnt(22)
	v_lshlrev_b32_e32 v42, 16, v42
	v_cndmask_b32_e32 v84, 0, v84, vcc
	v_cndmask_b32_e32 v64, 0, v64, vcc
	v_mul_f32_e32 v84, v84, v85
	v_mul_f32_e32 v64, v64, v88
	v_mul_f32_e32 v85, 0x3fb8aa3b, v90
	v_add_u32_e32 v64, 0x8000, v64
	v_exp_f32_e32 v85, v85
	ds_write_b16_d16_hi v83, v64 offset:31376
	v_or_b32_e32 v64, 3, v59
	v_mul_f32_e32 v88, 0xbfb8aa3b, v90
	v_cmp_lt_i32_e32 vcc, v64, v45
	v_lshlrev_b32_e32 v64, 16, v160
	v_exp_f32_e32 v88, v88
	v_add_u32_e32 v84, 0x8000, v84
	v_cndmask_b32_e32 v64, 0, v64, vcc
	ds_write_b16_d16_hi v83, v84 offset:22160
	v_lshlrev_b32_e32 v84, 16, v161
	v_mul_f32_e32 v64, v64, v85
	v_cndmask_b32_e32 v84, 0, v84, vcc
	v_add_u32_e32 v64, 0x8000, v64
	ds_write_b16_d16_hi v83, v64 offset:22304
	v_mul_f32_e32 v64, v84, v88
	v_mul_f32_e32 v85, 0xbfb8aa3b, v91
	v_add_u32_e32 v64, 0x8000, v64
	v_exp_f32_e32 v85, v85
	ds_write_b16_d16_hi v83, v64 offset:31520
	v_or_b32_e32 v64, 4, v59
	v_cmp_lt_i32_e32 vcc, v64, v45
	v_mul_f32_e32 v84, 0x3fb8aa3b, v91
	v_exp_f32_e32 v84, v84
	v_cndmask_b32_e32 v42, 0, v42, vcc
	v_mul_f32_e32 v42, v42, v85
	v_lshlrev_b32_e32 v64, 16, v168
	v_add_u32_e32 v42, 0x8000, v42
	v_cndmask_b32_e32 v64, 0, v64, vcc
	ds_write_b16_d16_hi v83, v42 offset:31664
	v_or_b32_e32 v42, 5, v59
	v_mul_f32_e32 v64, v64, v84
	v_cmp_lt_i32_e32 vcc, v42, v45
	s_waitcnt vmcnt(21)
	v_lshlrev_b32_e32 v42, 16, v43
	s_waitcnt vmcnt(20)
	v_lshlrev_b32_e32 v43, 16, v60
	v_mul_f32_e32 v60, 0x3fb8aa3b, v153
	v_add_u32_e32 v64, 0x8000, v64
	v_exp_f32_e32 v60, v60
	ds_write_b16_d16_hi v83, v64 offset:22448
	v_mul_f32_e32 v64, 0xbfb8aa3b, v153
	v_exp_f32_e32 v64, v64
	v_cndmask_b32_e32 v42, 0, v42, vcc
	v_mul_f32_e32 v42, v42, v60
	v_cndmask_b32_e32 v43, 0, v43, vcc
	v_add_u32_e32 v42, 0x8000, v42
	ds_write_b16_d16_hi v83, v42 offset:22592
	v_mul_f32_e32 v42, v43, v64
	v_add_u32_e32 v42, 0x8000, v42
	v_mul_f32_e32 v60, 0x3fb8aa3b, v65
	ds_write_b16_d16_hi v83, v42 offset:31808
	v_or_b32_e32 v42, 6, v59
	v_exp_f32_e32 v60, v60
	v_cmp_lt_i32_e32 vcc, v42, v45
	s_waitcnt vmcnt(19)
	v_lshlrev_b32_e32 v42, 16, v61
	v_mul_f32_e32 v61, 0xbfb8aa3b, v65
	v_exp_f32_e32 v61, v61
	v_cndmask_b32_e32 v42, 0, v42, vcc
	s_waitcnt vmcnt(18)
	v_lshlrev_b32_e32 v43, 16, v62
	v_mul_f32_e32 v42, v42, v60
	v_cndmask_b32_e32 v43, 0, v43, vcc
	v_add_u32_e32 v42, 0x8000, v42
	ds_write_b16_d16_hi v83, v42 offset:22736
	v_mul_f32_e32 v42, v43, v61
	v_mul_f32_e32 v60, 0x3fb8aa3b, v154
	v_add_u32_e32 v42, 0x8000, v42
	v_exp_f32_e32 v60, v60
	ds_write_b16_d16_hi v83, v42 offset:31952
	v_or_b32_e32 v42, 7, v59
	v_mul_f32_e32 v61, 0xbfb8aa3b, v154
	v_cmp_lt_i32_e32 vcc, v42, v45
	s_waitcnt vmcnt(17)
	v_lshlrev_b32_e32 v42, 16, v63
	v_exp_f32_e32 v61, v61
	v_cndmask_b32_e32 v42, 0, v42, vcc
	s_waitcnt vmcnt(16)
	v_lshlrev_b32_e32 v43, 16, v66
	v_mul_f32_e32 v42, v42, v60
	v_cndmask_b32_e32 v43, 0, v43, vcc
	v_add_u32_e32 v42, 0x8000, v42
	ds_write_b16_d16_hi v83, v42 offset:22880
	v_mul_f32_e32 v42, v43, v61
	v_mul_f32_e32 v60, 0x3fb8aa3b, v155
	v_add_u32_e32 v42, 0x8000, v42
	v_exp_f32_e32 v60, v60
	ds_write_b16_d16_hi v83, v42 offset:32096
	v_or_b32_e32 v42, 8, v59
	v_mul_f32_e32 v61, 0xbfb8aa3b, v155
	v_cmp_lt_i32_e32 vcc, v42, v45
	s_waitcnt vmcnt(15)
	v_lshlrev_b32_e32 v42, 16, v67
	v_exp_f32_e32 v61, v61
	v_cndmask_b32_e32 v42, 0, v42, vcc
	s_waitcnt vmcnt(14)
	v_lshlrev_b32_e32 v43, 16, v68
	v_mul_f32_e32 v42, v42, v60
	v_cndmask_b32_e32 v43, 0, v43, vcc
	v_add_u32_e32 v42, 0x8000, v42
	ds_write_b16_d16_hi v83, v42 offset:23024
	v_mul_f32_e32 v42, v43, v61
	v_mul_f32_e32 v60, 0x3fb8aa3b, v156
	v_add_u32_e32 v42, 0x8000, v42
	v_exp_f32_e32 v60, v60
	ds_write_b16_d16_hi v83, v42 offset:32240
	v_or_b32_e32 v42, 9, v59
	v_mul_f32_e32 v61, 0xbfb8aa3b, v156
	v_cmp_lt_i32_e32 vcc, v42, v45
	s_waitcnt vmcnt(13)
	v_lshlrev_b32_e32 v42, 16, v69
	v_exp_f32_e32 v61, v61
	v_cndmask_b32_e32 v42, 0, v42, vcc
	s_waitcnt vmcnt(12)
	v_lshlrev_b32_e32 v43, 16, v70
	v_mul_f32_e32 v42, v42, v60
	v_cndmask_b32_e32 v43, 0, v43, vcc
	v_add_u32_e32 v42, 0x8000, v42
	ds_write_b16_d16_hi v83, v42 offset:23168
	v_mul_f32_e32 v42, v43, v61
	v_mul_f32_e32 v60, 0x3fb8aa3b, v157
	v_add_u32_e32 v42, 0x8000, v42
	v_exp_f32_e32 v60, v60
	ds_write_b16_d16_hi v83, v42 offset:32384
	v_or_b32_e32 v42, 10, v59
	v_mul_f32_e32 v61, 0xbfb8aa3b, v157
	v_cmp_lt_i32_e32 vcc, v42, v45
	s_waitcnt vmcnt(11)
; DEVINL u16 f2bf(float f) { return (u16)((__float_as_uint(f) + 0x8000u) >> 16); }
; DEVINL float bf2f(u16 h) { return __uint_as_float(((unsigned)h) << 16); }
; DEVINL f32x4 mfma16(bf16x8 a, bf16x8 b, f32x4 c) { return __builtin_amdgcn_mfma_f32_16x16x32_bf16(a, b, c, 0, 0, 0); }
; DEVINL void gla_passC(const Params& p, char* smem, int item) {
;     ...
; #pragma unroll
;   for (int i = 0; i < 16; ++i) {
;     const int t = 16 * w + i;
;     const float qv = (t < ci.T) ? bf2f(qraw[i]) : 0.f, kv = (t < ci.T) ? bf2f(kraw16[i]) : 0.f;
;     const float bt = bcum[i];
;     Qd[t * 72 + lane] = f2bf(qv * __expf(bt));
;     Ki[t * 72 + lane] = f2bf(kv * __expf(-bt));
;   }
;   __syncthreads();
;   {
;     f32x4 at[4];
; #pragma unroll
;     for (int nf = 0; nf < 4; ++nf) at[nf] = f32x4{0, 0, 0, 0};
; #pragma unroll
;     for (int ks = 0; ks < 2; ++ks) {
;       bf16x8 a = *(const bf16x8*)(Qd + (16 * w + (lane & 15)) * 72 + ks * 32 + 8 * (lane >> 4));
; #pragma unroll
;       for (int nf = 0; nf < 4; ++nf) {
;         bf16x8 b = *(const bf16x8*)(Ki + (nf * 16 + (lane & 15)) * 72 + ks * 32 + 8 * (lane >> 4));
;         at[nf] = mfma16(a, b, at[nf]);
;       }
;     }
; #pragma unroll
;     for (int nf = 0; nf < 4; ++nf)
; #pragma unroll
;       for (int j = 0; j < 4; ++j) {
;         int t = 16 * w + (lane >> 4) * 4 + j, s = nf * 16 + (lane & 15);
;         Att[t * 72 + s] = f2bf((s <= t) ? at[nf][j] : 0.f);
;       }
	v_lshlrev_b32_e32 v42, 16, v71
	v_exp_f32_e32 v61, v61
	v_cndmask_b32_e32 v42, 0, v42, vcc
	s_waitcnt vmcnt(10)
	v_lshlrev_b32_e32 v43, 16, v72
	v_mul_f32_e32 v42, v42, v60
	v_cndmask_b32_e32 v43, 0, v43, vcc
	v_add_u32_e32 v42, 0x8000, v42
	ds_write_b16_d16_hi v83, v42 offset:23312
	v_mul_f32_e32 v42, v43, v61
	v_mul_f32_e32 v60, 0x3fb8aa3b, v165
	v_add_u32_e32 v42, 0x8000, v42
	v_exp_f32_e32 v60, v60
	ds_write_b16_d16_hi v83, v42 offset:32528
	v_or_b32_e32 v42, 11, v59
	v_mul_f32_e32 v61, 0xbfb8aa3b, v165
	v_cmp_lt_i32_e32 vcc, v42, v45
	s_waitcnt vmcnt(9)
	v_lshlrev_b32_e32 v42, 16, v73
	v_exp_f32_e32 v61, v61
	v_cndmask_b32_e32 v42, 0, v42, vcc
	s_waitcnt vmcnt(8)
	v_lshlrev_b32_e32 v43, 16, v74
	v_mul_f32_e32 v42, v42, v60
	v_cndmask_b32_e32 v43, 0, v43, vcc
	v_add_u32_e32 v42, 0x8000, v42
	ds_write_b16_d16_hi v83, v42 offset:23456
	v_mul_f32_e32 v42, v43, v61
	v_mul_f32_e32 v60, 0x3fb8aa3b, v166
	v_add_u32_e32 v42, 0x8000, v42
	v_exp_f32_e32 v60, v60
	ds_write_b16_d16_hi v83, v42 offset:32672
	v_or_b32_e32 v42, 12, v59
	v_mul_f32_e32 v61, 0xbfb8aa3b, v166
	v_cmp_lt_i32_e32 vcc, v42, v45
	s_waitcnt vmcnt(7)
	v_lshlrev_b32_e32 v42, 16, v75
	v_exp_f32_e32 v61, v61
	v_cndmask_b32_e32 v42, 0, v42, vcc
	s_waitcnt vmcnt(6)
	v_lshlrev_b32_e32 v43, 16, v78
	v_mul_f32_e32 v42, v42, v60
	v_cndmask_b32_e32 v43, 0, v43, vcc
	v_add_u32_e32 v42, 0x8000, v42
	ds_write_b16_d16_hi v83, v42 offset:23600
	v_mul_f32_e32 v42, v43, v61
	v_mul_f32_e32 v60, 0x3fb8aa3b, v167
	v_add_u32_e32 v42, 0x8000, v42
	v_exp_f32_e32 v60, v60
	ds_write_b16_d16_hi v83, v42 offset:32816
	v_or_b32_e32 v42, 13, v59
	v_mul_f32_e32 v61, 0xbfb8aa3b, v167
	v_cmp_lt_i32_e32 vcc, v42, v45
	s_waitcnt vmcnt(5)
	v_lshlrev_b32_e32 v42, 16, v79
	v_exp_f32_e32 v61, v61
	v_cndmask_b32_e32 v42, 0, v42, vcc
	s_waitcnt vmcnt(4)
	v_lshlrev_b32_e32 v43, 16, v80
	v_mul_f32_e32 v42, v42, v60
	v_cndmask_b32_e32 v43, 0, v43, vcc
	v_add_u32_e32 v42, 0x8000, v42
	ds_write_b16_d16_hi v83, v42 offset:23744
	v_mul_f32_e32 v42, v43, v61
	v_mul_f32_e32 v60, 0x3fb8aa3b, v39
	v_mul_f32_e32 v39, 0xbfb8aa3b, v39
	v_add_u32_e32 v42, 0x8000, v42
	v_exp_f32_e32 v39, v39
	ds_write_b16_d16_hi v83, v42 offset:32960
	v_or_b32_e32 v42, 14, v59
	v_cmp_lt_i32_e32 vcc, v42, v45
	s_waitcnt vmcnt(2)
	v_lshlrev_b32_e32 v43, 16, v82
	v_lshlrev_b32_e32 v42, 16, v81
	v_cndmask_b32_e32 v43, 0, v43, vcc
	v_mul_f32_e32 v39, v43, v39
	v_add_u32_e32 v39, 0x8000, v39
	ds_write_b16_d16_hi v83, v39 offset:33104
	v_or_b32_e32 v39, 15, v59
	v_cndmask_b32_e32 v42, 0, v42, vcc
	v_cmp_lt_i32_e32 vcc, v39, v45
	s_waitcnt vmcnt(1)
	v_lshlrev_b32_e32 v39, 16, v41
	v_mul_f32_e32 v41, 0x3fb8aa3b, v37
	v_mul_f32_e32 v37, 0xbfb8aa3b, v37
	v_exp_f32_e32 v37, v37
	v_exp_f32_e32 v41, v41
	v_exp_f32_e32 v60, v60
	s_waitcnt vmcnt(0)
	v_lshlrev_b32_e32 v40, 16, v40
	v_cndmask_b32_e32 v40, 0, v40, vcc
	v_cndmask_b32_e32 v39, 0, v39, vcc
	v_mul_f32_e32 v37, v40, v37
	v_mul_f32_e32 v39, v39, v41
	v_add_u32_e32 v37, 0x8000, v37
	v_mul_f32_e32 v42, v42, v60
	v_add_u32_e32 v39, 0x8000, v39
	ds_write_b16_d16_hi v83, v37 offset:33248
	v_or_b32_e32 v37, v59, v148
	v_add_u32_e32 v42, 0x8000, v42
	v_mad_u64_u32 v[78:79], s[0:1], v37, s34, v[38:39]
	ds_write_b16_d16_hi v83, v42 offset:23888
	ds_write_b16_d16_hi v83, v39 offset:24032
	s_waitcnt lgkmcnt(0)
	s_barrier
	ds_read_b128 v[40:43], v78 offset:22016
	v_mul_u32_u24_e32 v37, 0x48, v148
	v_lshl_add_u32 v88, v37, 1, v38
	ds_read_b128 v[60:63], v88 offset:31232
	ds_read_b128 v[64:67], v88 offset:33536
	ds_read_b128 v[68:71], v88 offset:35840
	ds_read_b128 v[72:75], v88 offset:38144
	ds_read_b128 v[78:81], v78 offset:22080
	s_waitcnt lgkmcnt(4)
	v_mfma_f32_16x16x32_bf16 v[60:63], v[40:43], v[60:63], 0
	v_or_b32_e32 v59, v59, v55
	v_cmp_le_i32_e32 vcc, v148, v59
	v_or_b32_e32 v37, 16, v148
	s_waitcnt lgkmcnt(3)
	v_mfma_f32_16x16x32_bf16 v[64:67], v[40:43], v[64:67], 0
	s_waitcnt lgkmcnt(2)
	v_mfma_f32_16x16x32_bf16 v[68:71], v[40:43], v[68:71], 0
	s_waitcnt lgkmcnt(1)
	v_mfma_f32_16x16x32_bf16 v[38:41], v[40:43], v[72:75], 0
	ds_read_b128 v[72:75], v88 offset:31296
	v_or_b32_e32 v42, 32, v148
	v_or_b32_e32 v43, 48, v148
	s_waitcnt lgkmcnt(0)
	v_mfma_f32_16x16x32_bf16 v[60:63], v[78:81], v[72:75], v[60:63]
	ds_read_b128 v[72:75], v88 offset:33600
	s_waitcnt lgkmcnt(0)
	v_mfma_f32_16x16x32_bf16 v[64:67], v[78:81], v[72:75], v[64:67]
	ds_read_b128 v[72:75], v88 offset:35904
	ds_read_b128 v[82:85], v88 offset:38208
	s_nop 2
	v_add_u32_e32 v60, 0x8000, v60
	v_lshrrev_b32_e32 v60, 16, v60
	s_waitcnt lgkmcnt(1)
	v_mfma_f32_16x16x32_bf16 v[68:71], v[78:81], v[72:75], v[68:71]
	v_mul_lo_u32 v72, v59, s34
	v_cndmask_b32_e32 v60, 0, v60, vcc
	v_or_b32_e32 v36, v72, v36
	ds_write_b16 v36, v60 offset:40448
	v_or_b32_e32 v60, 1, v59
	v_add_u32_e32 v61, 0x8000, v61
	v_lshrrev_b32_e32 v61, 16, v61
	v_cmp_le_i32_e32 vcc, v148, v60
	v_add_u32_e32 v62, 0x8000, v62
	v_lshrrev_b32_e32 v62, 16, v62
	v_cndmask_b32_e32 v61, 0, v61, vcc
	ds_write_b16 v36, v61 offset:40592
	v_or_b32_e32 v61, 2, v59
	v_cmp_le_i32_e32 vcc, v148, v61
	v_add_u32_e32 v63, 0x8000, v63
	v_lshrrev_b32_e32 v63, 16, v63
	v_cndmask_b32_e32 v62, 0, v62, vcc
	ds_write_b16 v36, v62 offset:40736
	v_or_b32_e32 v62, 3, v59
	v_cmp_le_i32_e32 vcc, v148, v62
	s_waitcnt lgkmcnt(3)
; DEVINL u16 f2bf(float f) { return (u16)((__float_as_uint(f) + 0x8000u) >> 16); }
; DEVINL f32x4 mfma16(bf16x8 a, bf16x8 b, f32x4 c) { return __builtin_amdgcn_mfma_f32_16x16x32_bf16(a, b, c, 0, 0, 0); }
; DEVINL void gla_passC(const Params& p, char* smem, int item) {
;     ...
; #pragma unroll
;     for (int nf = 0; nf < 4; ++nf)
; #pragma unroll
;       for (int j = 0; j < 4; ++j) {
;         int t = 16 * w + (lane >> 4) * 4 + j, s = nf * 16 + (lane & 15);
;         Att[t * 72 + s] = f2bf((s <= t) ? at[nf][j] : 0.f);
;       }
;   }
;   __syncthreads();
;   f32x4 o[4][2];
; #pragma unroll
;   for (int a = 0; a < 4; ++a) { o[a][0] = f32x4{0, 0, 0, 0}; o[a][1] = f32x4{0, 0, 0, 0}; }
; #pragma unroll
;   for (int ks = 0; ks < 2; ++ks) {
;     const int kb = ks * 32 + 8 * (lane >> 4);
;     bf16x8 bv[2], bs[2];
; #pragma unroll
;     for (int nf = 0; nf < 2; ++nf) { bv[nf] = bvv[ks][nf]; bs[nf] = bss[ks][nf]; }
; #pragma unroll
;     for (int mf = 0; mf < 4; ++mf) {
;       bf16x8 aa = *(const bf16x8*)(Att + (mf * 16 + (lane & 15)) * 72 + kb);
;       bf16x8 aq = *(const bf16x8*)(Qd + (mf * 16 + (lane & 15)) * 72 + kb);
; #pragma unroll
;       for (int nf = 0; nf < 2; ++nf) {
;         o[mf][nf] = mfma16(aa, bv[nf], o[mf][nf]);
;         o[mf][nf] = mfma16(aq, bs[nf], o[mf][nf]);
;       }
;     }
;   }
	v_mfma_f32_16x16x32_bf16 v[38:41], v[78:81], v[82:85], v[38:41]
	v_cmp_lt_u32_e64 s[34:35], v55, v45
	v_cndmask_b32_e32 v63, 0, v63, vcc
	ds_write_b16 v36, v63 offset:40880
	v_add_u32_e32 v63, 0x8000, v64
	v_lshrrev_b32_e32 v63, 16, v63
	v_cmp_le_i32_e32 vcc, v37, v59
	s_nop 1
	v_cndmask_b32_e32 v63, 0, v63, vcc
	ds_write_b16 v36, v63 offset:40480
	v_add_u32_e32 v63, 0x8000, v65
	v_lshrrev_b32_e32 v63, 16, v63
	v_cmp_le_i32_e32 vcc, v37, v60
	s_nop 1
	v_cndmask_b32_e32 v63, 0, v63, vcc
	ds_write_b16 v36, v63 offset:40624
	v_add_u32_e32 v63, 0x8000, v66
	v_lshrrev_b32_e32 v63, 16, v63
	v_cmp_le_i32_e32 vcc, v37, v61
	s_nop 1
	v_cndmask_b32_e32 v63, 0, v63, vcc
	ds_write_b16 v36, v63 offset:40768
	v_add_u32_e32 v63, 0x8000, v67
	v_lshrrev_b32_e32 v63, 16, v63
	v_cmp_le_i32_e32 vcc, v37, v62
	s_nop 1
	v_cndmask_b32_e32 v37, 0, v63, vcc
	ds_write_b16 v36, v37 offset:40912
	v_add_u32_e32 v37, 0x8000, v68
	v_lshrrev_b32_e32 v37, 16, v37
	v_cmp_le_i32_e32 vcc, v42, v59
	s_nop 1
	v_cndmask_b32_e32 v37, 0, v37, vcc
	ds_write_b16 v36, v37 offset:40512
	v_add_u32_e32 v37, 0x8000, v69
	v_lshrrev_b32_e32 v37, 16, v37
	v_cmp_le_i32_e32 vcc, v42, v60
	s_nop 1
	v_cndmask_b32_e32 v37, 0, v37, vcc
	ds_write_b16 v36, v37 offset:40656
	v_add_u32_e32 v37, 0x8000, v70
	v_lshrrev_b32_e32 v37, 16, v37
	v_cmp_le_i32_e32 vcc, v42, v61
	s_nop 1
	v_cndmask_b32_e32 v37, 0, v37, vcc
	ds_write_b16 v36, v37 offset:40800
	v_add_u32_e32 v37, 0x8000, v71
	v_lshrrev_b32_e32 v37, 16, v37
	v_cmp_le_i32_e32 vcc, v42, v62
	s_nop 1
	v_cndmask_b32_e32 v37, 0, v37, vcc
	ds_write_b16 v36, v37 offset:40944
	v_add_u32_e32 v37, 0x8000, v38
	v_lshrrev_b32_e32 v37, 16, v37
	v_cmp_le_i32_e32 vcc, v43, v59
	v_ashrrev_i32_e32 v59, 31, v58
	s_nop 0
	v_cndmask_b32_e32 v37, 0, v37, vcc
	ds_write_b16 v36, v37 offset:40544
	v_add_u32_e32 v37, 0x8000, v39
	v_lshrrev_b32_e32 v37, 16, v37
	v_cmp_le_i32_e32 vcc, v43, v60
	s_nop 1
	v_cndmask_b32_e32 v37, 0, v37, vcc
	ds_write_b16 v36, v37 offset:40688
	v_add_u32_e32 v37, 0x8000, v40
	v_lshrrev_b32_e32 v37, 16, v37
	v_cmp_le_i32_e32 vcc, v43, v61
	s_nop 1
	v_cndmask_b32_e32 v37, 0, v37, vcc
	ds_write_b16 v36, v37 offset:40832
	v_add_u32_e32 v37, 0x8000, v41
	v_lshrrev_b32_e32 v37, 16, v37
	v_cmp_le_i32_e32 vcc, v43, v62
	s_nop 1
	v_cndmask_b32_e32 v37, 0, v37, vcc
	ds_write_b16 v36, v37 offset:40976
	s_waitcnt lgkmcnt(0)
	s_barrier
	ds_read_b128 v[36:39], v88 offset:40448
	ds_read_b128 v[60:63], v88 offset:22016
	s_waitcnt lgkmcnt(1)
	v_mfma_f32_16x16x32_bf16 v[40:43], v[36:39], v[12:15], 0
	ds_read_b128 v[68:71], v88 offset:24320
	ds_read_b128 v[78:81], v88 offset:26624
	ds_read_b128 v[82:85], v88 offset:28928
	v_mfma_f32_16x16x32_bf16 v[36:39], v[36:39], v[28:31], 0
	s_waitcnt lgkmcnt(3)
	v_mfma_f32_16x16x32_bf16 v[40:43], v[60:63], v[16:19], v[40:43]
	v_mfma_f32_16x16x32_bf16 v[36:39], v[60:63], v[32:35], v[36:39]
	ds_read_b128 v[60:63], v88 offset:42752
	s_waitcnt lgkmcnt(0)
	v_mfma_f32_16x16x32_bf16 v[64:67], v[60:63], v[12:15], 0
	v_mfma_f32_16x16x32_bf16 v[60:63], v[60:63], v[28:31], 0
	v_mfma_f32_16x16x32_bf16 v[64:67], v[68:71], v[16:19], v[64:67]
	v_mfma_f32_16x16x32_bf16 v[60:63], v[68:71], v[32:35], v[60:63]
	ds_read_b128 v[68:71], v88 offset:45056
	s_waitcnt lgkmcnt(0)
	v_mfma_f32_16x16x32_bf16 v[72:75], v[68:71], v[12:15], 0
	v_mfma_f32_16x16x32_bf16 v[68:71], v[68:71], v[28:31], 0
	v_mfma_f32_16x16x32_bf16 v[72:75], v[78:81], v[16:19], v[72:75]
	v_mfma_f32_16x16x32_bf16 v[68:71], v[78:81], v[32:35], v[68:71]
	ds_read_b128 v[78:81], v88 offset:47360
	s_waitcnt lgkmcnt(0)
	v_mfma_f32_16x16x32_bf16 v[12:15], v[78:81], v[12:15], 0
	v_mfma_f32_16x16x32_bf16 v[148:151], v[82:85], v[16:19], v[12:15]
	v_mfma_f32_16x16x32_bf16 v[12:15], v[78:81], v[28:31], 0
	ds_read_b128 v[28:31], v88 offset:22080
	v_mfma_f32_16x16x32_bf16 v[78:81], v[82:85], v[32:35], v[12:15]
	s_nop 5
	ds_read_b128 v[12:15], v88 offset:40512
	s_waitcnt lgkmcnt(0)
	v_mfma_f32_16x16x32_bf16 v[16:19], v[12:15], v[8:11], v[40:43]
	v_mfma_f32_16x16x32_bf16 v[12:15], v[12:15], v[20:23], v[36:39]
	v_mfma_f32_16x16x32_bf16 v[36:39], v[28:31], v[24:27], v[12:15]
	v_mfma_f32_16x16x32_bf16 v[40:43], v[28:31], v[4:7], v[16:19]
	s_nop 5
	ds_read_b128 v[12:15], v88 offset:42816
	ds_read_b128 v[28:31], v88 offset:24384
	s_waitcnt lgkmcnt(1)
	v_mfma_f32_16x16x32_bf16 v[16:19], v[12:15], v[8:11], v[64:67]
	s_nop 2
	ds_read_b128 v[64:67], v88 offset:28992
	v_mfma_f32_16x16x32_bf16 v[12:15], v[12:15], v[20:23], v[60:63]
	s_waitcnt lgkmcnt(1)
	v_mfma_f32_16x16x32_bf16 v[32:35], v[28:31], v[4:7], v[16:19]
	s_nop 0
	ds_read_b128 v[60:63], v88 offset:26688
	v_mfma_f32_16x16x32_bf16 v[28:31], v[28:31], v[24:27], v[12:15]
	s_nop 2
	ds_read_b128 v[12:15], v88 offset:45120
	s_waitcnt lgkmcnt(0)
	v_mfma_f32_16x16x32_bf16 v[16:19], v[12:15], v[8:11], v[72:75]
	v_mfma_f32_16x16x32_bf16 v[12:15], v[12:15], v[20:23], v[68:71]
	v_mfma_f32_16x16x32_bf16 v[16:19], v[60:63], v[4:7], v[16:19]
	v_mfma_f32_16x16x32_bf16 v[12:15], v[60:63], v[24:27], v[12:15]
	ds_read_b128 v[60:63], v88 offset:47424
	s_waitcnt lgkmcnt(0)
; DEVINL void gla_passC(const Params& p, char* smem, int item) {
;     ...
; #pragma unroll
;   for (int mf = 0; mf < 4; ++mf)
; #pragma unroll
;     for (int j = 0; j < 4; ++j) {
;       const float s = red16(o[mf][0][j] * o[mf][0][j] + o[mf][1][j] * o[mf][1][j]);
;       red[w * 64 + mf * 16 + (lane >> 4) * 4 + j] = s;
;     }
	v_mfma_f32_16x16x32_bf16 v[8:11], v[60:63], v[8:11], v[148:151]
	v_mfma_f32_16x16x32_bf16 v[8:11], v[64:67], v[4:7], v[8:11]
	v_mfma_f32_16x16x32_bf16 v[4:7], v[60:63], v[20:23], v[78:81]
	v_and_b32_e32 v20, 0x3fffffc0, v143
	v_lshlrev_b32_e32 v23, 2, v55
	v_lshl_or_b32 v22, v20, 2, v23
	v_mfma_f32_16x16x32_bf16 v[4:7], v[64:67], v[24:27], v[4:7]
	v_mul_f32_e64 v24, v36, v36
	v_mul_f32_e64 v25, v37, v37
	v_pk_mul_f32 v[20:21], v[38:39], v[38:39]
	v_pk_fma_f32 v[24:25], v[40:41], v[40:41], v[24:25]
	v_pk_fma_f32 v[20:21], v[42:43], v[42:43], v[20:21]
	s_nop 0
	v_mov_b32_dpp v26, v24 quad_perm:[1,0,3,2] row_mask:0xf bank_mask:0xf bound_ctrl:1
	v_mov_b32_dpp v27, v25 quad_perm:[1,0,3,2] row_mask:0xf bank_mask:0xf bound_ctrl:1
	v_pk_add_f32 v[24:25], v[24:25], v[26:27]
	s_nop 1
	v_mov_b32_dpp v26, v24 quad_perm:[2,3,0,1] row_mask:0xf bank_mask:0xf bound_ctrl:1
	v_mov_b32_dpp v27, v25 quad_perm:[2,3,0,1] row_mask:0xf bank_mask:0xf bound_ctrl:1
	v_pk_add_f32 v[24:25], v[24:25], v[26:27]
	s_nop 1
	v_mov_b32_dpp v26, v24 row_half_mirror row_mask:0xf bank_mask:0xf bound_ctrl:1
	v_mov_b32_dpp v27, v25 row_half_mirror row_mask:0xf bank_mask:0xf bound_ctrl:1
	v_pk_add_f32 v[24:25], v[24:25], v[26:27]
	s_nop 1
	v_mov_b32_dpp v26, v24 row_mirror row_mask:0xf bank_mask:0xf bound_ctrl:1
	v_mov_b32_dpp v27, v25 row_mirror row_mask:0xf bank_mask:0xf bound_ctrl:1
	v_pk_add_f32 v[24:25], v[24:25], v[26:27]
	v_mov_b32_dpp v26, v20 quad_perm:[1,0,3,2] row_mask:0xf bank_mask:0xf bound_ctrl:1
	v_mov_b32_dpp v27, v21 quad_perm:[1,0,3,2] row_mask:0xf bank_mask:0xf bound_ctrl:1
	v_pk_add_f32 v[20:21], v[20:21], v[26:27]
	s_nop 1
	v_mov_b32_dpp v26, v20 quad_perm:[2,3,0,1] row_mask:0xf bank_mask:0xf bound_ctrl:1
	v_mov_b32_dpp v27, v21 quad_perm:[2,3,0,1] row_mask:0xf bank_mask:0xf bound_ctrl:1
	v_pk_add_f32 v[20:21], v[20:21], v[26:27]
	s_nop 1
	v_mov_b32_dpp v26, v20 row_half_mirror row_mask:0xf bank_mask:0xf bound_ctrl:1
	v_mov_b32_dpp v27, v21 row_half_mirror row_mask:0xf bank_mask:0xf bound_ctrl:1
	v_pk_add_f32 v[20:21], v[20:21], v[26:27]
	s_nop 1
	v_mov_b32_dpp v26, v20 row_mirror row_mask:0xf bank_mask:0xf bound_ctrl:1
	v_mov_b32_dpp v27, v21 row_mirror row_mask:0xf bank_mask:0xf bound_ctrl:1
	v_pk_add_f32 v[26:27], v[20:21], v[26:27]
	ds_write_b128 v22, v[24:27] offset:49664
	v_pk_mul_f32 v[24:25], v[28:29], v[28:29]
	v_pk_mul_f32 v[20:21], v[30:31], v[30:31]
	v_pk_fma_f32 v[24:25], v[32:33], v[32:33], v[24:25]
	v_pk_fma_f32 v[20:21], v[34:35], v[34:35], v[20:21]
	s_nop 0
	v_mov_b32_dpp v26, v24 quad_perm:[1,0,3,2] row_mask:0xf bank_mask:0xf bound_ctrl:1
	v_mov_b32_dpp v27, v25 quad_perm:[1,0,3,2] row_mask:0xf bank_mask:0xf bound_ctrl:1
	v_pk_add_f32 v[24:25], v[24:25], v[26:27]
	s_nop 1
	v_mov_b32_dpp v26, v24 quad_perm:[2,3,0,1] row_mask:0xf bank_mask:0xf bound_ctrl:1
	v_mov_b32_dpp v27, v25 quad_perm:[2,3,0,1] row_mask:0xf bank_mask:0xf bound_ctrl:1
	v_pk_add_f32 v[24:25], v[24:25], v[26:27]
	s_nop 1
	v_mov_b32_dpp v26, v24 row_half_mirror row_mask:0xf bank_mask:0xf bound_ctrl:1
	v_mov_b32_dpp v27, v25 row_half_mirror row_mask:0xf bank_mask:0xf bound_ctrl:1
	v_pk_add_f32 v[24:25], v[24:25], v[26:27]
	s_nop 1
	v_mov_b32_dpp v26, v24 row_mirror row_mask:0xf bank_mask:0xf bound_ctrl:1
	v_mov_b32_dpp v27, v25 row_mirror row_mask:0xf bank_mask:0xf bound_ctrl:1
	v_pk_add_f32 v[24:25], v[24:25], v[26:27]
	v_mov_b32_dpp v26, v20 quad_perm:[1,0,3,2] row_mask:0xf bank_mask:0xf bound_ctrl:1
	v_mov_b32_dpp v27, v21 quad_perm:[1,0,3,2] row_mask:0xf bank_mask:0xf bound_ctrl:1
	v_pk_add_f32 v[20:21], v[20:21], v[26:27]
	s_nop 1
	v_mov_b32_dpp v26, v20 quad_perm:[2,3,0,1] row_mask:0xf bank_mask:0xf bound_ctrl:1
	v_mov_b32_dpp v27, v21 quad_perm:[2,3,0,1] row_mask:0xf bank_mask:0xf bound_ctrl:1
	v_pk_add_f32 v[20:21], v[20:21], v[26:27]
	s_nop 1
	v_mov_b32_dpp v26, v20 row_half_mirror row_mask:0xf bank_mask:0xf bound_ctrl:1
	v_mov_b32_dpp v27, v21 row_half_mirror row_mask:0xf bank_mask:0xf bound_ctrl:1
	v_pk_add_f32 v[20:21], v[20:21], v[26:27]
	s_nop 1
	v_mov_b32_dpp v26, v20 row_mirror row_mask:0xf bank_mask:0xf bound_ctrl:1
	v_mov_b32_dpp v27, v21 row_mirror row_mask:0xf bank_mask:0xf bound_ctrl:1
	v_pk_add_f32 v[26:27], v[20:21], v[26:27]
	ds_write_b128 v22, v[24:27] offset:49728
	v_pk_mul_f32 v[24:25], v[12:13], v[12:13]
	v_pk_mul_f32 v[20:21], v[14:15], v[14:15]
	v_pk_fma_f32 v[24:25], v[16:17], v[16:17], v[24:25]
	v_pk_fma_f32 v[20:21], v[18:19], v[18:19], v[20:21]
	s_nop 0
	v_mov_b32_dpp v26, v24 quad_perm:[1,0,3,2] row_mask:0xf bank_mask:0xf bound_ctrl:1
	v_mov_b32_dpp v27, v25 quad_perm:[1,0,3,2] row_mask:0xf bank_mask:0xf bound_ctrl:1
	v_pk_add_f32 v[24:25], v[24:25], v[26:27]
	s_nop 1
	v_mov_b32_dpp v26, v24 quad_perm:[2,3,0,1] row_mask:0xf bank_mask:0xf bound_ctrl:1
	v_mov_b32_dpp v27, v25 quad_perm:[2,3,0,1] row_mask:0xf bank_mask:0xf bound_ctrl:1
	v_pk_add_f32 v[24:25], v[24:25], v[26:27]
	s_nop 1
	v_mov_b32_dpp v26, v24 row_half_mirror row_mask:0xf bank_mask:0xf bound_ctrl:1
	v_mov_b32_dpp v27, v25 row_half_mirror row_mask:0xf bank_mask:0xf bound_ctrl:1
	v_pk_add_f32 v[24:25], v[24:25], v[26:27]
	s_nop 1
	v_mov_b32_dpp v26, v24 row_mirror row_mask:0xf bank_mask:0xf bound_ctrl:1
	v_mov_b32_dpp v27, v25 row_mirror row_mask:0xf bank_mask:0xf bound_ctrl:1
	v_pk_add_f32 v[24:25], v[24:25], v[26:27]
	v_mov_b32_dpp v26, v20 quad_perm:[1,0,3,2] row_mask:0xf bank_mask:0xf bound_ctrl:1
	v_mov_b32_dpp v27, v21 quad_perm:[1,0,3,2] row_mask:0xf bank_mask:0xf bound_ctrl:1
	v_pk_add_f32 v[20:21], v[20:21], v[26:27]
	s_nop 1
	v_mov_b32_dpp v26, v20 quad_perm:[2,3,0,1] row_mask:0xf bank_mask:0xf bound_ctrl:1
	v_mov_b32_dpp v27, v21 quad_perm:[2,3,0,1] row_mask:0xf bank_mask:0xf bound_ctrl:1
; DEVINL void gla_passC(const Params& p, char* smem, int item) {
;     ...
; #pragma unroll
;   for (int mf = 0; mf < 4; ++mf)
; #pragma unroll
;     for (int j = 0; j < 4; ++j) {
;       const float s = red16(o[mf][0][j] * o[mf][0][j] + o[mf][1][j] * o[mf][1][j]);
;       red[w * 64 + mf * 16 + (lane >> 4) * 4 + j] = s;
;     }
;   __syncthreads();
;   u16* mixin = (u16*)(p.ws + OFF_MIXIN);
;   float gn[2];
; #pragma unroll
;   for (int nf = 0; nf < 2; ++nf) gn[nf] = p.gla_norm[32 * w + nf * 16 + (lane & 15)];
; #pragma unroll
;   for (int mf = 0; mf < 4; ++mf) {
;     const int t0 = mf * 16 + (lane >> 4) * 4;
;     if (t0 < ci.T) {
	v_pk_add_f32 v[20:21], v[20:21], v[26:27]
	s_nop 1
	v_mov_b32_dpp v26, v20 row_half_mirror row_mask:0xf bank_mask:0xf bound_ctrl:1
	v_mov_b32_dpp v27, v21 row_half_mirror row_mask:0xf bank_mask:0xf bound_ctrl:1
	v_pk_add_f32 v[20:21], v[20:21], v[26:27]
	s_nop 1
	v_mov_b32_dpp v26, v20 row_mirror row_mask:0xf bank_mask:0xf bound_ctrl:1
	v_mov_b32_dpp v27, v21 row_mirror row_mask:0xf bank_mask:0xf bound_ctrl:1
	v_pk_add_f32 v[26:27], v[20:21], v[26:27]
	ds_write_b128 v22, v[24:27] offset:49792
	v_pk_mul_f32 v[24:25], v[4:5], v[4:5]
	v_pk_mul_f32 v[20:21], v[6:7], v[6:7]
	v_pk_fma_f32 v[24:25], v[8:9], v[8:9], v[24:25]
	v_pk_fma_f32 v[20:21], v[10:11], v[10:11], v[20:21]
	s_nop 0
	v_mov_b32_dpp v26, v24 quad_perm:[1,0,3,2] row_mask:0xf bank_mask:0xf bound_ctrl:1
	v_mov_b32_dpp v27, v25 quad_perm:[1,0,3,2] row_mask:0xf bank_mask:0xf bound_ctrl:1
	v_pk_add_f32 v[24:25], v[24:25], v[26:27]
	s_nop 1
	v_mov_b32_dpp v26, v24 quad_perm:[2,3,0,1] row_mask:0xf bank_mask:0xf bound_ctrl:1
	v_mov_b32_dpp v27, v25 quad_perm:[2,3,0,1] row_mask:0xf bank_mask:0xf bound_ctrl:1
	v_pk_add_f32 v[24:25], v[24:25], v[26:27]
	s_nop 1
	v_mov_b32_dpp v26, v24 row_half_mirror row_mask:0xf bank_mask:0xf bound_ctrl:1
	v_mov_b32_dpp v27, v25 row_half_mirror row_mask:0xf bank_mask:0xf bound_ctrl:1
	v_pk_add_f32 v[24:25], v[24:25], v[26:27]
	s_nop 1
	v_mov_b32_dpp v26, v24 row_mirror row_mask:0xf bank_mask:0xf bound_ctrl:1
	v_mov_b32_dpp v27, v25 row_mirror row_mask:0xf bank_mask:0xf bound_ctrl:1
	v_pk_add_f32 v[24:25], v[24:25], v[26:27]
	v_mov_b32_dpp v26, v20 quad_perm:[1,0,3,2] row_mask:0xf bank_mask:0xf bound_ctrl:1
	v_mov_b32_dpp v27, v21 quad_perm:[1,0,3,2] row_mask:0xf bank_mask:0xf bound_ctrl:1
	v_pk_add_f32 v[20:21], v[20:21], v[26:27]
	s_nop 1
	v_mov_b32_dpp v26, v20 quad_perm:[2,3,0,1] row_mask:0xf bank_mask:0xf bound_ctrl:1
	v_mov_b32_dpp v27, v21 quad_perm:[2,3,0,1] row_mask:0xf bank_mask:0xf bound_ctrl:1
	v_pk_add_f32 v[20:21], v[20:21], v[26:27]
	s_nop 1
	v_mov_b32_dpp v26, v20 row_half_mirror row_mask:0xf bank_mask:0xf bound_ctrl:1
	v_mov_b32_dpp v27, v21 row_half_mirror row_mask:0xf bank_mask:0xf bound_ctrl:1
	v_pk_add_f32 v[20:21], v[20:21], v[26:27]
	s_nop 1
	v_mov_b32_dpp v26, v20 row_mirror row_mask:0xf bank_mask:0xf bound_ctrl:1
	v_mov_b32_dpp v27, v21 row_mirror row_mask:0xf bank_mask:0xf bound_ctrl:1
	v_pk_add_f32 v[26:27], v[20:21], v[26:27]
	v_lshl_add_u64 v[20:21], v[58:59], 2, s[72:73]
	ds_write_b128 v22, v[24:27] offset:49856
	s_waitcnt lgkmcnt(0)
	s_barrier
	global_load_dword v24, v[20:21], off
	global_load_dword v22, v[20:21], off offset:64
	v_and_or_b32 v20, v143, 14, v54
	v_add_u32_e32 v20, v20, v56
	v_and_b32_e32 v21, 1, v143
	v_cmp_eq_u32_e32 vcc, 0, v21
	v_lshl_add_u32 v25, v21, 1, v52
	v_ashrrev_i32_e32 v21, 31, v20
	s_and_saveexec_b64 s[46:47], s[34:35]
	s_cbranch_execz .LBB0_395
; DEVINL float bf2f(u16 h) { return __uint_as_float(((unsigned)h) << 16); }
; DEVINL float siluf_(float x) { return x * __builtin_amdgcn_rcpf(1.f + __expf(-x)); }
; DEVINL void gla_passC(const Params& p, char* smem, int item) {
;     ...
;   for (int mf = 0; mf < 4; ++mf) {
;     const int t0 = mf * 16 + (lane >> 4) * 4;
;     if (t0 < ci.T) {
;       float rs[4];
; #pragma unroll
;       for (int j = 0; j < 4; ++j) {
;         const int t = t0 + j;
;         rs[j] = rsqrtf((red[t] + red[64 + t] + red[128 + t] + red[192 + t]) * (1.f / 128.f) + EPS);
;       }
; #pragma unroll
;       for (int nf = 0; nf < 2; ++nf) {
;         const int dv = 32 * w + nf * 16 + (lane & 15);
;         float o4[4];
; #pragma unroll
;         for (int j = 0; j < 4; ++j) {
;           float gv = bf2f(graw[mf][nf][j]);
;           o4[j] = o[mf][nf][j] * rs[j] * gn[nf] * siluf_(gv);
;         }
;         store_pairs(mixin, 1024, ci.r0 + t0, ci.h * 128 + dv, o4[0], o4[1], o4[2], o4[3]);
;       }
	ds_read_b128 v[58:61], v23 offset:49664
	ds_read_b128 v[62:65], v23 offset:49920
	ds_read_b128 v[66:69], v23 offset:50176
	ds_read_b128 v[70:73], v23 offset:50432
	s_mov_b32 s0, 0x358637bd
	s_waitcnt lgkmcnt(2)
	v_pk_add_f32 v[26:27], v[58:59], v[62:63]
	s_waitcnt lgkmcnt(1)
	v_pk_add_f32 v[26:27], v[26:27], v[66:67]
	v_mov_b64_e32 v[58:59], s[0:1]
	s_waitcnt lgkmcnt(0)
	v_pk_add_f32 v[26:27], v[26:27], v[70:71]
	s_brev_b32 s0, 60
	v_pk_fma_f32 v[26:27], v[26:27], s[0:1], v[58:59] op_sel_hi:[1,0,0]
	s_nop 0
	v_mul_f32_e32 v52, 0x4b800000, v26
	v_cmp_gt_f32_e64 s[36:37], s33, v26
	v_cmp_gt_f32_e64 s[34:35], s33, v27
	s_nop 0
	v_cndmask_b32_e64 v26, v26, v52, s[36:37]
	v_rsq_f32_e32 v26, v26
	s_nop 0
	v_mul_f32_e32 v52, 0x45800000, v26
	v_cndmask_b32_e64 v52, v26, v52, s[36:37]
	v_mul_f32_e32 v26, 0x4b800000, v27
	v_cndmask_b32_e64 v26, v27, v26, s[34:35]
	v_rsq_f32_e32 v26, v26
	v_mul_f32_e32 v40, v40, v52
	s_waitcnt vmcnt(1)
	v_mul_f32_e32 v40, v24, v40
	v_mul_f32_e32 v36, v36, v52
	v_mul_f32_e32 v27, 0x45800000, v26
	v_cndmask_b32_e64 v54, v26, v27, s[34:35]
	v_pk_add_f32 v[26:27], v[60:61], v[64:65]
	v_mul_f32_e32 v41, v41, v54
	v_pk_add_f32 v[26:27], v[26:27], v[68:69]
	v_mul_f32_e32 v41, v24, v41
	v_pk_add_f32 v[26:27], v[26:27], v[72:73]
	s_waitcnt vmcnt(0)
	v_mul_f32_e32 v36, v22, v36
	v_pk_fma_f32 v[26:27], v[26:27], s[0:1], v[58:59] op_sel_hi:[1,0,0]
	v_lshlrev_b32_e32 v59, 16, v147
	v_mul_f32_e32 v60, 0xbfb8aa3b, v59
	v_exp_f32_e32 v60, v60
	v_mul_f32_e32 v56, 0x4b800000, v26
	v_cmp_gt_f32_e64 s[36:37], s33, v26
	v_cmp_gt_f32_e64 s[34:35], s33, v27
	v_add_f32_e32 v60, 1.0, v60
	v_rcp_f32_e32 v60, v60
	v_cndmask_b32_e64 v26, v26, v56, s[36:37]
	v_rsq_f32_e32 v26, v26
	v_readlane_b32 s0, v194, 19
	v_mul_f32_e32 v59, v60, v59
	v_mul_f32_e32 v40, v59, v40
	v_lshlrev_b32_e32 v59, 16, v146
	v_mul_f32_e32 v60, 0xbfb8aa3b, v59
	v_exp_f32_e32 v60, v60
	v_mul_f32_e32 v56, 0x45800000, v26
	v_cndmask_b32_e64 v56, v26, v56, s[36:37]
	v_mul_f32_e32 v42, v42, v56
	v_add_f32_e32 v60, 1.0, v60
	v_rcp_f32_e32 v60, v60
	v_mul_f32_e32 v42, v24, v42
	v_mul_f32_e32 v26, 0x4b800000, v27
	v_cndmask_b32_e64 v26, v27, v26, s[34:35]
	v_mul_f32_e32 v59, v60, v59
	v_mul_f32_e32 v41, v59, v41
	v_lshlrev_b32_e32 v59, 16, v145
	v_mul_f32_e32 v60, 0xbfb8aa3b, v59
	v_exp_f32_e32 v60, v60
	v_rsq_f32_e32 v26, v26
	v_readlane_b32 s1, v194, 20
	v_mul_f32_e32 v37, v37, v54
	v_add_f32_e32 v60, 1.0, v60
	v_rcp_f32_e32 v60, v60
	v_mul_f32_e32 v27, 0x45800000, v26
	v_cndmask_b32_e64 v58, v26, v27, s[34:35]
	v_mul_f32_e32 v43, v43, v58
	v_mul_f32_e32 v59, v60, v59
	v_mul_f32_e32 v42, v59, v42
	v_lshlrev_b32_e32 v59, 16, v144
	v_mul_f32_e32 v60, 0xbfb8aa3b, v59
	v_exp_f32_e32 v60, v60
	v_mul_f32_e32 v43, v24, v43
	v_add_u32_e32 v26, v25, v55
	v_mov_b32_dpp v61, v42 quad_perm:[1,0,3,2] row_mask:0xf bank_mask:0xf bound_ctrl:1
	v_add_f32_e32 v60, 1.0, v60
	v_rcp_f32_e32 v60, v60
	v_ashrrev_i32_e32 v27, 31, v26
	v_lshlrev_b64 v[26:27], 11, v[26:27]
	v_lshl_add_u64 v[26:27], s[0:1], 0, v[26:27]
	v_mul_f32_e32 v59, v60, v59
	v_mul_f32_e32 v43, v59, v43
	v_mov_b32_dpp v60, v41 quad_perm:[1,0,3,2] row_mask:0xf bank_mask:0xf bound_ctrl:1
	v_mov_b32_dpp v59, v40 quad_perm:[1,0,3,2] row_mask:0xf bank_mask:0xf bound_ctrl:1
	v_cndmask_b32_e32 v42, v42, v59, vcc
	v_cndmask_b32_e32 v40, v61, v40, vcc
	v_mov_b32_dpp v62, v43 quad_perm:[1,0,3,2] row_mask:0xf bank_mask:0xf bound_ctrl:1
	v_add_u32_e32 v42, 0x8000, v42
	v_add_u32_e32 v40, 0x8000, v40
	v_perm_b32 v40, v42, v40, s25
	v_cndmask_b32_e32 v42, v43, v60, vcc
	v_cndmask_b32_e32 v41, v62, v41, vcc
	v_add_u32_e32 v42, 0x8000, v42
	v_add_u32_e32 v41, 0x8000, v41
	v_lshl_add_u64 v[26:27], v[20:21], 1, v[26:27]
	v_perm_b32 v41, v42, v41, s25
	global_store_dword v[26:27], v40, off
	global_store_dword v[26:27], v41, off offset:2048
	v_lshlrev_b32_e32 v40, 16, v142
	v_mul_f32_e32 v41, 0xbfb8aa3b, v40
	v_exp_f32_e32 v41, v41
	v_mul_f32_e32 v37, v22, v37
	v_mul_f32_e32 v38, v38, v56
	v_mul_f32_e32 v38, v22, v38
	v_add_f32_e32 v41, 1.0, v41
	v_rcp_f32_e32 v41, v41
	v_mul_f32_e32 v39, v39, v58
	v_mul_f32_e32 v39, v22, v39
	v_mul_f32_e32 v40, v41, v40
	v_mul_f32_e32 v36, v40, v36
	v_lshlrev_b32_e32 v40, 16, v141
	v_mul_f32_e32 v41, 0xbfb8aa3b, v40
	v_exp_f32_e32 v41, v41
	s_nop 0
	v_add_f32_e32 v41, 1.0, v41
	v_rcp_f32_e32 v41, v41
	s_nop 0
	v_mul_f32_e32 v40, v41, v40
	v_mul_f32_e32 v37, v40, v37
	v_lshlrev_b32_e32 v40, 16, v140
	v_mul_f32_e32 v41, 0xbfb8aa3b, v40
	v_exp_f32_e32 v41, v41
	s_nop 0
	v_add_f32_e32 v41, 1.0, v41
	v_rcp_f32_e32 v41, v41
	s_nop 0
	v_mul_f32_e32 v40, v41, v40
	v_mul_f32_e32 v38, v40, v38
	v_lshlrev_b32_e32 v40, 16, v139
	v_mul_f32_e32 v41, 0xbfb8aa3b, v40
	v_exp_f32_e32 v41, v41
	v_mov_b32_dpp v42, v38 quad_perm:[1,0,3,2] row_mask:0xf bank_mask:0xf bound_ctrl:1
	v_add_f32_e32 v41, 1.0, v41
	v_rcp_f32_e32 v41, v41
	s_nop 0
	v_mul_f32_e32 v40, v41, v40
	v_mul_f32_e32 v39, v40, v39
	s_nop 0
	v_mov_b32_dpp v40, v36 quad_perm:[1,0,3,2] row_mask:0xf bank_mask:0xf bound_ctrl:1
	v_cndmask_b32_e32 v38, v38, v40, vcc
	v_cndmask_b32_e32 v36, v42, v36, vcc
	v_mov_b32_dpp v41, v37 quad_perm:[1,0,3,2] row_mask:0xf bank_mask:0xf bound_ctrl:1
	v_mov_b32_dpp v43, v39 quad_perm:[1,0,3,2] row_mask:0xf bank_mask:0xf bound_ctrl:1
	v_add_u32_e32 v38, 0x8000, v38
	v_add_u32_e32 v36, 0x8000, v36
	v_perm_b32 v36, v38, v36, s25
	v_cndmask_b32_e32 v38, v39, v41, vcc
	v_cndmask_b32_e32 v37, v43, v37, vcc
	v_add_u32_e32 v38, 0x8000, v38
	v_add_u32_e32 v37, 0x8000, v37
	v_perm_b32 v37, v38, v37, s25
	global_store_dword v[26:27], v36, off offset:32
	global_store_dword v[26:27], v37, off offset:2080

; DEVINL int tidx() { int t = threadIdx.x; asm volatile("" : "+v"(t)); return t; }
; DEVINL void gla_passC(const Params& p, char* smem, int item) {
;   const ChunkInfo ci = chunk_info(item);
;   const int tid = tidx(), lane = tid & 63, w = tid >> 6;
;   const u16* qk = (const u16*)(p.ws + OFF_QK);
;   const u16* vT = (const u16*)(p.ws + OFF_VT);
;   const u16* SpT = (const u16*)(p.ws + OFF_SPT) + (size_t)item * 8192;
;   const u16* gbuf = (const u16*)(p.ws + OFF_GB);
;   u16 qraw[16], kraw16[16];
; #pragma unroll
;   for (int i = 0; i < 16; ++i) {
;     const int t = 16 * w + i;
;     qraw[i] = qk[(size_t)(ci.r0 + t) * 512 + ci.h * 64 + lane];
;     kraw16[i] = qk[(size_t)(ci.r0 + t) * 512 + 256 + ci.h * 64 + lane];
;   }
;   bf16x8 bvv[2][2], bss[2][2];
; #pragma unroll
;   for (int ks = 0; ks < 2; ++ks) {
;     const int kb = ks * 32 + 8 * (lane >> 4);
; #pragma unroll
;     for (int nf = 0; nf < 2; ++nf) {
;       const int dv = 32 * w + nf * 16 + (lane & 15);
;       bvv[ks][nf] = *(const bf16x8*)(vT + (size_t)(ci.h * 128 + dv) * LDT + ci.r0 + kb);
;       bss[ks][nf] = *(const bf16x8*)(SpT + dv * 64 + kb);
;     }
;   }
;   u16 graw[4][2][4];
; #pragma unroll
;   for (int mf = 0; mf < 4; ++mf) {
;     const int t0 = mf * 16 + (lane >> 4) * 4;
; #pragma unroll
;     for (int nf = 0; nf < 2; ++nf)
; #pragma unroll
;       for (int j = 0; j < 4; ++j)
;         graw[mf][nf][j] = gbuf[(size_t)(ci.r0 + t0 + j) * 512 + ci.h * 128 + 32 * w + nf * 16 + (lane & 15)];
;   }
.LBB0_407:
	s_or_b64 exec, exec, s[0:1]
	v_mov_b32_e32 v134, v0
	v_and_b32_e32 v1, 3, v1
	v_ashrrev_i32_e32 v139, 6, v134
	v_lshlrev_b32_e32 v53, 4, v139
	v_add_u32_e32 v6, v53, v44
	v_ashrrev_i32_e32 v7, 31, v6
	v_lshlrev_b64 v[6:7], 10, v[6:7]
	v_and_b32_e32 v137, 63, v134
	v_mov_b32_e32 v47, v2
	v_readlane_b32 s0, v194, 33
	v_lshl_add_u64 v[6:7], s[94:95], 0, v[6:7]
	v_lshlrev_b32_e32 v48, 7, v1
	v_mov_b32_e32 v49, v2
	v_lshlrev_b64 v[78:79], 14, v[46:47]
	v_readlane_b32 s1, v194, 34
	v_lshl_add_u64 v[6:7], v[6:7], 0, v[48:49]
	v_lshlrev_b32_e32 v8, 1, v137
	v_mov_b32_e32 v9, v2
	s_waitcnt lgkmcnt(0)
	v_lshl_add_u64 v[4:5], s[0:1], 0, v[78:79]
	v_lshl_add_u64 v[42:43], v[6:7], 0, v[8:9]
	s_mov_b64 s[0:1], 0x1000
	v_lshl_add_u64 v[68:69], v[42:43], 0, s[0:1]
	s_mov_b64 s[0:1], 0x1400
	v_lshl_add_u64 v[70:71], v[42:43], 0, s[0:1]
	s_mov_b64 s[0:1], 0x1800
	v_lshl_add_u64 v[72:73], v[42:43], 0, s[0:1]
	s_mov_b64 s[0:1], 0x1c00
	v_lshl_add_u64 v[74:75], v[42:43], 0, s[0:1]
	s_mov_b64 s[0:1], 0x2000
	v_lshl_add_u64 v[66:67], v[42:43], 0, s[0:1]
	s_mov_b64 s[0:1], 0x2400
	v_lshl_add_u64 v[64:65], v[42:43], 0, s[0:1]
	s_mov_b64 s[0:1], 0x2800
	v_lshl_add_u64 v[62:63], v[42:43], 0, s[0:1]
	s_mov_b64 s[0:1], 0x2c00
	v_lshl_add_u64 v[60:61], v[42:43], 0, s[0:1]
	s_mov_b64 s[0:1], 0x3000
	v_lshl_add_u64 v[58:59], v[42:43], 0, s[0:1]
	s_mov_b64 s[0:1], 0x3400
	v_lshl_add_u64 v[56:57], v[42:43], 0, s[0:1]
	s_mov_b64 s[0:1], 0x3800
	v_lshlrev_b32_e32 v50, 5, v139
	v_and_b32_e32 v135, 15, v134
	v_lshl_add_u64 v[54:55], v[42:43], 0, s[0:1]
	s_mov_b64 s[0:1], 0x3c00
	v_or_b32_e32 v52, v50, v135
	v_lshl_add_u64 v[40:41], v[42:43], 0, s[0:1]
	v_readlane_b32 s0, v194, 35
	v_and_b32_e32 v38, 48, v134
	v_mov_b32_e32 v39, v2
	v_lshlrev_b32_e32 v10, 6, v52
	v_lshrrev_b32_e32 v36, 2, v134
	v_ashrrev_i32_e32 v45, 31, v44
	v_readlane_b32 s1, v194, 36
	v_lshl_add_u64 v[4:5], v[4:5], 0, v[38:39]
	v_ashrrev_i32_e32 v11, 31, v10
	v_and_b32_e32 v77, 12, v36
	v_lshlrev_b32_e32 v36, 8, v1
	v_mov_b32_e32 v37, v2
	v_lshl_add_u64 v[6:7], v[44:45], 1, s[0:1]
	v_lshl_add_u64 v[20:21], v[10:11], 1, v[4:5]
	v_or_b32_e32 v10, 16, v52
	v_add_u32_e32 v80, v77, v44
	v_ashrrev_i32_e32 v51, 31, v50
	v_lshl_add_u64 v[36:37], s[92:93], 0, v[36:37]
	v_add_u32_e32 v8, v52, v48
	v_lshl_add_u64 v[6:7], v[6:7], 0, v[38:39]
	v_add_u32_e32 v11, v10, v48
	v_lshl_add_u64 v[82:83], v[50:51], 1, v[36:37]
	v_lshlrev_b32_e32 v36, 1, v135
	v_mov_b32_e32 v37, v2
	v_ashrrev_i32_e32 v81, 31, v80
	v_mad_i64_i32 v[8:9], s[0:1], v8, s88, v[6:7]
	v_mad_i64_i32 v[22:23], s[0:1], v11, s88, v[6:7]
	v_lshl_add_u64 v[82:83], v[82:83], 0, v[36:37]
	v_lshlrev_b64 v[80:81], 10, v[80:81]
	v_lshl_add_u64 v[140:141], v[82:83], 0, v[80:81]
	s_movk_i32 s0, 0x4000
	v_add_co_u32_e32 v82, vcc, s0, v140
	s_mov_b64 s[0:1], 0x4400
	v_lshlrev_b32_e32 v6, 6, v10
	v_lshl_add_u64 v[84:85], v[140:141], 0, s[0:1]
	s_mov_b64 s[0:1], 0x4800
	v_ashrrev_i32_e32 v7, 31, v6
	v_lshl_add_u64 v[86:87], v[140:141], 0, s[0:1]
	s_mov_b64 s[0:1], 0x4c00
	v_lshl_add_u64 v[24:25], v[6:7], 1, v[4:5]
	v_lshl_add_u64 v[80:81], v[140:141], 0, s[12:13]
	v_addc_co_u32_e32 v83, vcc, 0, v141, vcc
	v_lshl_add_u64 v[88:89], v[140:141], 0, s[0:1]
	s_mov_b64 s[0:1], 0x8000
	global_load_dwordx4 v[12:15], v[8:9], off
	global_load_dwordx4 v[16:19], v[20:21], off
	global_load_dwordx4 v[28:31], v[22:23], off
	global_load_dwordx4 v[32:35], v[24:25], off
	s_nop 0
	global_load_dwordx4 v[8:11], v[8:9], off offset:64
	s_nop 0
	global_load_dwordx4 v[4:7], v[20:21], off offset:64
	s_nop 0
	global_load_dwordx4 v[20:23], v[22:23], off offset:64
	s_nop 0
	global_load_dwordx4 v[24:27], v[24:25], off offset:64
	s_nop 0
	global_load_ushort v133, v[140:141], off
	global_load_ushort v132, v[140:141], off offset:1024
	global_load_ushort v131, v[140:141], off offset:2048
	global_load_ushort v113, v[140:141], off offset:3072
	global_load_ushort v112, v[140:141], off offset:32
	global_load_ushort v111, v[140:141], off offset:1056
	global_load_ushort v110, v[140:141], off offset:2080
	global_load_ushort v109, v[140:141], off offset:3104
	global_load_ushort v108, v[82:83], off
	global_load_ushort v107, v[82:83], off offset:1024
	global_load_ushort v106, v[82:83], off offset:2048
	global_load_ushort v105, v[82:83], off offset:3072
	global_load_ushort v102, v[80:81], off offset:32
	global_load_ushort v91, v[84:85], off offset:32
	global_load_ushort v90, v[86:87], off offset:32
	s_nop 0
	global_load_ushort v89, v[88:89], off offset:32
	v_lshl_add_u64 v[80:81], v[140:141], 0, s[0:1]
	s_mov_b32 s0, 0x8000
	v_add_co_u32_e32 v82, vcc, s0, v140
	s_mov_b64 s[0:1], 0x8400
	v_lshl_add_u64 v[142:143], v[140:141], 0, s[0:1]
	s_mov_b64 s[0:1], 0x8800
	v_lshl_add_u64 v[144:145], v[140:141], 0, s[0:1]
	s_mov_b64 s[0:1], 0x8c00
	v_addc_co_u32_e32 v83, vcc, 0, v141, vcc
	v_lshl_add_u64 v[146:147], v[140:141], 0, s[0:1]
	v_readlane_b32 s0, v194, 37
	global_load_ushort v88, v[82:83], off
	global_load_ushort v87, v[82:83], off offset:1024
	global_load_ushort v86, v[82:83], off offset:2048
	global_load_ushort v85, v[82:83], off offset:3072
	global_load_ushort v84, v[80:81], off offset:32
	s_nop 0
	global_load_ushort v83, v[142:143], off offset:32
	global_load_ushort v82, v[144:145], off offset:32
	global_load_ushort v81, v[146:147], off offset:32
	v_readlane_b32 s1, v194, 38
	v_lshl_or_b32 v142, v139, 10, v137
	v_ashrrev_i32_e32 v143, 31, v142
	v_lshl_add_u64 v[78:79], s[0:1], 0, v[78:79]
	v_lshl_add_u64 v[142:143], v[142:143], 2, v[78:79]
	global_load_ushort v152, v[42:43], off
	global_load_dword v153, v[142:143], off
	global_load_ushort v154, v[42:43], off offset:512
	s_mov_b64 s[0:1], 0xc000
; DEVINL u16 f2bf(float f) { return (u16)((__float_as_uint(f) + 0x8000u) >> 16); }
; DEVINL float bf2f(u16 h) { return __uint_as_float(((unsigned)h) << 16); }
; DEVINL void gla_passC(const Params& p, char* smem, int item) {
;     ...
;   u16 graw[4][2][4];
; #pragma unroll
;   for (int mf = 0; mf < 4; ++mf) {
;     const int t0 = mf * 16 + (lane >> 4) * 4;
; #pragma unroll
;     for (int nf = 0; nf < 2; ++nf)
; #pragma unroll
;       for (int j = 0; j < 4; ++j)
;         graw[mf][nf][j] = gbuf[(size_t)(ci.r0 + t0 + j) * 512 + ci.h * 128 + 32 * w + nf * 16 + (lane & 15)];
;   }
;   float bcum[16];
;   {
;     const float* bc = (const float*)(p.ws + OFF_BCUM) + (size_t)item * 4096;
; #pragma unroll
;     for (int i = 0; i < 16; ++i) bcum[i] = bc[(16 * w + i) * 64 + lane];
;   }
;   __syncthreads();
;   u16* Qd = (u16*)(smem + G_QD); u16* Ki = (u16*)(smem + G_KI); u16* Att = (u16*)(smem + G_ATT);
;   float* red = (float*)(smem + G_RED);
; #pragma unroll
;   for (int i = 0; i < 16; ++i) {
;     const int t = 16 * w + i;
;     const float qv = (t < ci.T) ? bf2f(qraw[i]) : 0.f, kv = (t < ci.T) ? bf2f(kraw16[i]) : 0.f;
;     const float bt = bcum[i];
;     Qd[t * 72 + lane] = f2bf(qv * __expf(bt));
;     Ki[t * 72 + lane] = f2bf(kv * __expf(-bt));
;   }
	v_lshl_add_u64 v[144:145], v[140:141], 0, s[0:1]
	s_mov_b32 s0, 0xc000
	v_add_co_u32_e32 v146, vcc, s0, v140
	s_mov_b64 s[0:1], 0xc400
	v_lshl_add_u64 v[148:149], v[140:141], 0, s[0:1]
	s_mov_b64 s[0:1], 0xc800
	v_lshl_add_u64 v[150:151], v[140:141], 0, s[0:1]
	s_mov_b64 s[0:1], 0xcc00
	v_addc_co_u32_e32 v147, vcc, 0, v141, vcc
	v_lshl_add_u64 v[140:141], v[140:141], 0, s[0:1]
	global_load_ushort v80, v[146:147], off
	global_load_ushort v79, v[146:147], off offset:1024
	global_load_ushort v78, v[146:147], off offset:2048
	global_load_ushort v51, v[146:147], off offset:3072
	global_load_ushort v49, v[144:145], off offset:32
	global_load_ushort v47, v[148:149], off offset:32
	global_load_ushort v45, v[150:151], off offset:32
	global_load_ushort v1, v[140:141], off offset:32
	s_nop 0
	global_load_ushort v141, v[42:43], off offset:1024
	global_load_dword v146, v[142:143], off offset:256
	global_load_dword v147, v[142:143], off offset:512
	global_load_dword v148, v[142:143], off offset:768
	global_load_ushort v149, v[42:43], off offset:1536
	global_load_dword v150, v[142:143], off offset:1024
	global_load_dword v151, v[142:143], off offset:1280
	global_load_dword v155, v[142:143], off offset:1536
	global_load_dword v156, v[142:143], off offset:1792
	global_load_dword v157, v[142:143], off offset:2048
	global_load_dword v158, v[142:143], off offset:2304
	global_load_dword v159, v[142:143], off offset:2560
	global_load_dword v140, v[142:143], off offset:2816
	global_load_dword v138, v[142:143], off offset:3072
	global_load_dword v136, v[142:143], off offset:3328
	global_load_dword v39, v[142:143], off offset:3584
	global_load_dword v37, v[142:143], off offset:3840
	global_load_ushort v160, v[42:43], off offset:2048
	global_load_ushort v161, v[42:43], off offset:2560
	global_load_ushort v162, v[42:43], off offset:3072
	global_load_ushort v163, v[42:43], off offset:3584
	s_movk_i32 s0, 0x1000
	v_add_co_u32_e32 v142, vcc, s0, v42
	s_movk_i32 s0, 0x2000
	s_nop 0
	v_addc_co_u32_e32 v143, vcc, 0, v43, vcc
	v_add_co_u32_e32 v144, vcc, s0, v42
	s_movk_i32 s0, 0x3000
	s_nop 0
	v_addc_co_u32_e32 v145, vcc, 0, v43, vcc
	global_load_ushort v164, v[144:145], off offset:-4096
	s_nop 0
	global_load_ushort v68, v[68:69], off offset:512
	s_nop 0
	global_load_ushort v69, v[142:143], off offset:1024
	s_nop 0
	global_load_ushort v70, v[70:71], off offset:512
	s_nop 0
	global_load_ushort v71, v[142:143], off offset:2048
	s_nop 0
	global_load_ushort v72, v[72:73], off offset:512
	s_nop 0
	global_load_ushort v73, v[142:143], off offset:3072
	s_nop 0
	global_load_ushort v74, v[74:75], off offset:512
	s_nop 0
	global_load_ushort v75, v[144:145], off
	s_nop 0
	global_load_ushort v66, v[66:67], off offset:512
	s_nop 0
	global_load_ushort v67, v[144:145], off offset:1024
	s_nop 0
	global_load_ushort v64, v[64:65], off offset:512
	s_nop 0
	global_load_ushort v65, v[144:145], off offset:2048
	s_nop 0
	global_load_ushort v62, v[62:63], off offset:512
	s_nop 0
	global_load_ushort v63, v[144:145], off offset:3072
	s_nop 0
	global_load_ushort v60, v[60:61], off offset:512
	v_add_co_u32_e32 v42, vcc, s0, v42
	s_movk_i32 s0, 0x480
	s_nop 0
	v_addc_co_u32_e32 v43, vcc, 0, v43, vcc
	global_load_ushort v61, v[42:43], off
	s_nop 0
	global_load_ushort v58, v[58:59], off offset:512
	s_nop 0
	global_load_ushort v59, v[42:43], off offset:1024
	s_nop 0
	global_load_ushort v56, v[56:57], off offset:512
	s_nop 0
	global_load_ushort v57, v[42:43], off offset:2048
	s_nop 0
	global_load_ushort v54, v[54:55], off offset:512
	s_nop 0
	global_load_ushort v42, v[42:43], off offset:3072
	s_nop 0
	global_load_ushort v40, v[40:41], off offset:512
	v_cmp_lt_i32_e32 vcc, v53, v3
	s_waitcnt vmcnt(63) expcnt(7) lgkmcnt(15)
	s_barrier
	s_movk_i32 s34, 0x90
	s_waitcnt vmcnt(55)
	v_lshlrev_b32_e32 v41, 16, v152
	s_waitcnt vmcnt(54)
	v_mul_f32_e32 v43, 0x3fb8aa3b, v153
	v_exp_f32_e32 v43, v43
	v_cndmask_b32_e32 v41, 0, v41, vcc
	s_waitcnt vmcnt(53)
	v_lshlrev_b32_e32 v55, 16, v154
	v_cndmask_b32_e32 v55, 0, v55, vcc
	v_mul_f32_e32 v41, v41, v43
	v_mul_lo_u32 v43, v139, s0
	v_mul_f32_e32 v139, 0xbfb8aa3b, v153
	v_exp_f32_e32 v139, v139
	v_or_b32_e32 v43, v43, v137
	v_add_u32_e32 v41, 0x8000, v41
	v_lshlrev_b32_e32 v43, 1, v43
	ds_write_b16_d16_hi v43, v41 offset:22016
	v_mul_f32_e32 v41, v55, v139
	s_waitcnt vmcnt(43)
	v_mul_f32_e32 v55, 0x3fb8aa3b, v146
	v_add_u32_e32 v41, 0x8000, v41
	v_exp_f32_e32 v55, v55
	ds_write_b16_d16_hi v43, v41 offset:31232
	v_or_b32_e32 v41, 1, v53
	v_cmp_lt_i32_e32 vcc, v41, v3
	v_lshlrev_b32_e32 v43, 16, v141
	s_movk_i32 s0, 0x48
	v_cndmask_b32_e32 v43, 0, v43, vcc
	v_mul_f32_e32 v43, v43, v55
	v_mul_f32_e32 v55, 0xbfb8aa3b, v146
	v_exp_f32_e32 v55, v55
	s_waitcnt vmcnt(40)
	v_lshlrev_b32_e32 v139, 16, v149
	v_mul_lo_u32 v41, v41, s0
	v_cndmask_b32_e32 v139, 0, v139, vcc
	v_add_u32_e32 v43, 0x8000, v43
	v_add_lshl_u32 v41, v41, v137, 1
	ds_write_b16_d16_hi v41, v43 offset:22016
	v_mul_f32_e32 v43, v139, v55
	v_mul_f32_e32 v137, 0x3fb8aa3b, v147
	v_add_u32_e32 v43, 0x8000, v43
	v_exp_f32_e32 v137, v137
	ds_write_b16_d16_hi v41, v43 offset:31232
	v_or_b32_e32 v43, 2, v53
	v_mul_f32_e32 v139, 0xbfb8aa3b, v147
	v_cmp_lt_i32_e32 vcc, v43, v3
	s_waitcnt vmcnt(27)
	v_lshlrev_b32_e32 v43, 16, v160
	v_exp_f32_e32 v139, v139
	v_cndmask_b32_e32 v43, 0, v43, vcc
	s_waitcnt vmcnt(26)
	v_lshlrev_b32_e32 v55, 16, v161
	v_mul_f32_e32 v43, v43, v137
	v_cndmask_b32_e32 v55, 0, v55, vcc
	v_add_u32_e32 v43, 0x8000, v43
	ds_write_b16_d16_hi v41, v43 offset:22160
	v_mul_f32_e32 v43, v55, v139
	v_mul_f32_e32 v137, 0x3fb8aa3b, v148
	v_add_u32_e32 v43, 0x8000, v43
	v_exp_f32_e32 v137, v137
	ds_write_b16_d16_hi v41, v43 offset:31376
	v_or_b32_e32 v43, 3, v53
	v_mul_f32_e32 v139, 0xbfb8aa3b, v148
	v_cmp_lt_i32_e32 vcc, v43, v3
	s_waitcnt vmcnt(25)
; DEVINL u16 f2bf(float f) { return (u16)((__float_as_uint(f) + 0x8000u) >> 16); }
; DEVINL float bf2f(u16 h) { return __uint_as_float(((unsigned)h) << 16); }
; DEVINL void gla_passC(const Params& p, char* smem, int item) {
;     ...
; #pragma unroll
;   for (int i = 0; i < 16; ++i) {
;     const int t = 16 * w + i;
;     const float qv = (t < ci.T) ? bf2f(qraw[i]) : 0.f, kv = (t < ci.T) ? bf2f(kraw16[i]) : 0.f;
;     const float bt = bcum[i];
;     Qd[t * 72 + lane] = f2bf(qv * __expf(bt));
;     Ki[t * 72 + lane] = f2bf(kv * __expf(-bt));
;   }
	v_lshlrev_b32_e32 v43, 16, v162
	v_exp_f32_e32 v139, v139
	v_cndmask_b32_e32 v43, 0, v43, vcc
	s_waitcnt vmcnt(24)
	v_lshlrev_b32_e32 v55, 16, v163
	v_mul_f32_e32 v43, v43, v137
	v_cndmask_b32_e32 v55, 0, v55, vcc
	v_add_u32_e32 v43, 0x8000, v43
	ds_write_b16_d16_hi v41, v43 offset:22304
	v_mul_f32_e32 v43, v55, v139
	s_waitcnt vmcnt(22)
	v_lshlrev_b32_e32 v55, 16, v68
	v_mul_f32_e32 v68, 0x3fb8aa3b, v150
	v_add_u32_e32 v43, 0x8000, v43
	v_exp_f32_e32 v68, v68
	ds_write_b16_d16_hi v41, v43 offset:31520
	v_or_b32_e32 v43, 4, v53
	v_mul_f32_e32 v137, 0xbfb8aa3b, v150
	v_cmp_lt_i32_e32 vcc, v43, v3
	v_lshlrev_b32_e32 v43, 16, v164
	v_exp_f32_e32 v137, v137
	v_cndmask_b32_e32 v43, 0, v43, vcc
	v_mul_f32_e32 v43, v43, v68
	v_cndmask_b32_e32 v55, 0, v55, vcc
	v_add_u32_e32 v43, 0x8000, v43
	ds_write_b16_d16_hi v41, v43 offset:22448
	v_mul_f32_e32 v43, v55, v137
	v_add_u32_e32 v43, 0x8000, v43
	v_mul_f32_e32 v68, 0x3fb8aa3b, v151
	ds_write_b16_d16_hi v41, v43 offset:31664
	v_or_b32_e32 v43, 5, v53
	v_exp_f32_e32 v68, v68
	v_cmp_lt_i32_e32 vcc, v43, v3
	s_waitcnt vmcnt(21)
	v_lshlrev_b32_e32 v43, 16, v69
	v_mul_f32_e32 v69, 0xbfb8aa3b, v151
	v_exp_f32_e32 v69, v69
	v_cndmask_b32_e32 v43, 0, v43, vcc
	s_waitcnt vmcnt(20)
	v_lshlrev_b32_e32 v55, 16, v70
	v_mul_f32_e32 v43, v43, v68
	v_cndmask_b32_e32 v55, 0, v55, vcc
	v_add_u32_e32 v43, 0x8000, v43
	ds_write_b16_d16_hi v41, v43 offset:22592
	v_mul_f32_e32 v43, v55, v69
	v_mul_f32_e32 v68, 0x3fb8aa3b, v155
	v_add_u32_e32 v43, 0x8000, v43
	v_exp_f32_e32 v68, v68
	ds_write_b16_d16_hi v41, v43 offset:31808
	v_or_b32_e32 v43, 6, v53
	v_mul_f32_e32 v69, 0xbfb8aa3b, v155
	v_cmp_lt_i32_e32 vcc, v43, v3
	s_waitcnt vmcnt(19)
	v_lshlrev_b32_e32 v43, 16, v71
	v_exp_f32_e32 v69, v69
	v_cndmask_b32_e32 v43, 0, v43, vcc
	s_waitcnt vmcnt(18)
	v_lshlrev_b32_e32 v55, 16, v72
	v_mul_f32_e32 v43, v43, v68
	v_cndmask_b32_e32 v55, 0, v55, vcc
	v_add_u32_e32 v43, 0x8000, v43
	ds_write_b16_d16_hi v41, v43 offset:22736
	v_mul_f32_e32 v43, v55, v69
	v_mul_f32_e32 v68, 0x3fb8aa3b, v156
	v_add_u32_e32 v43, 0x8000, v43
	v_exp_f32_e32 v68, v68
	ds_write_b16_d16_hi v41, v43 offset:31952
	v_or_b32_e32 v43, 7, v53
	v_mul_f32_e32 v69, 0xbfb8aa3b, v156
	v_cmp_lt_i32_e32 vcc, v43, v3
	s_waitcnt vmcnt(17)
	v_lshlrev_b32_e32 v43, 16, v73
	v_exp_f32_e32 v69, v69
	v_cndmask_b32_e32 v43, 0, v43, vcc
	s_waitcnt vmcnt(16)
	v_lshlrev_b32_e32 v55, 16, v74
	v_mul_f32_e32 v43, v43, v68
	v_cndmask_b32_e32 v55, 0, v55, vcc
	v_add_u32_e32 v43, 0x8000, v43
	ds_write_b16_d16_hi v41, v43 offset:22880
	v_mul_f32_e32 v43, v55, v69
	s_waitcnt vmcnt(14)
	v_lshlrev_b32_e32 v55, 16, v66
	v_mul_f32_e32 v66, 0x3fb8aa3b, v157
	v_add_u32_e32 v43, 0x8000, v43
	v_exp_f32_e32 v66, v66
	ds_write_b16_d16_hi v41, v43 offset:32096
	v_or_b32_e32 v43, 8, v53
	v_mul_f32_e32 v68, 0xbfb8aa3b, v157
	v_cmp_lt_i32_e32 vcc, v43, v3
	v_lshlrev_b32_e32 v43, 16, v75
	v_exp_f32_e32 v68, v68
	v_cndmask_b32_e32 v43, 0, v43, vcc
	v_mul_f32_e32 v43, v43, v66
	v_cndmask_b32_e32 v55, 0, v55, vcc
	v_add_u32_e32 v43, 0x8000, v43
	ds_write_b16_d16_hi v41, v43 offset:23024
	v_mul_f32_e32 v43, v55, v68
	s_waitcnt vmcnt(12)
	v_lshlrev_b32_e32 v55, 16, v64
	v_mul_f32_e32 v64, 0x3fb8aa3b, v158
	v_add_u32_e32 v43, 0x8000, v43
	v_exp_f32_e32 v64, v64
	ds_write_b16_d16_hi v41, v43 offset:32240
	v_or_b32_e32 v43, 9, v53
	v_mul_f32_e32 v66, 0xbfb8aa3b, v158
	v_cmp_lt_i32_e32 vcc, v43, v3
	v_lshlrev_b32_e32 v43, 16, v67
	v_exp_f32_e32 v66, v66
	v_cndmask_b32_e32 v43, 0, v43, vcc
	v_mul_f32_e32 v43, v43, v64
	v_cndmask_b32_e32 v55, 0, v55, vcc
	v_add_u32_e32 v43, 0x8000, v43
	ds_write_b16_d16_hi v41, v43 offset:23168
	v_mul_f32_e32 v43, v55, v66
	s_waitcnt vmcnt(10)
	v_lshlrev_b32_e32 v55, 16, v62
	v_mul_f32_e32 v62, 0x3fb8aa3b, v159
	v_add_u32_e32 v43, 0x8000, v43
	v_exp_f32_e32 v62, v62
	ds_write_b16_d16_hi v41, v43 offset:32384
	v_or_b32_e32 v43, 10, v53
	v_mul_f32_e32 v64, 0xbfb8aa3b, v159
	v_cmp_lt_i32_e32 vcc, v43, v3
	v_lshlrev_b32_e32 v43, 16, v65
	v_exp_f32_e32 v64, v64
	v_cndmask_b32_e32 v43, 0, v43, vcc
	v_mul_f32_e32 v43, v43, v62
	v_cndmask_b32_e32 v55, 0, v55, vcc
	v_add_u32_e32 v43, 0x8000, v43
	ds_write_b16_d16_hi v41, v43 offset:23312
	v_mul_f32_e32 v43, v55, v64
	s_waitcnt vmcnt(8)
	v_lshlrev_b32_e32 v55, 16, v60
	v_mul_f32_e32 v60, 0x3fb8aa3b, v140
	v_add_u32_e32 v43, 0x8000, v43
	v_exp_f32_e32 v60, v60
	ds_write_b16_d16_hi v41, v43 offset:32528
	v_or_b32_e32 v43, 11, v53
	v_mul_f32_e32 v62, 0xbfb8aa3b, v140
	v_cmp_lt_i32_e32 vcc, v43, v3
	v_lshlrev_b32_e32 v43, 16, v63
	v_exp_f32_e32 v62, v62
	v_cndmask_b32_e32 v43, 0, v43, vcc
	v_mul_f32_e32 v43, v43, v60
	v_cndmask_b32_e32 v55, 0, v55, vcc
	v_add_u32_e32 v43, 0x8000, v43
	ds_write_b16_d16_hi v41, v43 offset:23456
	v_mul_f32_e32 v43, v55, v62
	s_waitcnt vmcnt(6)
	v_lshlrev_b32_e32 v55, 16, v58
	v_mul_f32_e32 v58, 0x3fb8aa3b, v138
	v_add_u32_e32 v43, 0x8000, v43
	v_exp_f32_e32 v58, v58
	ds_write_b16_d16_hi v41, v43 offset:32672
	v_or_b32_e32 v43, 12, v53
	v_mul_f32_e32 v60, 0xbfb8aa3b, v138
	v_cmp_lt_i32_e32 vcc, v43, v3
	v_lshlrev_b32_e32 v43, 16, v61
	v_exp_f32_e32 v60, v60
	v_cndmask_b32_e32 v43, 0, v43, vcc
	v_mul_f32_e32 v43, v43, v58
	v_cndmask_b32_e32 v55, 0, v55, vcc
	v_add_u32_e32 v43, 0x8000, v43
	ds_write_b16_d16_hi v41, v43 offset:23600
	v_mul_f32_e32 v43, v55, v60
	s_waitcnt vmcnt(4)
; DEVINL u16 f2bf(float f) { return (u16)((__float_as_uint(f) + 0x8000u) >> 16); }
; DEVINL float bf2f(u16 h) { return __uint_as_float(((unsigned)h) << 16); }
; DEVINL f32x4 mfma16(bf16x8 a, bf16x8 b, f32x4 c) { return __builtin_amdgcn_mfma_f32_16x16x32_bf16(a, b, c, 0, 0, 0); }
; DEVINL void gla_passC(const Params& p, char* smem, int item) {
;     ...
; #pragma unroll
;   for (int i = 0; i < 16; ++i) {
;     const int t = 16 * w + i;
;     const float qv = (t < ci.T) ? bf2f(qraw[i]) : 0.f, kv = (t < ci.T) ? bf2f(kraw16[i]) : 0.f;
;     const float bt = bcum[i];
;     Qd[t * 72 + lane] = f2bf(qv * __expf(bt));
;     Ki[t * 72 + lane] = f2bf(kv * __expf(-bt));
;   }
;   __syncthreads();
;   {
;     f32x4 at[4];
; #pragma unroll
;     for (int nf = 0; nf < 4; ++nf) at[nf] = f32x4{0, 0, 0, 0};
; #pragma unroll
;     for (int ks = 0; ks < 2; ++ks) {
;       bf16x8 a = *(const bf16x8*)(Qd + (16 * w + (lane & 15)) * 72 + ks * 32 + 8 * (lane >> 4));
; #pragma unroll
;       for (int nf = 0; nf < 4; ++nf) {
;         bf16x8 b = *(const bf16x8*)(Ki + (nf * 16 + (lane & 15)) * 72 + ks * 32 + 8 * (lane >> 4));
;         at[nf] = mfma16(a, b, at[nf]);
;       }
;     }
; #pragma unroll
;     for (int nf = 0; nf < 4; ++nf)
; #pragma unroll
;       for (int j = 0; j < 4; ++j) {
;         int t = 16 * w + (lane >> 4) * 4 + j, s = nf * 16 + (lane & 15);
;         Att[t * 72 + s] = f2bf((s <= t) ? at[nf][j] : 0.f);
;       }
;   }
;   __syncthreads();
	v_lshlrev_b32_e32 v55, 16, v56
	v_mul_f32_e32 v56, 0x3fb8aa3b, v136
	v_add_u32_e32 v43, 0x8000, v43
	v_exp_f32_e32 v56, v56
	ds_write_b16_d16_hi v41, v43 offset:32816
	v_or_b32_e32 v43, 13, v53
	v_mul_f32_e32 v58, 0xbfb8aa3b, v136
	v_cmp_lt_i32_e32 vcc, v43, v3
	v_lshlrev_b32_e32 v43, 16, v59
	v_exp_f32_e32 v58, v58
	v_cndmask_b32_e32 v43, 0, v43, vcc
	v_mul_f32_e32 v43, v43, v56
	v_cndmask_b32_e32 v55, 0, v55, vcc
	v_add_u32_e32 v43, 0x8000, v43
	ds_write_b16_d16_hi v41, v43 offset:23744
	v_mul_f32_e32 v43, v55, v58
	v_mul_f32_e32 v55, 0x3fb8aa3b, v39
	v_mul_f32_e32 v39, 0xbfb8aa3b, v39
	v_add_u32_e32 v43, 0x8000, v43
	v_exp_f32_e32 v39, v39
	ds_write_b16_d16_hi v41, v43 offset:32960
	v_or_b32_e32 v43, 14, v53
	v_cmp_lt_i32_e32 vcc, v43, v3
	s_waitcnt vmcnt(2)
	v_lshlrev_b32_e32 v54, 16, v54
	v_lshlrev_b32_e32 v43, 16, v57
	v_cndmask_b32_e32 v54, 0, v54, vcc
	v_mul_f32_e32 v39, v54, v39
	v_add_u32_e32 v39, 0x8000, v39
	ds_write_b16_d16_hi v41, v39 offset:33104
	v_or_b32_e32 v39, 15, v53
	v_cndmask_b32_e32 v43, 0, v43, vcc
	v_cmp_lt_i32_e32 vcc, v39, v3
	s_waitcnt vmcnt(1)
	v_lshlrev_b32_e32 v39, 16, v42
	v_mul_f32_e32 v42, 0x3fb8aa3b, v37
	v_mul_f32_e32 v37, 0xbfb8aa3b, v37
	v_exp_f32_e32 v37, v37
	v_exp_f32_e32 v42, v42
	v_exp_f32_e32 v55, v55
	s_waitcnt vmcnt(0)
	v_lshlrev_b32_e32 v40, 16, v40
	v_cndmask_b32_e32 v40, 0, v40, vcc
	v_cndmask_b32_e32 v39, 0, v39, vcc
	v_mul_f32_e32 v37, v40, v37
	v_mul_f32_e32 v39, v39, v42
	v_add_u32_e32 v37, 0x8000, v37
	v_mul_f32_e32 v43, v43, v55
	v_add_u32_e32 v39, 0x8000, v39
	ds_write_b16_d16_hi v41, v37 offset:33248
	v_or_b32_e32 v37, v53, v135
	v_add_u32_e32 v43, 0x8000, v43
	v_mad_u64_u32 v[70:71], s[0:1], v37, s34, v[38:39]
	ds_write_b16_d16_hi v41, v43 offset:23888
	ds_write_b16_d16_hi v41, v39 offset:24032
	s_waitcnt lgkmcnt(0)
	s_barrier
	ds_read_b128 v[40:43], v70 offset:22016
	v_mul_u32_u24_e32 v37, 0x48, v135
	v_lshl_add_u32 v74, v37, 1, v38
	ds_read_b128 v[54:57], v74 offset:31232
	ds_read_b128 v[58:61], v74 offset:33536
	ds_read_b128 v[62:65], v74 offset:35840
	ds_read_b128 v[66:69], v74 offset:38144
	ds_read_b128 v[70:73], v70 offset:22080
	s_waitcnt lgkmcnt(4)
	v_mfma_f32_16x16x32_bf16 v[54:57], v[40:43], v[54:57], 0
	v_or_b32_e32 v53, v53, v77
	v_cmp_le_i32_e32 vcc, v135, v53
	v_or_b32_e32 v37, 16, v135
	s_waitcnt lgkmcnt(3)
	v_mfma_f32_16x16x32_bf16 v[58:61], v[40:43], v[58:61], 0
	s_waitcnt lgkmcnt(2)
	v_mfma_f32_16x16x32_bf16 v[62:65], v[40:43], v[62:65], 0
	s_waitcnt lgkmcnt(1)
	v_mfma_f32_16x16x32_bf16 v[38:41], v[40:43], v[66:69], 0
	ds_read_b128 v[66:69], v74 offset:31296
	v_or_b32_e32 v42, 32, v135
	v_or_b32_e32 v43, 48, v135
	s_waitcnt lgkmcnt(0)
	v_mfma_f32_16x16x32_bf16 v[54:57], v[70:73], v[66:69], v[54:57]
	ds_read_b128 v[66:69], v74 offset:33600
	s_waitcnt lgkmcnt(0)
	v_mfma_f32_16x16x32_bf16 v[58:61], v[70:73], v[66:69], v[58:61]
	ds_read_b128 v[66:69], v74 offset:35904
	ds_read_b128 v[136:139], v74 offset:38208
	s_nop 2
	v_add_u32_e32 v54, 0x8000, v54
	v_lshrrev_b32_e32 v54, 16, v54
	s_waitcnt lgkmcnt(1)
	v_mfma_f32_16x16x32_bf16 v[62:65], v[70:73], v[66:69], v[62:65]
	v_mul_lo_u32 v66, v53, s34
	v_cndmask_b32_e32 v54, 0, v54, vcc
	v_or_b32_e32 v36, v66, v36
	ds_write_b16 v36, v54 offset:40448
	v_or_b32_e32 v54, 1, v53
	v_add_u32_e32 v55, 0x8000, v55
	v_lshrrev_b32_e32 v55, 16, v55
	v_cmp_le_i32_e32 vcc, v135, v54
	v_add_u32_e32 v56, 0x8000, v56
	v_lshrrev_b32_e32 v56, 16, v56
	v_cndmask_b32_e32 v55, 0, v55, vcc
	ds_write_b16 v36, v55 offset:40592
	v_or_b32_e32 v55, 2, v53
	v_cmp_le_i32_e32 vcc, v135, v55
	v_add_u32_e32 v57, 0x8000, v57
	v_lshrrev_b32_e32 v57, 16, v57
	v_cndmask_b32_e32 v56, 0, v56, vcc
	ds_write_b16 v36, v56 offset:40736
	v_or_b32_e32 v56, 3, v53
	v_cmp_le_i32_e32 vcc, v135, v56
	s_waitcnt lgkmcnt(3)
	v_mfma_f32_16x16x32_bf16 v[38:41], v[70:73], v[136:139], v[38:41]
	v_cmp_lt_u32_e64 s[34:35], v77, v3
	v_cndmask_b32_e32 v57, 0, v57, vcc
	ds_write_b16 v36, v57 offset:40880
	v_add_u32_e32 v57, 0x8000, v58
	v_lshrrev_b32_e32 v57, 16, v57
	v_cmp_le_i32_e32 vcc, v37, v53
	s_nop 1
	v_cndmask_b32_e32 v57, 0, v57, vcc
	ds_write_b16 v36, v57 offset:40480
	v_add_u32_e32 v57, 0x8000, v59
	v_lshrrev_b32_e32 v57, 16, v57
	v_cmp_le_i32_e32 vcc, v37, v54
	s_nop 1
	v_cndmask_b32_e32 v57, 0, v57, vcc
	ds_write_b16 v36, v57 offset:40624
	v_add_u32_e32 v57, 0x8000, v60
	v_lshrrev_b32_e32 v57, 16, v57
	v_cmp_le_i32_e32 vcc, v37, v55
	s_nop 1
	v_cndmask_b32_e32 v57, 0, v57, vcc
	ds_write_b16 v36, v57 offset:40768
	v_add_u32_e32 v57, 0x8000, v61
	v_lshrrev_b32_e32 v57, 16, v57
	v_cmp_le_i32_e32 vcc, v37, v56
	s_nop 1
	v_cndmask_b32_e32 v37, 0, v57, vcc
	ds_write_b16 v36, v37 offset:40912
	v_add_u32_e32 v37, 0x8000, v62
	v_lshrrev_b32_e32 v37, 16, v37
	v_cmp_le_i32_e32 vcc, v42, v53
	s_nop 1
	v_cndmask_b32_e32 v37, 0, v37, vcc
	ds_write_b16 v36, v37 offset:40512
	v_add_u32_e32 v37, 0x8000, v63
	v_lshrrev_b32_e32 v37, 16, v37
	v_cmp_le_i32_e32 vcc, v42, v54
	s_nop 1
	v_cndmask_b32_e32 v37, 0, v37, vcc
	ds_write_b16 v36, v37 offset:40656
	v_add_u32_e32 v37, 0x8000, v64
	v_lshrrev_b32_e32 v37, 16, v37
	v_cmp_le_i32_e32 vcc, v42, v55
	s_nop 1
	v_cndmask_b32_e32 v37, 0, v37, vcc
	ds_write_b16 v36, v37 offset:40800
	v_add_u32_e32 v37, 0x8000, v65
	v_lshrrev_b32_e32 v37, 16, v37
	v_cmp_le_i32_e32 vcc, v42, v56
	s_nop 1
	v_cndmask_b32_e32 v37, 0, v37, vcc
	ds_write_b16 v36, v37 offset:40944
	v_add_u32_e32 v37, 0x8000, v38
	v_lshrrev_b32_e32 v37, 16, v37
	v_cmp_le_i32_e32 vcc, v43, v53
	v_ashrrev_i32_e32 v53, 31, v52
	s_nop 0
	v_cndmask_b32_e32 v37, 0, v37, vcc
	ds_write_b16 v36, v37 offset:40544
	v_add_u32_e32 v37, 0x8000, v39
	v_lshrrev_b32_e32 v37, 16, v37
	v_cmp_le_i32_e32 vcc, v43, v54
	s_nop 1
	v_cndmask_b32_e32 v37, 0, v37, vcc
	ds_write_b16 v36, v37 offset:40688
	v_add_u32_e32 v37, 0x8000, v40
	v_lshrrev_b32_e32 v37, 16, v37
	v_cmp_le_i32_e32 vcc, v43, v55
	s_nop 1
	v_cndmask_b32_e32 v37, 0, v37, vcc
	ds_write_b16 v36, v37 offset:40832
	v_add_u32_e32 v37, 0x8000, v41
	v_lshrrev_b32_e32 v37, 16, v37
	v_cmp_le_i32_e32 vcc, v43, v56
	s_nop 1
	v_cndmask_b32_e32 v37, 0, v37, vcc
	ds_write_b16 v36, v37 offset:40976
	s_waitcnt lgkmcnt(0)
	s_barrier
; DEVINL f32x4 mfma16(bf16x8 a, bf16x8 b, f32x4 c) { return __builtin_amdgcn_mfma_f32_16x16x32_bf16(a, b, c, 0, 0, 0); }
; DEVINL void gla_passC(const Params& p, char* smem, int item) {
;     ...
;   f32x4 o[4][2];
; #pragma unroll
;   for (int a = 0; a < 4; ++a) { o[a][0] = f32x4{0, 0, 0, 0}; o[a][1] = f32x4{0, 0, 0, 0}; }
; #pragma unroll
;   for (int ks = 0; ks < 2; ++ks) {
;     const int kb = ks * 32 + 8 * (lane >> 4);
;     bf16x8 bv[2], bs[2];
; #pragma unroll
;     for (int nf = 0; nf < 2; ++nf) { bv[nf] = bvv[ks][nf]; bs[nf] = bss[ks][nf]; }
; #pragma unroll
;     for (int mf = 0; mf < 4; ++mf) {
;       bf16x8 aa = *(const bf16x8*)(Att + (mf * 16 + (lane & 15)) * 72 + kb);
;       bf16x8 aq = *(const bf16x8*)(Qd + (mf * 16 + (lane & 15)) * 72 + kb);
; #pragma unroll
;       for (int nf = 0; nf < 2; ++nf) {
;         o[mf][nf] = mfma16(aa, bv[nf], o[mf][nf]);
;         o[mf][nf] = mfma16(aq, bs[nf], o[mf][nf]);
;       }
;     }
;   }
; #pragma unroll
;   for (int mf = 0; mf < 4; ++mf)
; #pragma unroll
;     for (int j = 0; j < 4; ++j) {
;       const float s = red16(o[mf][0][j] * o[mf][0][j] + o[mf][1][j] * o[mf][1][j]);
;       red[w * 64 + mf * 16 + (lane >> 4) * 4 + j] = s;
;     }
	ds_read_b128 v[36:39], v74 offset:40448
	ds_read_b128 v[54:57], v74 offset:22016
	s_waitcnt lgkmcnt(1)
	v_mfma_f32_16x16x32_bf16 v[40:43], v[36:39], v[12:15], 0
	ds_read_b128 v[62:65], v74 offset:24320
	ds_read_b128 v[70:73], v74 offset:26624
	ds_read_b128 v[136:139], v74 offset:28928
	v_mfma_f32_16x16x32_bf16 v[36:39], v[36:39], v[28:31], 0
	s_waitcnt lgkmcnt(3)
	v_mfma_f32_16x16x32_bf16 v[40:43], v[54:57], v[16:19], v[40:43]
	v_mfma_f32_16x16x32_bf16 v[36:39], v[54:57], v[32:35], v[36:39]
	ds_read_b128 v[54:57], v74 offset:42752
	s_waitcnt lgkmcnt(0)
	v_mfma_f32_16x16x32_bf16 v[58:61], v[54:57], v[12:15], 0
	v_mfma_f32_16x16x32_bf16 v[54:57], v[54:57], v[28:31], 0
	v_mfma_f32_16x16x32_bf16 v[58:61], v[62:65], v[16:19], v[58:61]
	v_mfma_f32_16x16x32_bf16 v[54:57], v[62:65], v[32:35], v[54:57]
	ds_read_b128 v[62:65], v74 offset:45056
	s_waitcnt lgkmcnt(0)
	v_mfma_f32_16x16x32_bf16 v[66:69], v[62:65], v[12:15], 0
	v_mfma_f32_16x16x32_bf16 v[62:65], v[62:65], v[28:31], 0
	v_mfma_f32_16x16x32_bf16 v[66:69], v[70:73], v[16:19], v[66:69]
	v_mfma_f32_16x16x32_bf16 v[62:65], v[70:73], v[32:35], v[62:65]
	ds_read_b128 v[70:73], v74 offset:47360
	s_waitcnt lgkmcnt(0)
	v_mfma_f32_16x16x32_bf16 v[12:15], v[70:73], v[12:15], 0
	v_mfma_f32_16x16x32_bf16 v[140:143], v[136:139], v[16:19], v[12:15]
	v_mfma_f32_16x16x32_bf16 v[12:15], v[70:73], v[28:31], 0
	ds_read_b128 v[28:31], v74 offset:22080
	v_mfma_f32_16x16x32_bf16 v[70:73], v[136:139], v[32:35], v[12:15]
	s_nop 5
	ds_read_b128 v[12:15], v74 offset:40512
	s_waitcnt lgkmcnt(0)
	v_mfma_f32_16x16x32_bf16 v[16:19], v[12:15], v[8:11], v[40:43]
	v_mfma_f32_16x16x32_bf16 v[12:15], v[12:15], v[20:23], v[36:39]
	v_mfma_f32_16x16x32_bf16 v[36:39], v[28:31], v[24:27], v[12:15]
	v_mfma_f32_16x16x32_bf16 v[40:43], v[28:31], v[4:7], v[16:19]
	s_nop 5
	ds_read_b128 v[12:15], v74 offset:42816
	ds_read_b128 v[28:31], v74 offset:24384
	s_waitcnt lgkmcnt(1)
	v_mfma_f32_16x16x32_bf16 v[16:19], v[12:15], v[8:11], v[58:61]
	s_nop 2
	ds_read_b128 v[58:61], v74 offset:28992
	v_mfma_f32_16x16x32_bf16 v[12:15], v[12:15], v[20:23], v[54:57]
	s_waitcnt lgkmcnt(1)
	v_mfma_f32_16x16x32_bf16 v[32:35], v[28:31], v[4:7], v[16:19]
	s_nop 0
	ds_read_b128 v[54:57], v74 offset:26688
	v_mfma_f32_16x16x32_bf16 v[28:31], v[28:31], v[24:27], v[12:15]
	s_nop 2
	ds_read_b128 v[12:15], v74 offset:45120
	s_waitcnt lgkmcnt(0)
	v_mfma_f32_16x16x32_bf16 v[16:19], v[12:15], v[8:11], v[66:69]
	v_mfma_f32_16x16x32_bf16 v[12:15], v[12:15], v[20:23], v[62:65]
	v_mfma_f32_16x16x32_bf16 v[16:19], v[54:57], v[4:7], v[16:19]
	v_mfma_f32_16x16x32_bf16 v[12:15], v[54:57], v[24:27], v[12:15]
	ds_read_b128 v[54:57], v74 offset:47424
	s_waitcnt lgkmcnt(0)
	v_mfma_f32_16x16x32_bf16 v[8:11], v[54:57], v[8:11], v[140:143]
	v_mfma_f32_16x16x32_bf16 v[8:11], v[58:61], v[4:7], v[8:11]
	v_mfma_f32_16x16x32_bf16 v[4:7], v[54:57], v[20:23], v[70:73]
	v_and_b32_e32 v20, 0x3fffffc0, v134
	v_lshlrev_b32_e32 v23, 2, v77
	v_lshl_or_b32 v22, v20, 2, v23
	v_mfma_f32_16x16x32_bf16 v[4:7], v[58:61], v[24:27], v[4:7]
	v_mul_f32_e64 v24, v36, v36
	v_mul_f32_e64 v25, v37, v37
	v_pk_mul_f32 v[20:21], v[38:39], v[38:39]
	v_pk_fma_f32 v[24:25], v[40:41], v[40:41], v[24:25]
	v_pk_fma_f32 v[20:21], v[42:43], v[42:43], v[20:21]
	s_nop 0
	v_mov_b32_dpp v26, v24 quad_perm:[1,0,3,2] row_mask:0xf bank_mask:0xf bound_ctrl:1
	v_mov_b32_dpp v27, v25 quad_perm:[1,0,3,2] row_mask:0xf bank_mask:0xf bound_ctrl:1
	v_pk_add_f32 v[24:25], v[24:25], v[26:27]
	s_nop 1
	v_mov_b32_dpp v26, v24 quad_perm:[2,3,0,1] row_mask:0xf bank_mask:0xf bound_ctrl:1
	v_mov_b32_dpp v27, v25 quad_perm:[2,3,0,1] row_mask:0xf bank_mask:0xf bound_ctrl:1
	v_pk_add_f32 v[24:25], v[24:25], v[26:27]
	s_nop 1
	v_mov_b32_dpp v26, v24 row_half_mirror row_mask:0xf bank_mask:0xf bound_ctrl:1
	v_mov_b32_dpp v27, v25 row_half_mirror row_mask:0xf bank_mask:0xf bound_ctrl:1
	v_pk_add_f32 v[24:25], v[24:25], v[26:27]
	s_nop 1
	v_mov_b32_dpp v26, v24 row_mirror row_mask:0xf bank_mask:0xf bound_ctrl:1
	v_mov_b32_dpp v27, v25 row_mirror row_mask:0xf bank_mask:0xf bound_ctrl:1
	v_pk_add_f32 v[24:25], v[24:25], v[26:27]
	v_mov_b32_dpp v26, v20 quad_perm:[1,0,3,2] row_mask:0xf bank_mask:0xf bound_ctrl:1
	v_mov_b32_dpp v27, v21 quad_perm:[1,0,3,2] row_mask:0xf bank_mask:0xf bound_ctrl:1
	v_pk_add_f32 v[20:21], v[20:21], v[26:27]
	s_nop 1
	v_mov_b32_dpp v26, v20 quad_perm:[2,3,0,1] row_mask:0xf bank_mask:0xf bound_ctrl:1
	v_mov_b32_dpp v27, v21 quad_perm:[2,3,0,1] row_mask:0xf bank_mask:0xf bound_ctrl:1
	v_pk_add_f32 v[20:21], v[20:21], v[26:27]
	s_nop 1
	v_mov_b32_dpp v26, v20 row_half_mirror row_mask:0xf bank_mask:0xf bound_ctrl:1
	v_mov_b32_dpp v27, v21 row_half_mirror row_mask:0xf bank_mask:0xf bound_ctrl:1
	v_pk_add_f32 v[20:21], v[20:21], v[26:27]
	s_nop 1
	v_mov_b32_dpp v26, v20 row_mirror row_mask:0xf bank_mask:0xf bound_ctrl:1
	v_mov_b32_dpp v27, v21 row_mirror row_mask:0xf bank_mask:0xf bound_ctrl:1
	v_pk_add_f32 v[26:27], v[20:21], v[26:27]
	ds_write_b128 v22, v[24:27] offset:49664
	v_pk_mul_f32 v[24:25], v[28:29], v[28:29]
	v_pk_mul_f32 v[20:21], v[30:31], v[30:31]
	v_pk_fma_f32 v[24:25], v[32:33], v[32:33], v[24:25]
	v_pk_fma_f32 v[20:21], v[34:35], v[34:35], v[20:21]
	s_nop 0
	v_mov_b32_dpp v26, v24 quad_perm:[1,0,3,2] row_mask:0xf bank_mask:0xf bound_ctrl:1
	v_mov_b32_dpp v27, v25 quad_perm:[1,0,3,2] row_mask:0xf bank_mask:0xf bound_ctrl:1
	v_pk_add_f32 v[24:25], v[24:25], v[26:27]
	s_nop 1
	v_mov_b32_dpp v26, v24 quad_perm:[2,3,0,1] row_mask:0xf bank_mask:0xf bound_ctrl:1
	v_mov_b32_dpp v27, v25 quad_perm:[2,3,0,1] row_mask:0xf bank_mask:0xf bound_ctrl:1
	v_pk_add_f32 v[24:25], v[24:25], v[26:27]
	s_nop 1
; DEVINL void gla_passC(const Params& p, char* smem, int item) {
;     ...
; #pragma unroll
;   for (int mf = 0; mf < 4; ++mf)
; #pragma unroll
;     for (int j = 0; j < 4; ++j) {
;       const float s = red16(o[mf][0][j] * o[mf][0][j] + o[mf][1][j] * o[mf][1][j]);
;       red[w * 64 + mf * 16 + (lane >> 4) * 4 + j] = s;
;     }
;   __syncthreads();
;   u16* mixin = (u16*)(p.ws + OFF_MIXIN);
;   float gn[2];
; #pragma unroll
;   for (int nf = 0; nf < 2; ++nf) gn[nf] = p.gla_norm[32 * w + nf * 16 + (lane & 15)];
; #pragma unroll
;   for (int mf = 0; mf < 4; ++mf) {
;     const int t0 = mf * 16 + (lane >> 4) * 4;
;     if (t0 < ci.T) {
	v_mov_b32_dpp v26, v24 row_half_mirror row_mask:0xf bank_mask:0xf bound_ctrl:1
	v_mov_b32_dpp v27, v25 row_half_mirror row_mask:0xf bank_mask:0xf bound_ctrl:1
	v_pk_add_f32 v[24:25], v[24:25], v[26:27]
	s_nop 1
	v_mov_b32_dpp v26, v24 row_mirror row_mask:0xf bank_mask:0xf bound_ctrl:1
	v_mov_b32_dpp v27, v25 row_mirror row_mask:0xf bank_mask:0xf bound_ctrl:1
	v_pk_add_f32 v[24:25], v[24:25], v[26:27]
	v_mov_b32_dpp v26, v20 quad_perm:[1,0,3,2] row_mask:0xf bank_mask:0xf bound_ctrl:1
	v_mov_b32_dpp v27, v21 quad_perm:[1,0,3,2] row_mask:0xf bank_mask:0xf bound_ctrl:1
	v_pk_add_f32 v[20:21], v[20:21], v[26:27]
	s_nop 1
	v_mov_b32_dpp v26, v20 quad_perm:[2,3,0,1] row_mask:0xf bank_mask:0xf bound_ctrl:1
	v_mov_b32_dpp v27, v21 quad_perm:[2,3,0,1] row_mask:0xf bank_mask:0xf bound_ctrl:1
	v_pk_add_f32 v[20:21], v[20:21], v[26:27]
	s_nop 1
	v_mov_b32_dpp v26, v20 row_half_mirror row_mask:0xf bank_mask:0xf bound_ctrl:1
	v_mov_b32_dpp v27, v21 row_half_mirror row_mask:0xf bank_mask:0xf bound_ctrl:1
	v_pk_add_f32 v[20:21], v[20:21], v[26:27]
	s_nop 1
	v_mov_b32_dpp v26, v20 row_mirror row_mask:0xf bank_mask:0xf bound_ctrl:1
	v_mov_b32_dpp v27, v21 row_mirror row_mask:0xf bank_mask:0xf bound_ctrl:1
	v_pk_add_f32 v[26:27], v[20:21], v[26:27]
	ds_write_b128 v22, v[24:27] offset:49728
	v_pk_mul_f32 v[24:25], v[12:13], v[12:13]
	v_pk_mul_f32 v[20:21], v[14:15], v[14:15]
	v_pk_fma_f32 v[24:25], v[16:17], v[16:17], v[24:25]
	v_pk_fma_f32 v[20:21], v[18:19], v[18:19], v[20:21]
	s_nop 0
	v_mov_b32_dpp v26, v24 quad_perm:[1,0,3,2] row_mask:0xf bank_mask:0xf bound_ctrl:1
	v_mov_b32_dpp v27, v25 quad_perm:[1,0,3,2] row_mask:0xf bank_mask:0xf bound_ctrl:1
	v_pk_add_f32 v[24:25], v[24:25], v[26:27]
	s_nop 1
	v_mov_b32_dpp v26, v24 quad_perm:[2,3,0,1] row_mask:0xf bank_mask:0xf bound_ctrl:1
	v_mov_b32_dpp v27, v25 quad_perm:[2,3,0,1] row_mask:0xf bank_mask:0xf bound_ctrl:1
	v_pk_add_f32 v[24:25], v[24:25], v[26:27]
	s_nop 1
	v_mov_b32_dpp v26, v24 row_half_mirror row_mask:0xf bank_mask:0xf bound_ctrl:1
	v_mov_b32_dpp v27, v25 row_half_mirror row_mask:0xf bank_mask:0xf bound_ctrl:1
	v_pk_add_f32 v[24:25], v[24:25], v[26:27]
	s_nop 1
	v_mov_b32_dpp v26, v24 row_mirror row_mask:0xf bank_mask:0xf bound_ctrl:1
	v_mov_b32_dpp v27, v25 row_mirror row_mask:0xf bank_mask:0xf bound_ctrl:1
	v_pk_add_f32 v[24:25], v[24:25], v[26:27]
	v_mov_b32_dpp v26, v20 quad_perm:[1,0,3,2] row_mask:0xf bank_mask:0xf bound_ctrl:1
	v_mov_b32_dpp v27, v21 quad_perm:[1,0,3,2] row_mask:0xf bank_mask:0xf bound_ctrl:1
	v_pk_add_f32 v[20:21], v[20:21], v[26:27]
	s_nop 1
	v_mov_b32_dpp v26, v20 quad_perm:[2,3,0,1] row_mask:0xf bank_mask:0xf bound_ctrl:1
	v_mov_b32_dpp v27, v21 quad_perm:[2,3,0,1] row_mask:0xf bank_mask:0xf bound_ctrl:1
	v_pk_add_f32 v[20:21], v[20:21], v[26:27]
	s_nop 1
	v_mov_b32_dpp v26, v20 row_half_mirror row_mask:0xf bank_mask:0xf bound_ctrl:1
	v_mov_b32_dpp v27, v21 row_half_mirror row_mask:0xf bank_mask:0xf bound_ctrl:1
	v_pk_add_f32 v[20:21], v[20:21], v[26:27]
	s_nop 1
	v_mov_b32_dpp v26, v20 row_mirror row_mask:0xf bank_mask:0xf bound_ctrl:1
	v_mov_b32_dpp v27, v21 row_mirror row_mask:0xf bank_mask:0xf bound_ctrl:1
	v_pk_add_f32 v[26:27], v[20:21], v[26:27]
	ds_write_b128 v22, v[24:27] offset:49792
	v_pk_mul_f32 v[24:25], v[4:5], v[4:5]
	v_pk_mul_f32 v[20:21], v[6:7], v[6:7]
	v_pk_fma_f32 v[24:25], v[8:9], v[8:9], v[24:25]
	v_pk_fma_f32 v[20:21], v[10:11], v[10:11], v[20:21]
	s_nop 0
	v_mov_b32_dpp v26, v24 quad_perm:[1,0,3,2] row_mask:0xf bank_mask:0xf bound_ctrl:1
	v_mov_b32_dpp v27, v25 quad_perm:[1,0,3,2] row_mask:0xf bank_mask:0xf bound_ctrl:1
	v_pk_add_f32 v[24:25], v[24:25], v[26:27]
	s_nop 1
	v_mov_b32_dpp v26, v24 quad_perm:[2,3,0,1] row_mask:0xf bank_mask:0xf bound_ctrl:1
	v_mov_b32_dpp v27, v25 quad_perm:[2,3,0,1] row_mask:0xf bank_mask:0xf bound_ctrl:1
	v_pk_add_f32 v[24:25], v[24:25], v[26:27]
	s_nop 1
	v_mov_b32_dpp v26, v24 row_half_mirror row_mask:0xf bank_mask:0xf bound_ctrl:1
	v_mov_b32_dpp v27, v25 row_half_mirror row_mask:0xf bank_mask:0xf bound_ctrl:1
	v_pk_add_f32 v[24:25], v[24:25], v[26:27]
	s_nop 1
	v_mov_b32_dpp v26, v24 row_mirror row_mask:0xf bank_mask:0xf bound_ctrl:1
	v_mov_b32_dpp v27, v25 row_mirror row_mask:0xf bank_mask:0xf bound_ctrl:1
	v_pk_add_f32 v[24:25], v[24:25], v[26:27]
	v_mov_b32_dpp v26, v20 quad_perm:[1,0,3,2] row_mask:0xf bank_mask:0xf bound_ctrl:1
	v_mov_b32_dpp v27, v21 quad_perm:[1,0,3,2] row_mask:0xf bank_mask:0xf bound_ctrl:1
	v_pk_add_f32 v[20:21], v[20:21], v[26:27]
	s_nop 1
	v_mov_b32_dpp v26, v20 quad_perm:[2,3,0,1] row_mask:0xf bank_mask:0xf bound_ctrl:1
	v_mov_b32_dpp v27, v21 quad_perm:[2,3,0,1] row_mask:0xf bank_mask:0xf bound_ctrl:1
	v_pk_add_f32 v[20:21], v[20:21], v[26:27]
	s_nop 1
	v_mov_b32_dpp v26, v20 row_half_mirror row_mask:0xf bank_mask:0xf bound_ctrl:1
	v_mov_b32_dpp v27, v21 row_half_mirror row_mask:0xf bank_mask:0xf bound_ctrl:1
	v_pk_add_f32 v[20:21], v[20:21], v[26:27]
	s_nop 1
	v_mov_b32_dpp v26, v20 row_mirror row_mask:0xf bank_mask:0xf bound_ctrl:1
	v_mov_b32_dpp v27, v21 row_mirror row_mask:0xf bank_mask:0xf bound_ctrl:1
	v_pk_add_f32 v[26:27], v[20:21], v[26:27]
	v_lshl_add_u64 v[20:21], v[52:53], 2, s[72:73]
	ds_write_b128 v22, v[24:27] offset:49856
	s_waitcnt lgkmcnt(0)
	s_barrier
	global_load_dword v24, v[20:21], off
	global_load_dword v22, v[20:21], off offset:64
	v_and_or_b32 v20, v134, 14, v48
	v_add_u32_e32 v20, v20, v50
	v_and_b32_e32 v21, 1, v134
	v_cmp_eq_u32_e32 vcc, 0, v21
	v_lshl_add_u32 v25, v21, 1, v44
	v_ashrrev_i32_e32 v21, 31, v20
	s_and_saveexec_b64 s[42:43], s[34:35]
	s_cbranch_execz .LBB0_409
; DEVINL float bf2f(u16 h) { return __uint_as_float(((unsigned)h) << 16); }
; DEVINL float siluf_(float x) { return x * __builtin_amdgcn_rcpf(1.f + __expf(-x)); }
; DEVINL void gla_passC(const Params& p, char* smem, int item) {
;     ...
;   for (int mf = 0; mf < 4; ++mf) {
;     const int t0 = mf * 16 + (lane >> 4) * 4;
;     if (t0 < ci.T) {
;       float rs[4];
; #pragma unroll
;       for (int j = 0; j < 4; ++j) {
;         const int t = t0 + j;
;         rs[j] = rsqrtf((red[t] + red[64 + t] + red[128 + t] + red[192 + t]) * (1.f / 128.f) + EPS);
;       }
; #pragma unroll
;       for (int nf = 0; nf < 2; ++nf) {
;         const int dv = 32 * w + nf * 16 + (lane & 15);
;         float o4[4];
; #pragma unroll
;         for (int j = 0; j < 4; ++j) {
;           float gv = bf2f(graw[mf][nf][j]);
;           o4[j] = o[mf][nf][j] * rs[j] * gn[nf] * siluf_(gv);
;         }
;         store_pairs(mixin, 1024, ci.r0 + t0, ci.h * 128 + dv, o4[0], o4[1], o4[2], o4[3]);
;       }
	ds_read_b128 v[52:55], v23 offset:49664
	ds_read_b128 v[56:59], v23 offset:49920
	ds_read_b128 v[60:63], v23 offset:50176
	ds_read_b128 v[64:67], v23 offset:50432
	s_mov_b32 s0, 0x358637bd
	s_waitcnt lgkmcnt(2)
	v_pk_add_f32 v[26:27], v[52:53], v[56:57]
	s_waitcnt lgkmcnt(1)
	v_pk_add_f32 v[26:27], v[26:27], v[60:61]
	v_mov_b64_e32 v[52:53], s[0:1]
	s_waitcnt lgkmcnt(0)
	v_pk_add_f32 v[26:27], v[26:27], v[64:65]
	s_brev_b32 s0, 60
	v_pk_fma_f32 v[26:27], v[26:27], s[0:1], v[52:53] op_sel_hi:[1,0,0]
	s_nop 0
	v_mul_f32_e32 v44, 0x4b800000, v26
	v_cmp_gt_f32_e64 s[36:37], s33, v26
	v_cmp_gt_f32_e64 s[34:35], s33, v27
	s_nop 0
	v_cndmask_b32_e64 v26, v26, v44, s[36:37]
	v_rsq_f32_e32 v26, v26
	s_nop 0
	v_mul_f32_e32 v44, 0x45800000, v26
	v_cndmask_b32_e64 v44, v26, v44, s[36:37]
	v_mul_f32_e32 v26, 0x4b800000, v27
	v_cndmask_b32_e64 v26, v27, v26, s[34:35]
	v_rsq_f32_e32 v26, v26
	v_mul_f32_e32 v40, v40, v44
	s_waitcnt vmcnt(1)
	v_mul_f32_e32 v40, v24, v40
	v_mul_f32_e32 v36, v36, v44
	v_mul_f32_e32 v27, 0x45800000, v26
	v_cndmask_b32_e64 v48, v26, v27, s[34:35]
	v_pk_add_f32 v[26:27], v[54:55], v[58:59]
	v_mul_f32_e32 v41, v41, v48
	v_pk_add_f32 v[26:27], v[26:27], v[62:63]
	v_mul_f32_e32 v41, v24, v41
	v_pk_add_f32 v[26:27], v[26:27], v[66:67]
	s_waitcnt vmcnt(0)
	v_mul_f32_e32 v36, v22, v36
	v_pk_fma_f32 v[26:27], v[26:27], s[0:1], v[52:53] op_sel_hi:[1,0,0]
	v_lshlrev_b32_e32 v53, 16, v133
	v_mul_f32_e32 v54, 0xbfb8aa3b, v53
	v_exp_f32_e32 v54, v54
	v_mul_f32_e32 v50, 0x4b800000, v26
	v_cmp_gt_f32_e64 s[36:37], s33, v26
	v_cmp_gt_f32_e64 s[34:35], s33, v27
	v_add_f32_e32 v54, 1.0, v54
	v_rcp_f32_e32 v54, v54
	v_cndmask_b32_e64 v26, v26, v50, s[36:37]
	v_rsq_f32_e32 v26, v26
	v_readlane_b32 s0, v194, 19
	v_mul_f32_e32 v53, v54, v53
	v_mul_f32_e32 v40, v53, v40
	v_lshlrev_b32_e32 v53, 16, v132
	v_mul_f32_e32 v54, 0xbfb8aa3b, v53
	v_exp_f32_e32 v54, v54
	v_mul_f32_e32 v50, 0x45800000, v26
	v_cndmask_b32_e64 v50, v26, v50, s[36:37]
	v_mul_f32_e32 v42, v42, v50
	v_add_f32_e32 v54, 1.0, v54
	v_rcp_f32_e32 v54, v54
	v_mul_f32_e32 v42, v24, v42
	v_mul_f32_e32 v26, 0x4b800000, v27
	v_cndmask_b32_e64 v26, v27, v26, s[34:35]
	v_mul_f32_e32 v53, v54, v53
	v_mul_f32_e32 v41, v53, v41
	v_lshlrev_b32_e32 v53, 16, v131
	v_mul_f32_e32 v54, 0xbfb8aa3b, v53
	v_exp_f32_e32 v54, v54
	v_rsq_f32_e32 v26, v26
	v_readlane_b32 s1, v194, 20
	v_mul_f32_e32 v37, v37, v48
	v_add_f32_e32 v54, 1.0, v54
	v_rcp_f32_e32 v54, v54
	v_mul_f32_e32 v27, 0x45800000, v26
	v_cndmask_b32_e64 v52, v26, v27, s[34:35]
	v_mul_f32_e32 v43, v43, v52
	v_mul_f32_e32 v53, v54, v53
	v_mul_f32_e32 v42, v53, v42
	v_lshlrev_b32_e32 v53, 16, v113
	v_mul_f32_e32 v54, 0xbfb8aa3b, v53
	v_exp_f32_e32 v54, v54
	v_mul_f32_e32 v43, v24, v43
	v_add_u32_e32 v26, v25, v77
	v_mov_b32_dpp v55, v42 quad_perm:[1,0,3,2] row_mask:0xf bank_mask:0xf bound_ctrl:1
	v_add_f32_e32 v54, 1.0, v54
	v_rcp_f32_e32 v54, v54
	v_ashrrev_i32_e32 v27, 31, v26
	v_lshlrev_b64 v[26:27], 11, v[26:27]
	v_lshl_add_u64 v[26:27], s[0:1], 0, v[26:27]
	v_mul_f32_e32 v53, v54, v53
	v_mul_f32_e32 v43, v53, v43
	v_mov_b32_dpp v54, v41 quad_perm:[1,0,3,2] row_mask:0xf bank_mask:0xf bound_ctrl:1
	v_mov_b32_dpp v53, v40 quad_perm:[1,0,3,2] row_mask:0xf bank_mask:0xf bound_ctrl:1
	v_cndmask_b32_e32 v42, v42, v53, vcc
	v_cndmask_b32_e32 v40, v55, v40, vcc
	v_mov_b32_dpp v56, v43 quad_perm:[1,0,3,2] row_mask:0xf bank_mask:0xf bound_ctrl:1
	v_add_u32_e32 v42, 0x8000, v42
	v_add_u32_e32 v40, 0x8000, v40
	v_perm_b32 v40, v42, v40, s25
	v_cndmask_b32_e32 v42, v43, v54, vcc
	v_cndmask_b32_e32 v41, v56, v41, vcc
	v_add_u32_e32 v42, 0x8000, v42
	v_add_u32_e32 v41, 0x8000, v41
	v_lshl_add_u64 v[26:27], v[20:21], 1, v[26:27]
	v_perm_b32 v41, v42, v41, s25
	global_store_dword v[26:27], v40, off
	global_store_dword v[26:27], v41, off offset:2048
	v_lshlrev_b32_e32 v40, 16, v112
	v_mul_f32_e32 v41, 0xbfb8aa3b, v40
	v_exp_f32_e32 v41, v41
	v_mul_f32_e32 v37, v22, v37
	v_mul_f32_e32 v38, v38, v50
	v_mul_f32_e32 v38, v22, v38
	v_add_f32_e32 v41, 1.0, v41
	v_rcp_f32_e32 v41, v41
	v_mul_f32_e32 v39, v39, v52
	v_mul_f32_e32 v39, v22, v39
	v_mul_f32_e32 v40, v41, v40
	v_mul_f32_e32 v36, v40, v36
	v_lshlrev_b32_e32 v40, 16, v111
	v_mul_f32_e32 v41, 0xbfb8aa3b, v40
	v_exp_f32_e32 v41, v41
	s_nop 0
	v_add_f32_e32 v41, 1.0, v41
	v_rcp_f32_e32 v41, v41
	s_nop 0
	v_mul_f32_e32 v40, v41, v40
	v_mul_f32_e32 v37, v40, v37
	v_lshlrev_b32_e32 v40, 16, v110
	v_mul_f32_e32 v41, 0xbfb8aa3b, v40
	v_exp_f32_e32 v41, v41
	s_nop 0
	v_add_f32_e32 v41, 1.0, v41
	v_rcp_f32_e32 v41, v41
	s_nop 0
	v_mul_f32_e32 v40, v41, v40
	v_mul_f32_e32 v38, v40, v38
	v_lshlrev_b32_e32 v40, 16, v109
	v_mul_f32_e32 v41, 0xbfb8aa3b, v40
	v_exp_f32_e32 v41, v41
	v_mov_b32_dpp v42, v38 quad_perm:[1,0,3,2] row_mask:0xf bank_mask:0xf bound_ctrl:1
	v_add_f32_e32 v41, 1.0, v41
	v_rcp_f32_e32 v41, v41
	s_nop 0
	v_mul_f32_e32 v40, v41, v40
	v_mul_f32_e32 v39, v40, v39
	s_nop 0
	v_mov_b32_dpp v40, v36 quad_perm:[1,0,3,2] row_mask:0xf bank_mask:0xf bound_ctrl:1
	v_cndmask_b32_e32 v38, v38, v40, vcc
	v_cndmask_b32_e32 v36, v42, v36, vcc
	v_mov_b32_dpp v41, v37 quad_perm:[1,0,3,2] row_mask:0xf bank_mask:0xf bound_ctrl:1
	v_mov_b32_dpp v43, v39 quad_perm:[1,0,3,2] row_mask:0xf bank_mask:0xf bound_ctrl:1
	v_add_u32_e32 v38, 0x8000, v38
	v_add_u32_e32 v36, 0x8000, v36
	v_perm_b32 v36, v38, v36, s25
	v_cndmask_b32_e32 v38, v39, v41, vcc
	v_cndmask_b32_e32 v37, v43, v37, vcc
	v_add_u32_e32 v38, 0x8000, v38
	v_add_u32_e32 v37, 0x8000, v37
	v_perm_b32 v37, v38, v37, s25
	global_store_dword v[26:27], v36, off offset:32
	global_store_dword v[26:27], v37, off offset:2080

; DEVINL void gla_passC(const Params& p, char* smem, int item) {
;     ...
;   const u16* qk = (const u16*)(p.ws + OFF_QK);
;   const u16* vT = (const u16*)(p.ws + OFF_VT);
;   const u16* SpT = (const u16*)(p.ws + OFF_SPT) + (size_t)item * 8192;
;   const u16* gbuf = (const u16*)(p.ws + OFF_GB);
;   u16 qraw[16], kraw16[16];
; #pragma unroll
;   for (int i = 0; i < 16; ++i) {
;     const int t = 16 * w + i;
;     qraw[i] = qk[(size_t)(ci.r0 + t) * 512 + ci.h * 64 + lane];
;     kraw16[i] = qk[(size_t)(ci.r0 + t) * 512 + 256 + ci.h * 64 + lane];
;   }
;   bf16x8 bvv[2][2], bss[2][2];
; #pragma unroll
;   for (int ks = 0; ks < 2; ++ks) {
;     const int kb = ks * 32 + 8 * (lane >> 4);
; #pragma unroll
;     for (int nf = 0; nf < 2; ++nf) {
;       const int dv = 32 * w + nf * 16 + (lane & 15);
;       bvv[ks][nf] = *(const bf16x8*)(vT + (size_t)(ci.h * 128 + dv) * LDT + ci.r0 + kb);
;       bss[ks][nf] = *(const bf16x8*)(SpT + dv * 64 + kb);
;     }
;   }
;   u16 graw[4][2][4];
; #pragma unroll
;   for (int mf = 0; mf < 4; ++mf) {
;     const int t0 = mf * 16 + (lane >> 4) * 4;
; #pragma unroll
;     for (int nf = 0; nf < 2; ++nf)
; #pragma unroll
;       for (int j = 0; j < 4; ++j)
;         graw[mf][nf][j] = gbuf[(size_t)(ci.r0 + t0 + j) * 512 + ci.h * 128 + 32 * w + nf * 16 + (lane & 15)];
;   }
;   float bcum[16];
;   {
;     const float* bc = (const float*)(p.ws + OFF_BCUM) + (size_t)item * 4096;
; #pragma unroll
;     for (int i = 0; i < 16; ++i) bcum[i] = bc[(16 * w + i) * 64 + lane];
;   }
.LBB0_419:
	s_or_b64 exec, exec, s[0:1]
	v_mov_b32_e32 v132, v0
	v_and_b32_e32 v1, 3, v1
	v_ashrrev_i32_e32 v137, 6, v132
	v_lshlrev_b32_e32 v51, 4, v137
	v_add_u32_e32 v6, v51, v44
	v_ashrrev_i32_e32 v7, 31, v6
	v_lshlrev_b64 v[6:7], 10, v[6:7]
	v_and_b32_e32 v135, 63, v132
	v_mov_b32_e32 v5, v2
	v_readlane_b32 s0, v194, 33
	v_lshl_add_u64 v[6:7], s[94:95], 0, v[6:7]
	v_lshlrev_b32_e32 v46, 7, v1
	v_mov_b32_e32 v47, v2
	v_lshlrev_b64 v[76:77], 14, v[4:5]
	v_readlane_b32 s1, v194, 34
	v_lshl_add_u64 v[6:7], v[6:7], 0, v[46:47]
	v_lshlrev_b32_e32 v8, 1, v135
	v_mov_b32_e32 v9, v2
	v_lshl_add_u64 v[4:5], s[0:1], 0, v[76:77]
	v_lshl_add_u64 v[42:43], v[6:7], 0, v[8:9]
	s_mov_b64 s[0:1], 0x1000
	v_lshl_add_u64 v[66:67], v[42:43], 0, s[0:1]
	s_mov_b64 s[0:1], 0x1400
	v_lshl_add_u64 v[68:69], v[42:43], 0, s[0:1]
	s_mov_b64 s[0:1], 0x1800
	v_lshl_add_u64 v[70:71], v[42:43], 0, s[0:1]
	s_mov_b64 s[0:1], 0x1c00
	v_lshl_add_u64 v[72:73], v[42:43], 0, s[0:1]
	s_mov_b64 s[0:1], 0x2000
	v_lshl_add_u64 v[64:65], v[42:43], 0, s[0:1]
	s_mov_b64 s[0:1], 0x2400
	v_lshl_add_u64 v[62:63], v[42:43], 0, s[0:1]
	s_mov_b64 s[0:1], 0x2800
	v_lshl_add_u64 v[60:61], v[42:43], 0, s[0:1]
	s_mov_b64 s[0:1], 0x2c00
	v_lshl_add_u64 v[58:59], v[42:43], 0, s[0:1]
	s_mov_b64 s[0:1], 0x3000
	v_lshl_add_u64 v[56:57], v[42:43], 0, s[0:1]
	s_mov_b64 s[0:1], 0x3400
	v_lshl_add_u64 v[54:55], v[42:43], 0, s[0:1]
	s_mov_b64 s[0:1], 0x3800
	v_lshlrev_b32_e32 v48, 5, v137
	v_and_b32_e32 v133, 15, v132
	v_lshl_add_u64 v[52:53], v[42:43], 0, s[0:1]
	s_mov_b64 s[0:1], 0x3c00
	v_or_b32_e32 v50, v48, v133
	v_lshl_add_u64 v[40:41], v[42:43], 0, s[0:1]
	v_readlane_b32 s0, v194, 35
	v_and_b32_e32 v38, 48, v132
	v_mov_b32_e32 v39, v2
	v_lshlrev_b32_e32 v10, 6, v50
	v_lshrrev_b32_e32 v36, 2, v132
	v_ashrrev_i32_e32 v45, 31, v44
	v_readlane_b32 s1, v194, 36
	v_lshl_add_u64 v[4:5], v[4:5], 0, v[38:39]
	v_ashrrev_i32_e32 v11, 31, v10
	v_and_b32_e32 v74, 12, v36
	v_lshlrev_b32_e32 v36, 8, v1
	v_mov_b32_e32 v37, v2
	v_lshl_add_u64 v[6:7], v[44:45], 1, s[0:1]
	v_lshl_add_u64 v[20:21], v[10:11], 1, v[4:5]
	v_or_b32_e32 v10, 16, v50
	v_add_u32_e32 v78, v74, v44
	v_ashrrev_i32_e32 v49, 31, v48
	v_lshl_add_u64 v[36:37], s[92:93], 0, v[36:37]
	v_add_u32_e32 v8, v50, v46
	v_lshl_add_u64 v[6:7], v[6:7], 0, v[38:39]
	v_add_u32_e32 v11, v10, v46
	v_lshl_add_u64 v[80:81], v[48:49], 1, v[36:37]
	v_lshlrev_b32_e32 v36, 1, v133
	v_mov_b32_e32 v37, v2
	v_ashrrev_i32_e32 v79, 31, v78
	v_mad_i64_i32 v[8:9], s[0:1], v8, s88, v[6:7]
	v_mad_i64_i32 v[22:23], s[0:1], v11, s88, v[6:7]
	v_lshl_add_u64 v[80:81], v[80:81], 0, v[36:37]
	v_lshlrev_b64 v[78:79], 10, v[78:79]
	v_lshl_add_u64 v[138:139], v[80:81], 0, v[78:79]
	s_movk_i32 s0, 0x4000
	v_add_co_u32_e32 v80, vcc, s0, v138
	s_mov_b64 s[0:1], 0x4400
	v_lshlrev_b32_e32 v6, 6, v10
	v_lshl_add_u64 v[82:83], v[138:139], 0, s[0:1]
	s_mov_b64 s[0:1], 0x4800
	v_ashrrev_i32_e32 v7, 31, v6
	v_lshl_add_u64 v[84:85], v[138:139], 0, s[0:1]
	s_mov_b64 s[0:1], 0x4c00
	v_lshl_add_u64 v[24:25], v[6:7], 1, v[4:5]
	v_lshl_add_u64 v[78:79], v[138:139], 0, s[12:13]
	v_addc_co_u32_e32 v81, vcc, 0, v139, vcc
	v_lshl_add_u64 v[86:87], v[138:139], 0, s[0:1]
	s_mov_b64 s[0:1], 0x8000
	global_load_dwordx4 v[12:15], v[8:9], off
	global_load_dwordx4 v[16:19], v[20:21], off
	global_load_dwordx4 v[28:31], v[22:23], off
	global_load_dwordx4 v[32:35], v[24:25], off
	s_nop 0
	global_load_dwordx4 v[8:11], v[8:9], off offset:64
	s_nop 0
	global_load_dwordx4 v[4:7], v[20:21], off offset:64
	s_nop 0
	global_load_dwordx4 v[20:23], v[22:23], off offset:64
	s_nop 0
	global_load_dwordx4 v[24:27], v[24:25], off offset:64
	s_nop 0
	global_load_ushort v131, v[138:139], off
	global_load_ushort v113, v[138:139], off offset:1024
	global_load_ushort v112, v[138:139], off offset:2048
	global_load_ushort v111, v[138:139], off offset:3072
	global_load_ushort v110, v[138:139], off offset:32
	global_load_ushort v109, v[138:139], off offset:1056
	global_load_ushort v108, v[138:139], off offset:2080
	global_load_ushort v107, v[138:139], off offset:3104
	global_load_ushort v106, v[80:81], off
	global_load_ushort v105, v[80:81], off offset:1024
	global_load_ushort v102, v[80:81], off offset:2048
	global_load_ushort v91, v[80:81], off offset:3072
	global_load_ushort v90, v[78:79], off offset:32
	global_load_ushort v89, v[82:83], off offset:32
	global_load_ushort v88, v[84:85], off offset:32
	s_nop 0
	global_load_ushort v87, v[86:87], off offset:32
	v_lshl_add_u64 v[78:79], v[138:139], 0, s[0:1]
	s_mov_b32 s0, 0x8000
	v_add_co_u32_e32 v80, vcc, s0, v138
	s_mov_b64 s[0:1], 0x8400
	v_lshl_add_u64 v[140:141], v[138:139], 0, s[0:1]
	s_mov_b64 s[0:1], 0x8800
	v_lshl_add_u64 v[142:143], v[138:139], 0, s[0:1]
	s_mov_b64 s[0:1], 0x8c00
	v_addc_co_u32_e32 v81, vcc, 0, v139, vcc
	v_lshl_add_u64 v[144:145], v[138:139], 0, s[0:1]
	v_readlane_b32 s0, v194, 37
	global_load_ushort v86, v[80:81], off
	global_load_ushort v85, v[80:81], off offset:1024
	global_load_ushort v84, v[80:81], off offset:2048
	global_load_ushort v83, v[80:81], off offset:3072
	global_load_ushort v82, v[78:79], off offset:32
	s_nop 0
	global_load_ushort v81, v[140:141], off offset:32
	global_load_ushort v80, v[142:143], off offset:32
	global_load_ushort v79, v[144:145], off offset:32
	v_readlane_b32 s1, v194, 38
	v_lshl_or_b32 v140, v137, 10, v135
	v_ashrrev_i32_e32 v141, 31, v140
	v_lshl_add_u64 v[76:77], s[0:1], 0, v[76:77]
	v_lshl_add_u64 v[140:141], v[140:141], 2, v[76:77]
	global_load_ushort v150, v[42:43], off
	global_load_dword v151, v[140:141], off
	global_load_ushort v152, v[42:43], off offset:512
	s_mov_b64 s[0:1], 0xc000
	v_lshl_add_u64 v[142:143], v[138:139], 0, s[0:1]
; DEVINL u16 f2bf(float f) { return (u16)((__float_as_uint(f) + 0x8000u) >> 16); }
; DEVINL float bf2f(u16 h) { return __uint_as_float(((unsigned)h) << 16); }
; DEVINL void gla_passC(const Params& p, char* smem, int item) {
;     ...
;   for (int i = 0; i < 16; ++i) {
;     const int t = 16 * w + i;
;     qraw[i] = qk[(size_t)(ci.r0 + t) * 512 + ci.h * 64 + lane];
;     kraw16[i] = qk[(size_t)(ci.r0 + t) * 512 + 256 + ci.h * 64 + lane];
;   }
;   bf16x8 bvv[2][2], bss[2][2];
; #pragma unroll
;   for (int ks = 0; ks < 2; ++ks) {
;     const int kb = ks * 32 + 8 * (lane >> 4);
; #pragma unroll
;     for (int nf = 0; nf < 2; ++nf) {
;       const int dv = 32 * w + nf * 16 + (lane & 15);
;       bvv[ks][nf] = *(const bf16x8*)(vT + (size_t)(ci.h * 128 + dv) * LDT + ci.r0 + kb);
;       bss[ks][nf] = *(const bf16x8*)(SpT + dv * 64 + kb);
;     }
;   }
;   u16 graw[4][2][4];
; #pragma unroll
;   for (int mf = 0; mf < 4; ++mf) {
;     const int t0 = mf * 16 + (lane >> 4) * 4;
; #pragma unroll
;     for (int nf = 0; nf < 2; ++nf)
; #pragma unroll
;       for (int j = 0; j < 4; ++j)
;         graw[mf][nf][j] = gbuf[(size_t)(ci.r0 + t0 + j) * 512 + ci.h * 128 + 32 * w + nf * 16 + (lane & 15)];
;   }
;   float bcum[16];
;   {
;     const float* bc = (const float*)(p.ws + OFF_BCUM) + (size_t)item * 4096;
; #pragma unroll
;     for (int i = 0; i < 16; ++i) bcum[i] = bc[(16 * w + i) * 64 + lane];
;   }
;   __syncthreads();
;   u16* Qd = (u16*)(smem + G_QD); u16* Ki = (u16*)(smem + G_KI); u16* Att = (u16*)(smem + G_ATT);
;   float* red = (float*)(smem + G_RED);
; #pragma unroll
;   for (int i = 0; i < 16; ++i) {
;     const int t = 16 * w + i;
;     const float qv = (t < ci.T) ? bf2f(qraw[i]) : 0.f, kv = (t < ci.T) ? bf2f(kraw16[i]) : 0.f;
;     const float bt = bcum[i];
;     Qd[t * 72 + lane] = f2bf(qv * __expf(bt));
;     Ki[t * 72 + lane] = f2bf(kv * __expf(-bt));
;   }
	s_mov_b32 s0, 0xc000
	v_add_co_u32_e32 v144, vcc, s0, v138
	s_mov_b64 s[0:1], 0xc400
	v_lshl_add_u64 v[146:147], v[138:139], 0, s[0:1]
	s_mov_b64 s[0:1], 0xc800
	v_lshl_add_u64 v[148:149], v[138:139], 0, s[0:1]
	s_mov_b64 s[0:1], 0xcc00
	v_addc_co_u32_e32 v145, vcc, 0, v139, vcc
	v_lshl_add_u64 v[138:139], v[138:139], 0, s[0:1]
	global_load_ushort v78, v[144:145], off
	global_load_ushort v77, v[144:145], off offset:1024
	global_load_ushort v76, v[144:145], off offset:2048
	global_load_ushort v75, v[144:145], off offset:3072
	global_load_ushort v49, v[142:143], off offset:32
	global_load_ushort v47, v[146:147], off offset:32
	global_load_ushort v45, v[148:149], off offset:32
	global_load_ushort v1, v[138:139], off offset:32
	s_nop 0
	global_load_ushort v139, v[42:43], off offset:1024
	global_load_dword v144, v[140:141], off offset:256
	global_load_dword v145, v[140:141], off offset:512
	global_load_dword v146, v[140:141], off offset:768
	global_load_ushort v147, v[42:43], off offset:1536
	global_load_dword v148, v[140:141], off offset:1024
	global_load_dword v149, v[140:141], off offset:1280
	global_load_dword v153, v[140:141], off offset:1536
	global_load_dword v154, v[140:141], off offset:1792
	global_load_dword v155, v[140:141], off offset:2048
	global_load_dword v156, v[140:141], off offset:2304
	global_load_dword v157, v[140:141], off offset:2560
	global_load_dword v138, v[140:141], off offset:2816
	global_load_dword v136, v[140:141], off offset:3072
	global_load_dword v134, v[140:141], off offset:3328
	global_load_dword v39, v[140:141], off offset:3584
	global_load_dword v37, v[140:141], off offset:3840
	global_load_ushort v158, v[42:43], off offset:2048
	global_load_ushort v159, v[42:43], off offset:2560
	global_load_ushort v160, v[42:43], off offset:3072
	global_load_ushort v161, v[42:43], off offset:3584
	s_movk_i32 s0, 0x1000
	v_add_co_u32_e32 v140, vcc, s0, v42
	s_movk_i32 s0, 0x2000
	s_nop 0
	v_addc_co_u32_e32 v141, vcc, 0, v43, vcc
	v_add_co_u32_e32 v142, vcc, s0, v42
	s_movk_i32 s0, 0x3000
	s_nop 0
	v_addc_co_u32_e32 v143, vcc, 0, v43, vcc
	global_load_ushort v162, v[142:143], off offset:-4096
	s_nop 0
	global_load_ushort v66, v[66:67], off offset:512
	s_nop 0
	global_load_ushort v67, v[140:141], off offset:1024
	s_nop 0
	global_load_ushort v68, v[68:69], off offset:512
	s_nop 0
	global_load_ushort v69, v[140:141], off offset:2048
	s_nop 0
	global_load_ushort v70, v[70:71], off offset:512
	s_nop 0
	global_load_ushort v71, v[140:141], off offset:3072
	s_nop 0
	global_load_ushort v72, v[72:73], off offset:512
	s_nop 0
	global_load_ushort v73, v[142:143], off
	s_nop 0
	global_load_ushort v64, v[64:65], off offset:512
	s_nop 0
	global_load_ushort v65, v[142:143], off offset:1024
	s_nop 0
	global_load_ushort v62, v[62:63], off offset:512
	s_nop 0
	global_load_ushort v63, v[142:143], off offset:2048
	s_nop 0
	global_load_ushort v60, v[60:61], off offset:512
	s_nop 0
	global_load_ushort v61, v[142:143], off offset:3072
	s_nop 0
	global_load_ushort v58, v[58:59], off offset:512
	v_add_co_u32_e32 v42, vcc, s0, v42
	s_movk_i32 s0, 0x480
	s_nop 0
	v_addc_co_u32_e32 v43, vcc, 0, v43, vcc
	global_load_ushort v59, v[42:43], off
	s_nop 0
	global_load_ushort v56, v[56:57], off offset:512
	s_nop 0
	global_load_ushort v57, v[42:43], off offset:1024
	s_nop 0
	global_load_ushort v54, v[54:55], off offset:512
	s_nop 0
	global_load_ushort v55, v[42:43], off offset:2048
	s_nop 0
	global_load_ushort v52, v[52:53], off offset:512
	s_nop 0
	global_load_ushort v42, v[42:43], off offset:3072
	s_nop 0
	global_load_ushort v40, v[40:41], off offset:512
	v_cmp_lt_i32_e32 vcc, v51, v3
	s_waitcnt vmcnt(63) expcnt(7) lgkmcnt(15)
	s_barrier
	s_movk_i32 s34, 0x90
	s_waitcnt vmcnt(55)
	v_lshlrev_b32_e32 v41, 16, v150
	s_waitcnt vmcnt(54)
	v_mul_f32_e32 v43, 0x3fb8aa3b, v151
	v_exp_f32_e32 v43, v43
	v_cndmask_b32_e32 v41, 0, v41, vcc
	s_waitcnt vmcnt(53)
	v_lshlrev_b32_e32 v53, 16, v152
	v_cndmask_b32_e32 v53, 0, v53, vcc
	v_mul_f32_e32 v41, v41, v43
	v_mul_lo_u32 v43, v137, s0
	v_mul_f32_e32 v137, 0xbfb8aa3b, v151
	v_exp_f32_e32 v137, v137
	v_or_b32_e32 v43, v43, v135
	v_add_u32_e32 v41, 0x8000, v41
	v_lshlrev_b32_e32 v43, 1, v43
	ds_write_b16_d16_hi v43, v41 offset:22016
	v_mul_f32_e32 v41, v53, v137
	s_waitcnt vmcnt(43)
	v_mul_f32_e32 v53, 0x3fb8aa3b, v144
	v_add_u32_e32 v41, 0x8000, v41
	v_exp_f32_e32 v53, v53
	ds_write_b16_d16_hi v43, v41 offset:31232
	v_or_b32_e32 v41, 1, v51
	v_cmp_lt_i32_e32 vcc, v41, v3
	v_lshlrev_b32_e32 v43, 16, v139
	s_movk_i32 s0, 0x48
	v_cndmask_b32_e32 v43, 0, v43, vcc
	v_mul_f32_e32 v43, v43, v53
	v_mul_f32_e32 v53, 0xbfb8aa3b, v144
	v_exp_f32_e32 v53, v53
	s_waitcnt vmcnt(40)
	v_lshlrev_b32_e32 v137, 16, v147
	v_mul_lo_u32 v41, v41, s0
	v_cndmask_b32_e32 v137, 0, v137, vcc
	v_add_u32_e32 v43, 0x8000, v43
	v_add_lshl_u32 v41, v41, v135, 1
	ds_write_b16_d16_hi v41, v43 offset:22016
	v_mul_f32_e32 v43, v137, v53
	v_mul_f32_e32 v135, 0x3fb8aa3b, v145
	v_add_u32_e32 v43, 0x8000, v43
	v_exp_f32_e32 v135, v135
	ds_write_b16_d16_hi v41, v43 offset:31232
	v_or_b32_e32 v43, 2, v51
	v_mul_f32_e32 v137, 0xbfb8aa3b, v145
	v_cmp_lt_i32_e32 vcc, v43, v3
	s_waitcnt vmcnt(27)
	v_lshlrev_b32_e32 v43, 16, v158
	v_exp_f32_e32 v137, v137
	v_cndmask_b32_e32 v43, 0, v43, vcc
	s_waitcnt vmcnt(26)
	v_lshlrev_b32_e32 v53, 16, v159
	v_mul_f32_e32 v43, v43, v135
	v_cndmask_b32_e32 v53, 0, v53, vcc
	v_add_u32_e32 v43, 0x8000, v43
	ds_write_b16_d16_hi v41, v43 offset:22160
	v_mul_f32_e32 v43, v53, v137
	v_mul_f32_e32 v135, 0x3fb8aa3b, v146
	v_add_u32_e32 v43, 0x8000, v43
	v_exp_f32_e32 v135, v135
	ds_write_b16_d16_hi v41, v43 offset:31376
	v_or_b32_e32 v43, 3, v51
	v_mul_f32_e32 v137, 0xbfb8aa3b, v146
	v_cmp_lt_i32_e32 vcc, v43, v3
	s_waitcnt vmcnt(25)
; DEVINL u16 f2bf(float f) { return (u16)((__float_as_uint(f) + 0x8000u) >> 16); }
; DEVINL float bf2f(u16 h) { return __uint_as_float(((unsigned)h) << 16); }
; DEVINL void gla_passC(const Params& p, char* smem, int item) {
;     ...
;   for (int i = 0; i < 16; ++i) {
;     const int t = 16 * w + i;
;     const float qv = (t < ci.T) ? bf2f(qraw[i]) : 0.f, kv = (t < ci.T) ? bf2f(kraw16[i]) : 0.f;
;     const float bt = bcum[i];
;     Qd[t * 72 + lane] = f2bf(qv * __expf(bt));
;     Ki[t * 72 + lane] = f2bf(kv * __expf(-bt));
;   }
	v_lshlrev_b32_e32 v43, 16, v160
	v_exp_f32_e32 v137, v137
	v_cndmask_b32_e32 v43, 0, v43, vcc
	s_waitcnt vmcnt(24)
	v_lshlrev_b32_e32 v53, 16, v161
	v_mul_f32_e32 v43, v43, v135
	v_cndmask_b32_e32 v53, 0, v53, vcc
	v_add_u32_e32 v43, 0x8000, v43
	ds_write_b16_d16_hi v41, v43 offset:22304
	v_mul_f32_e32 v43, v53, v137
	s_waitcnt vmcnt(22)
	v_lshlrev_b32_e32 v53, 16, v66
	v_mul_f32_e32 v66, 0x3fb8aa3b, v148
	v_add_u32_e32 v43, 0x8000, v43
	v_exp_f32_e32 v66, v66
	ds_write_b16_d16_hi v41, v43 offset:31520
	v_or_b32_e32 v43, 4, v51
	v_mul_f32_e32 v135, 0xbfb8aa3b, v148
	v_cmp_lt_i32_e32 vcc, v43, v3
	v_lshlrev_b32_e32 v43, 16, v162
	v_exp_f32_e32 v135, v135
	v_cndmask_b32_e32 v43, 0, v43, vcc
	v_mul_f32_e32 v43, v43, v66
	v_cndmask_b32_e32 v53, 0, v53, vcc
	v_add_u32_e32 v43, 0x8000, v43
	ds_write_b16_d16_hi v41, v43 offset:22448
	v_mul_f32_e32 v43, v53, v135
	v_add_u32_e32 v43, 0x8000, v43
	v_mul_f32_e32 v66, 0x3fb8aa3b, v149
	ds_write_b16_d16_hi v41, v43 offset:31664
	v_or_b32_e32 v43, 5, v51
	v_exp_f32_e32 v66, v66
	v_cmp_lt_i32_e32 vcc, v43, v3
	s_waitcnt vmcnt(21)
	v_lshlrev_b32_e32 v43, 16, v67
	v_mul_f32_e32 v67, 0xbfb8aa3b, v149
	v_exp_f32_e32 v67, v67
	v_cndmask_b32_e32 v43, 0, v43, vcc
	s_waitcnt vmcnt(20)
	v_lshlrev_b32_e32 v53, 16, v68
	v_mul_f32_e32 v43, v43, v66
	v_cndmask_b32_e32 v53, 0, v53, vcc
	v_add_u32_e32 v43, 0x8000, v43
	ds_write_b16_d16_hi v41, v43 offset:22592
	v_mul_f32_e32 v43, v53, v67
	v_mul_f32_e32 v66, 0x3fb8aa3b, v153
	v_add_u32_e32 v43, 0x8000, v43
	v_exp_f32_e32 v66, v66
	ds_write_b16_d16_hi v41, v43 offset:31808
	v_or_b32_e32 v43, 6, v51
	v_mul_f32_e32 v67, 0xbfb8aa3b, v153
	v_cmp_lt_i32_e32 vcc, v43, v3
	s_waitcnt vmcnt(19)
	v_lshlrev_b32_e32 v43, 16, v69
	v_exp_f32_e32 v67, v67
	v_cndmask_b32_e32 v43, 0, v43, vcc
	s_waitcnt vmcnt(18)
	v_lshlrev_b32_e32 v53, 16, v70
	v_mul_f32_e32 v43, v43, v66
	v_cndmask_b32_e32 v53, 0, v53, vcc
	v_add_u32_e32 v43, 0x8000, v43
	ds_write_b16_d16_hi v41, v43 offset:22736
	v_mul_f32_e32 v43, v53, v67
	v_mul_f32_e32 v66, 0x3fb8aa3b, v154
	v_add_u32_e32 v43, 0x8000, v43
	v_exp_f32_e32 v66, v66
	ds_write_b16_d16_hi v41, v43 offset:31952
	v_or_b32_e32 v43, 7, v51
	v_mul_f32_e32 v67, 0xbfb8aa3b, v154
	v_cmp_lt_i32_e32 vcc, v43, v3
	s_waitcnt vmcnt(17)
	v_lshlrev_b32_e32 v43, 16, v71
	v_exp_f32_e32 v67, v67
	v_cndmask_b32_e32 v43, 0, v43, vcc
	s_waitcnt vmcnt(16)
	v_lshlrev_b32_e32 v53, 16, v72
	v_mul_f32_e32 v43, v43, v66
	v_cndmask_b32_e32 v53, 0, v53, vcc
	v_add_u32_e32 v43, 0x8000, v43
	ds_write_b16_d16_hi v41, v43 offset:22880
	v_mul_f32_e32 v43, v53, v67
	s_waitcnt vmcnt(14)
	v_lshlrev_b32_e32 v53, 16, v64
	v_mul_f32_e32 v64, 0x3fb8aa3b, v155
	v_add_u32_e32 v43, 0x8000, v43
	v_exp_f32_e32 v64, v64
	ds_write_b16_d16_hi v41, v43 offset:32096
	v_or_b32_e32 v43, 8, v51
	v_mul_f32_e32 v66, 0xbfb8aa3b, v155
	v_cmp_lt_i32_e32 vcc, v43, v3
	v_lshlrev_b32_e32 v43, 16, v73
	v_exp_f32_e32 v66, v66
	v_cndmask_b32_e32 v43, 0, v43, vcc
	v_mul_f32_e32 v43, v43, v64
	v_cndmask_b32_e32 v53, 0, v53, vcc
	v_add_u32_e32 v43, 0x8000, v43
	ds_write_b16_d16_hi v41, v43 offset:23024
	v_mul_f32_e32 v43, v53, v66
	s_waitcnt vmcnt(12)
	v_lshlrev_b32_e32 v53, 16, v62
	v_mul_f32_e32 v62, 0x3fb8aa3b, v156
	v_add_u32_e32 v43, 0x8000, v43
	v_exp_f32_e32 v62, v62
	ds_write_b16_d16_hi v41, v43 offset:32240
	v_or_b32_e32 v43, 9, v51
	v_mul_f32_e32 v64, 0xbfb8aa3b, v156
	v_cmp_lt_i32_e32 vcc, v43, v3
	v_lshlrev_b32_e32 v43, 16, v65
	v_exp_f32_e32 v64, v64
	v_cndmask_b32_e32 v43, 0, v43, vcc
	v_mul_f32_e32 v43, v43, v62
	v_cndmask_b32_e32 v53, 0, v53, vcc
	v_add_u32_e32 v43, 0x8000, v43
	ds_write_b16_d16_hi v41, v43 offset:23168
	v_mul_f32_e32 v43, v53, v64
	s_waitcnt vmcnt(10)
	v_lshlrev_b32_e32 v53, 16, v60
	v_mul_f32_e32 v60, 0x3fb8aa3b, v157
	v_add_u32_e32 v43, 0x8000, v43
	v_exp_f32_e32 v60, v60
	ds_write_b16_d16_hi v41, v43 offset:32384
	v_or_b32_e32 v43, 10, v51
	v_mul_f32_e32 v62, 0xbfb8aa3b, v157
	v_cmp_lt_i32_e32 vcc, v43, v3
	v_lshlrev_b32_e32 v43, 16, v63
	v_exp_f32_e32 v62, v62
	v_cndmask_b32_e32 v43, 0, v43, vcc
	v_mul_f32_e32 v43, v43, v60
	v_cndmask_b32_e32 v53, 0, v53, vcc
	v_add_u32_e32 v43, 0x8000, v43
	ds_write_b16_d16_hi v41, v43 offset:23312
	v_mul_f32_e32 v43, v53, v62
	s_waitcnt vmcnt(8)
	v_lshlrev_b32_e32 v53, 16, v58
	v_mul_f32_e32 v58, 0x3fb8aa3b, v138
	v_add_u32_e32 v43, 0x8000, v43
	v_exp_f32_e32 v58, v58
	ds_write_b16_d16_hi v41, v43 offset:32528
	v_or_b32_e32 v43, 11, v51
	v_mul_f32_e32 v60, 0xbfb8aa3b, v138
	v_cmp_lt_i32_e32 vcc, v43, v3
	v_lshlrev_b32_e32 v43, 16, v61
	v_exp_f32_e32 v60, v60
	v_cndmask_b32_e32 v43, 0, v43, vcc
	v_mul_f32_e32 v43, v43, v58
	v_cndmask_b32_e32 v53, 0, v53, vcc
	v_add_u32_e32 v43, 0x8000, v43
	ds_write_b16_d16_hi v41, v43 offset:23456
	v_mul_f32_e32 v43, v53, v60
	s_waitcnt vmcnt(6)
	v_lshlrev_b32_e32 v53, 16, v56
	v_mul_f32_e32 v56, 0x3fb8aa3b, v136
	v_add_u32_e32 v43, 0x8000, v43
	v_exp_f32_e32 v56, v56
	ds_write_b16_d16_hi v41, v43 offset:32672
	v_or_b32_e32 v43, 12, v51
	v_mul_f32_e32 v58, 0xbfb8aa3b, v136
	v_cmp_lt_i32_e32 vcc, v43, v3
	v_lshlrev_b32_e32 v43, 16, v59
	v_exp_f32_e32 v58, v58
	v_cndmask_b32_e32 v43, 0, v43, vcc
	v_mul_f32_e32 v43, v43, v56
	v_cndmask_b32_e32 v53, 0, v53, vcc
	v_add_u32_e32 v43, 0x8000, v43
	ds_write_b16_d16_hi v41, v43 offset:23600
	v_mul_f32_e32 v43, v53, v58
	s_waitcnt vmcnt(4)
; DEVINL u16 f2bf(float f) { return (u16)((__float_as_uint(f) + 0x8000u) >> 16); }
; DEVINL float bf2f(u16 h) { return __uint_as_float(((unsigned)h) << 16); }
; DEVINL f32x4 mfma16(bf16x8 a, bf16x8 b, f32x4 c) { return __builtin_amdgcn_mfma_f32_16x16x32_bf16(a, b, c, 0, 0, 0); }
; DEVINL void gla_passC(const Params& p, char* smem, int item) {
;     ...
;   for (int i = 0; i < 16; ++i) {
;     const int t = 16 * w + i;
;     const float qv = (t < ci.T) ? bf2f(qraw[i]) : 0.f, kv = (t < ci.T) ? bf2f(kraw16[i]) : 0.f;
;     const float bt = bcum[i];
;     Qd[t * 72 + lane] = f2bf(qv * __expf(bt));
;     Ki[t * 72 + lane] = f2bf(kv * __expf(-bt));
;   }
;   __syncthreads();
;   {
;     f32x4 at[4];
; #pragma unroll
;     for (int nf = 0; nf < 4; ++nf) at[nf] = f32x4{0, 0, 0, 0};
; #pragma unroll
;     for (int ks = 0; ks < 2; ++ks) {
;       bf16x8 a = *(const bf16x8*)(Qd + (16 * w + (lane & 15)) * 72 + ks * 32 + 8 * (lane >> 4));
; #pragma unroll
;       for (int nf = 0; nf < 4; ++nf) {
;         bf16x8 b = *(const bf16x8*)(Ki + (nf * 16 + (lane & 15)) * 72 + ks * 32 + 8 * (lane >> 4));
;         at[nf] = mfma16(a, b, at[nf]);
;       }
;     }
; #pragma unroll
;     for (int nf = 0; nf < 4; ++nf)
; #pragma unroll
;       for (int j = 0; j < 4; ++j) {
;         int t = 16 * w + (lane >> 4) * 4 + j, s = nf * 16 + (lane & 15);
;         Att[t * 72 + s] = f2bf((s <= t) ? at[nf][j] : 0.f);
;       }
;   }
;   __syncthreads();
	v_lshlrev_b32_e32 v53, 16, v54
	v_mul_f32_e32 v54, 0x3fb8aa3b, v134
	v_add_u32_e32 v43, 0x8000, v43
	v_exp_f32_e32 v54, v54
	ds_write_b16_d16_hi v41, v43 offset:32816
	v_or_b32_e32 v43, 13, v51
	v_mul_f32_e32 v56, 0xbfb8aa3b, v134
	v_cmp_lt_i32_e32 vcc, v43, v3
	v_lshlrev_b32_e32 v43, 16, v57
	v_exp_f32_e32 v56, v56
	v_cndmask_b32_e32 v43, 0, v43, vcc
	v_mul_f32_e32 v43, v43, v54
	v_cndmask_b32_e32 v53, 0, v53, vcc
	v_add_u32_e32 v43, 0x8000, v43
	ds_write_b16_d16_hi v41, v43 offset:23744
	v_mul_f32_e32 v43, v53, v56
	v_mul_f32_e32 v53, 0x3fb8aa3b, v39
	v_mul_f32_e32 v39, 0xbfb8aa3b, v39
	v_add_u32_e32 v43, 0x8000, v43
	v_exp_f32_e32 v39, v39
	ds_write_b16_d16_hi v41, v43 offset:32960
	v_or_b32_e32 v43, 14, v51
	v_cmp_lt_i32_e32 vcc, v43, v3
	s_waitcnt vmcnt(2)
	v_lshlrev_b32_e32 v52, 16, v52
	v_lshlrev_b32_e32 v43, 16, v55
	v_cndmask_b32_e32 v52, 0, v52, vcc
	v_mul_f32_e32 v39, v52, v39
	v_add_u32_e32 v39, 0x8000, v39
	ds_write_b16_d16_hi v41, v39 offset:33104
	v_or_b32_e32 v39, 15, v51
	v_cndmask_b32_e32 v43, 0, v43, vcc
	v_cmp_lt_i32_e32 vcc, v39, v3
	s_waitcnt vmcnt(1)
	v_lshlrev_b32_e32 v39, 16, v42
	v_mul_f32_e32 v42, 0x3fb8aa3b, v37
	v_mul_f32_e32 v37, 0xbfb8aa3b, v37
	v_exp_f32_e32 v37, v37
	v_exp_f32_e32 v42, v42
	v_exp_f32_e32 v53, v53
	s_waitcnt vmcnt(0)
	v_lshlrev_b32_e32 v40, 16, v40
	v_cndmask_b32_e32 v40, 0, v40, vcc
	v_cndmask_b32_e32 v39, 0, v39, vcc
	v_mul_f32_e32 v37, v40, v37
	v_mul_f32_e32 v39, v39, v42
	v_add_u32_e32 v37, 0x8000, v37
	v_mul_f32_e32 v43, v43, v53
	v_add_u32_e32 v39, 0x8000, v39
	ds_write_b16_d16_hi v41, v37 offset:33248
	v_or_b32_e32 v37, v51, v133
	v_add_u32_e32 v43, 0x8000, v43
	v_mad_u64_u32 v[68:69], s[0:1], v37, s34, v[38:39]
	ds_write_b16_d16_hi v41, v43 offset:23888
	ds_write_b16_d16_hi v41, v39 offset:24032
	s_waitcnt lgkmcnt(0)
	s_barrier
	ds_read_b128 v[40:43], v68 offset:22016
	v_mul_u32_u24_e32 v37, 0x48, v133
	v_lshl_add_u32 v72, v37, 1, v38
	ds_read_b128 v[52:55], v72 offset:31232
	ds_read_b128 v[56:59], v72 offset:33536
	ds_read_b128 v[60:63], v72 offset:35840
	ds_read_b128 v[64:67], v72 offset:38144
	ds_read_b128 v[68:71], v68 offset:22080
	s_waitcnt lgkmcnt(4)
	v_mfma_f32_16x16x32_bf16 v[52:55], v[40:43], v[52:55], 0
	v_or_b32_e32 v51, v51, v74
	v_cmp_le_i32_e32 vcc, v133, v51
	v_or_b32_e32 v37, 16, v133
	s_waitcnt lgkmcnt(3)
	v_mfma_f32_16x16x32_bf16 v[56:59], v[40:43], v[56:59], 0
	s_waitcnt lgkmcnt(2)
	v_mfma_f32_16x16x32_bf16 v[60:63], v[40:43], v[60:63], 0
	s_waitcnt lgkmcnt(1)
	v_mfma_f32_16x16x32_bf16 v[38:41], v[40:43], v[64:67], 0
	ds_read_b128 v[64:67], v72 offset:31296
	v_or_b32_e32 v42, 32, v133
	v_or_b32_e32 v43, 48, v133
	s_waitcnt lgkmcnt(0)
	v_mfma_f32_16x16x32_bf16 v[52:55], v[68:71], v[64:67], v[52:55]
	ds_read_b128 v[64:67], v72 offset:33600
	s_waitcnt lgkmcnt(0)
	v_mfma_f32_16x16x32_bf16 v[56:59], v[68:71], v[64:67], v[56:59]
	ds_read_b128 v[64:67], v72 offset:35904
	ds_read_b128 v[134:137], v72 offset:38208
	s_nop 2
	v_add_u32_e32 v52, 0x8000, v52
	v_lshrrev_b32_e32 v52, 16, v52
	s_waitcnt lgkmcnt(1)
	v_mfma_f32_16x16x32_bf16 v[60:63], v[68:71], v[64:67], v[60:63]
	v_mul_lo_u32 v64, v51, s34
	v_cndmask_b32_e32 v52, 0, v52, vcc
	v_or_b32_e32 v36, v64, v36
	ds_write_b16 v36, v52 offset:40448
	v_or_b32_e32 v52, 1, v51
	v_add_u32_e32 v53, 0x8000, v53
	v_lshrrev_b32_e32 v53, 16, v53
	v_cmp_le_i32_e32 vcc, v133, v52
	v_add_u32_e32 v54, 0x8000, v54
	v_lshrrev_b32_e32 v54, 16, v54
	v_cndmask_b32_e32 v53, 0, v53, vcc
	ds_write_b16 v36, v53 offset:40592
	v_or_b32_e32 v53, 2, v51
	v_cmp_le_i32_e32 vcc, v133, v53
	v_add_u32_e32 v55, 0x8000, v55
	v_lshrrev_b32_e32 v55, 16, v55
	v_cndmask_b32_e32 v54, 0, v54, vcc
	ds_write_b16 v36, v54 offset:40736
	v_or_b32_e32 v54, 3, v51
	v_cmp_le_i32_e32 vcc, v133, v54
	s_waitcnt lgkmcnt(3)
	v_mfma_f32_16x16x32_bf16 v[38:41], v[68:71], v[134:137], v[38:41]
	v_cmp_lt_u32_e64 s[34:35], v74, v3
	v_cndmask_b32_e32 v55, 0, v55, vcc
	ds_write_b16 v36, v55 offset:40880
	v_add_u32_e32 v55, 0x8000, v56
	v_lshrrev_b32_e32 v55, 16, v55
	v_cmp_le_i32_e32 vcc, v37, v51
	s_nop 1
	v_cndmask_b32_e32 v55, 0, v55, vcc
	ds_write_b16 v36, v55 offset:40480
	v_add_u32_e32 v55, 0x8000, v57
	v_lshrrev_b32_e32 v55, 16, v55
	v_cmp_le_i32_e32 vcc, v37, v52
	s_nop 1
	v_cndmask_b32_e32 v55, 0, v55, vcc
	ds_write_b16 v36, v55 offset:40624
	v_add_u32_e32 v55, 0x8000, v58
	v_lshrrev_b32_e32 v55, 16, v55
	v_cmp_le_i32_e32 vcc, v37, v53
	s_nop 1
	v_cndmask_b32_e32 v55, 0, v55, vcc
	ds_write_b16 v36, v55 offset:40768
	v_add_u32_e32 v55, 0x8000, v59
	v_lshrrev_b32_e32 v55, 16, v55
	v_cmp_le_i32_e32 vcc, v37, v54
	s_nop 1
	v_cndmask_b32_e32 v37, 0, v55, vcc
	ds_write_b16 v36, v37 offset:40912
	v_add_u32_e32 v37, 0x8000, v60
	v_lshrrev_b32_e32 v37, 16, v37
	v_cmp_le_i32_e32 vcc, v42, v51
	s_nop 1
	v_cndmask_b32_e32 v37, 0, v37, vcc
	ds_write_b16 v36, v37 offset:40512
	v_add_u32_e32 v37, 0x8000, v61
	v_lshrrev_b32_e32 v37, 16, v37
	v_cmp_le_i32_e32 vcc, v42, v52
	s_nop 1
	v_cndmask_b32_e32 v37, 0, v37, vcc
	ds_write_b16 v36, v37 offset:40656
	v_add_u32_e32 v37, 0x8000, v62
	v_lshrrev_b32_e32 v37, 16, v37
	v_cmp_le_i32_e32 vcc, v42, v53
	s_nop 1
	v_cndmask_b32_e32 v37, 0, v37, vcc
	ds_write_b16 v36, v37 offset:40800
	v_add_u32_e32 v37, 0x8000, v63
	v_lshrrev_b32_e32 v37, 16, v37
	v_cmp_le_i32_e32 vcc, v42, v54
	s_nop 1
	v_cndmask_b32_e32 v37, 0, v37, vcc
	ds_write_b16 v36, v37 offset:40944
	v_add_u32_e32 v37, 0x8000, v38
	v_lshrrev_b32_e32 v37, 16, v37
	v_cmp_le_i32_e32 vcc, v43, v51
	v_ashrrev_i32_e32 v51, 31, v50
	s_nop 0
	v_cndmask_b32_e32 v37, 0, v37, vcc
	ds_write_b16 v36, v37 offset:40544
	v_add_u32_e32 v37, 0x8000, v39
	v_lshrrev_b32_e32 v37, 16, v37
	v_cmp_le_i32_e32 vcc, v43, v52
	s_nop 1
	v_cndmask_b32_e32 v37, 0, v37, vcc
	ds_write_b16 v36, v37 offset:40688
	v_add_u32_e32 v37, 0x8000, v40
	v_lshrrev_b32_e32 v37, 16, v37
	v_cmp_le_i32_e32 vcc, v43, v53
	s_nop 1
	v_cndmask_b32_e32 v37, 0, v37, vcc
	ds_write_b16 v36, v37 offset:40832
	v_add_u32_e32 v37, 0x8000, v41
	v_lshrrev_b32_e32 v37, 16, v37
	v_cmp_le_i32_e32 vcc, v43, v54
	s_nop 1
	v_cndmask_b32_e32 v37, 0, v37, vcc
	ds_write_b16 v36, v37 offset:40976
	s_waitcnt lgkmcnt(0)
	s_barrier
; DEVINL f32x4 mfma16(bf16x8 a, bf16x8 b, f32x4 c) { return __builtin_amdgcn_mfma_f32_16x16x32_bf16(a, b, c, 0, 0, 0); }
; DEVINL void gla_passC(const Params& p, char* smem, int item) {
;     ...
;   f32x4 o[4][2];
; #pragma unroll
;   for (int a = 0; a < 4; ++a) { o[a][0] = f32x4{0, 0, 0, 0}; o[a][1] = f32x4{0, 0, 0, 0}; }
; #pragma unroll
;   for (int ks = 0; ks < 2; ++ks) {
;     const int kb = ks * 32 + 8 * (lane >> 4);
;     bf16x8 bv[2], bs[2];
; #pragma unroll
;     for (int nf = 0; nf < 2; ++nf) { bv[nf] = bvv[ks][nf]; bs[nf] = bss[ks][nf]; }
; #pragma unroll
;     for (int mf = 0; mf < 4; ++mf) {
;       bf16x8 aa = *(const bf16x8*)(Att + (mf * 16 + (lane & 15)) * 72 + kb);
;       bf16x8 aq = *(const bf16x8*)(Qd + (mf * 16 + (lane & 15)) * 72 + kb);
; #pragma unroll
;       for (int nf = 0; nf < 2; ++nf) {
;         o[mf][nf] = mfma16(aa, bv[nf], o[mf][nf]);
;         o[mf][nf] = mfma16(aq, bs[nf], o[mf][nf]);
;       }
;     }
;   }
; #pragma unroll
;   for (int mf = 0; mf < 4; ++mf)
; #pragma unroll
;     for (int j = 0; j < 4; ++j) {
;       const float s = red16(o[mf][0][j] * o[mf][0][j] + o[mf][1][j] * o[mf][1][j]);
;       red[w * 64 + mf * 16 + (lane >> 4) * 4 + j] = s;
;     }
;   __syncthreads();
	ds_read_b128 v[36:39], v72 offset:40448
	ds_read_b128 v[52:55], v72 offset:22016
	s_waitcnt lgkmcnt(1)
	v_mfma_f32_16x16x32_bf16 v[40:43], v[36:39], v[12:15], 0
	ds_read_b128 v[60:63], v72 offset:24320
	ds_read_b128 v[68:71], v72 offset:26624
	ds_read_b128 v[134:137], v72 offset:28928
	v_mfma_f32_16x16x32_bf16 v[36:39], v[36:39], v[28:31], 0
	s_waitcnt lgkmcnt(3)
	v_mfma_f32_16x16x32_bf16 v[40:43], v[52:55], v[16:19], v[40:43]
	v_mfma_f32_16x16x32_bf16 v[36:39], v[52:55], v[32:35], v[36:39]
	ds_read_b128 v[52:55], v72 offset:42752
	s_waitcnt lgkmcnt(0)
	v_mfma_f32_16x16x32_bf16 v[56:59], v[52:55], v[12:15], 0
	v_mfma_f32_16x16x32_bf16 v[52:55], v[52:55], v[28:31], 0
	v_mfma_f32_16x16x32_bf16 v[56:59], v[60:63], v[16:19], v[56:59]
	v_mfma_f32_16x16x32_bf16 v[52:55], v[60:63], v[32:35], v[52:55]
	ds_read_b128 v[60:63], v72 offset:45056
	s_waitcnt lgkmcnt(0)
	v_mfma_f32_16x16x32_bf16 v[64:67], v[60:63], v[12:15], 0
	v_mfma_f32_16x16x32_bf16 v[60:63], v[60:63], v[28:31], 0
	v_mfma_f32_16x16x32_bf16 v[64:67], v[68:71], v[16:19], v[64:67]
	v_mfma_f32_16x16x32_bf16 v[60:63], v[68:71], v[32:35], v[60:63]
	ds_read_b128 v[68:71], v72 offset:47360
	s_waitcnt lgkmcnt(0)
	v_mfma_f32_16x16x32_bf16 v[12:15], v[68:71], v[12:15], 0
	v_mfma_f32_16x16x32_bf16 v[138:141], v[134:137], v[16:19], v[12:15]
	v_mfma_f32_16x16x32_bf16 v[12:15], v[68:71], v[28:31], 0
	ds_read_b128 v[28:31], v72 offset:22080
	v_mfma_f32_16x16x32_bf16 v[68:71], v[134:137], v[32:35], v[12:15]
	s_nop 5
	ds_read_b128 v[12:15], v72 offset:40512
	s_waitcnt lgkmcnt(0)
	v_mfma_f32_16x16x32_bf16 v[16:19], v[12:15], v[8:11], v[40:43]
	v_mfma_f32_16x16x32_bf16 v[12:15], v[12:15], v[20:23], v[36:39]
	v_mfma_f32_16x16x32_bf16 v[36:39], v[28:31], v[24:27], v[12:15]
	v_mfma_f32_16x16x32_bf16 v[40:43], v[28:31], v[4:7], v[16:19]
	s_nop 5
	ds_read_b128 v[12:15], v72 offset:42816
	ds_read_b128 v[28:31], v72 offset:24384
	s_waitcnt lgkmcnt(1)
	v_mfma_f32_16x16x32_bf16 v[16:19], v[12:15], v[8:11], v[56:59]
	s_nop 2
	ds_read_b128 v[56:59], v72 offset:28992
	v_mfma_f32_16x16x32_bf16 v[12:15], v[12:15], v[20:23], v[52:55]
	s_waitcnt lgkmcnt(1)
	v_mfma_f32_16x16x32_bf16 v[32:35], v[28:31], v[4:7], v[16:19]
	s_nop 0
	ds_read_b128 v[52:55], v72 offset:26688
	v_mfma_f32_16x16x32_bf16 v[28:31], v[28:31], v[24:27], v[12:15]
	s_nop 2
	ds_read_b128 v[12:15], v72 offset:45120
	s_waitcnt lgkmcnt(0)
	v_mfma_f32_16x16x32_bf16 v[16:19], v[12:15], v[8:11], v[64:67]
	v_mfma_f32_16x16x32_bf16 v[12:15], v[12:15], v[20:23], v[60:63]
	v_mfma_f32_16x16x32_bf16 v[16:19], v[52:55], v[4:7], v[16:19]
	v_mfma_f32_16x16x32_bf16 v[12:15], v[52:55], v[24:27], v[12:15]
	ds_read_b128 v[52:55], v72 offset:47424
	s_waitcnt lgkmcnt(0)
	v_mfma_f32_16x16x32_bf16 v[8:11], v[52:55], v[8:11], v[138:141]
	v_mfma_f32_16x16x32_bf16 v[8:11], v[56:59], v[4:7], v[8:11]
	v_mfma_f32_16x16x32_bf16 v[4:7], v[52:55], v[20:23], v[68:71]
	v_and_b32_e32 v20, 0x3fffffc0, v132
	v_lshlrev_b32_e32 v23, 2, v74
	v_lshl_or_b32 v22, v20, 2, v23
	v_mfma_f32_16x16x32_bf16 v[4:7], v[56:59], v[24:27], v[4:7]
	v_mul_f32_e64 v24, v36, v36
	v_mul_f32_e64 v25, v37, v37
	v_pk_mul_f32 v[20:21], v[38:39], v[38:39]
	v_pk_fma_f32 v[24:25], v[40:41], v[40:41], v[24:25]
	v_pk_fma_f32 v[20:21], v[42:43], v[42:43], v[20:21]
	s_nop 0
	v_mov_b32_dpp v26, v24 quad_perm:[1,0,3,2] row_mask:0xf bank_mask:0xf bound_ctrl:1
	v_mov_b32_dpp v27, v25 quad_perm:[1,0,3,2] row_mask:0xf bank_mask:0xf bound_ctrl:1
	v_pk_add_f32 v[24:25], v[24:25], v[26:27]
	s_nop 1
	v_mov_b32_dpp v26, v24 quad_perm:[2,3,0,1] row_mask:0xf bank_mask:0xf bound_ctrl:1
	v_mov_b32_dpp v27, v25 quad_perm:[2,3,0,1] row_mask:0xf bank_mask:0xf bound_ctrl:1
	v_pk_add_f32 v[24:25], v[24:25], v[26:27]
	s_nop 1
	v_mov_b32_dpp v26, v24 row_half_mirror row_mask:0xf bank_mask:0xf bound_ctrl:1
	v_mov_b32_dpp v27, v25 row_half_mirror row_mask:0xf bank_mask:0xf bound_ctrl:1
	v_pk_add_f32 v[24:25], v[24:25], v[26:27]
	s_nop 1
	v_mov_b32_dpp v26, v24 row_mirror row_mask:0xf bank_mask:0xf bound_ctrl:1
	v_mov_b32_dpp v27, v25 row_mirror row_mask:0xf bank_mask:0xf bound_ctrl:1
	v_pk_add_f32 v[24:25], v[24:25], v[26:27]
	v_mov_b32_dpp v26, v20 quad_perm:[1,0,3,2] row_mask:0xf bank_mask:0xf bound_ctrl:1
	v_mov_b32_dpp v27, v21 quad_perm:[1,0,3,2] row_mask:0xf bank_mask:0xf bound_ctrl:1
	v_pk_add_f32 v[20:21], v[20:21], v[26:27]
	s_nop 1
	v_mov_b32_dpp v26, v20 quad_perm:[2,3,0,1] row_mask:0xf bank_mask:0xf bound_ctrl:1
	v_mov_b32_dpp v27, v21 quad_perm:[2,3,0,1] row_mask:0xf bank_mask:0xf bound_ctrl:1
	v_pk_add_f32 v[20:21], v[20:21], v[26:27]
	s_nop 1
	v_mov_b32_dpp v26, v20 row_half_mirror row_mask:0xf bank_mask:0xf bound_ctrl:1
	v_mov_b32_dpp v27, v21 row_half_mirror row_mask:0xf bank_mask:0xf bound_ctrl:1
	v_pk_add_f32 v[20:21], v[20:21], v[26:27]
	s_nop 1
	v_mov_b32_dpp v26, v20 row_mirror row_mask:0xf bank_mask:0xf bound_ctrl:1
	v_mov_b32_dpp v27, v21 row_mirror row_mask:0xf bank_mask:0xf bound_ctrl:1
	v_pk_add_f32 v[26:27], v[20:21], v[26:27]
	ds_write_b128 v22, v[24:27] offset:49664
	v_pk_mul_f32 v[24:25], v[28:29], v[28:29]
	v_pk_mul_f32 v[20:21], v[30:31], v[30:31]
	v_pk_fma_f32 v[24:25], v[32:33], v[32:33], v[24:25]
	v_pk_fma_f32 v[20:21], v[34:35], v[34:35], v[20:21]
	s_nop 0
	v_mov_b32_dpp v26, v24 quad_perm:[1,0,3,2] row_mask:0xf bank_mask:0xf bound_ctrl:1
	v_mov_b32_dpp v27, v25 quad_perm:[1,0,3,2] row_mask:0xf bank_mask:0xf bound_ctrl:1
	v_pk_add_f32 v[24:25], v[24:25], v[26:27]
	s_nop 1
	v_mov_b32_dpp v26, v24 quad_perm:[2,3,0,1] row_mask:0xf bank_mask:0xf bound_ctrl:1
	v_mov_b32_dpp v27, v25 quad_perm:[2,3,0,1] row_mask:0xf bank_mask:0xf bound_ctrl:1
	v_pk_add_f32 v[24:25], v[24:25], v[26:27]
	s_nop 1
; DEVINL void gla_passC(const Params& p, char* smem, int item) {
;     ...
; #pragma unroll
;   for (int mf = 0; mf < 4; ++mf)
; #pragma unroll
;     for (int j = 0; j < 4; ++j) {
;       const float s = red16(o[mf][0][j] * o[mf][0][j] + o[mf][1][j] * o[mf][1][j]);
;       red[w * 64 + mf * 16 + (lane >> 4) * 4 + j] = s;
;     }
;   __syncthreads();
;   u16* mixin = (u16*)(p.ws + OFF_MIXIN);
;   float gn[2];
; #pragma unroll
;   for (int nf = 0; nf < 2; ++nf) gn[nf] = p.gla_norm[32 * w + nf * 16 + (lane & 15)];
; #pragma unroll
;   for (int mf = 0; mf < 4; ++mf) {
;     const int t0 = mf * 16 + (lane >> 4) * 4;
;     if (t0 < ci.T) {
	v_mov_b32_dpp v26, v24 row_half_mirror row_mask:0xf bank_mask:0xf bound_ctrl:1
	v_mov_b32_dpp v27, v25 row_half_mirror row_mask:0xf bank_mask:0xf bound_ctrl:1
	v_pk_add_f32 v[24:25], v[24:25], v[26:27]
	s_nop 1
	v_mov_b32_dpp v26, v24 row_mirror row_mask:0xf bank_mask:0xf bound_ctrl:1
	v_mov_b32_dpp v27, v25 row_mirror row_mask:0xf bank_mask:0xf bound_ctrl:1
	v_pk_add_f32 v[24:25], v[24:25], v[26:27]
	v_mov_b32_dpp v26, v20 quad_perm:[1,0,3,2] row_mask:0xf bank_mask:0xf bound_ctrl:1
	v_mov_b32_dpp v27, v21 quad_perm:[1,0,3,2] row_mask:0xf bank_mask:0xf bound_ctrl:1
	v_pk_add_f32 v[20:21], v[20:21], v[26:27]
	s_nop 1
	v_mov_b32_dpp v26, v20 quad_perm:[2,3,0,1] row_mask:0xf bank_mask:0xf bound_ctrl:1
	v_mov_b32_dpp v27, v21 quad_perm:[2,3,0,1] row_mask:0xf bank_mask:0xf bound_ctrl:1
	v_pk_add_f32 v[20:21], v[20:21], v[26:27]
	s_nop 1
	v_mov_b32_dpp v26, v20 row_half_mirror row_mask:0xf bank_mask:0xf bound_ctrl:1
	v_mov_b32_dpp v27, v21 row_half_mirror row_mask:0xf bank_mask:0xf bound_ctrl:1
	v_pk_add_f32 v[20:21], v[20:21], v[26:27]
	s_nop 1
	v_mov_b32_dpp v26, v20 row_mirror row_mask:0xf bank_mask:0xf bound_ctrl:1
	v_mov_b32_dpp v27, v21 row_mirror row_mask:0xf bank_mask:0xf bound_ctrl:1
	v_pk_add_f32 v[26:27], v[20:21], v[26:27]
	ds_write_b128 v22, v[24:27] offset:49728
	v_pk_mul_f32 v[24:25], v[12:13], v[12:13]
	v_pk_mul_f32 v[20:21], v[14:15], v[14:15]
	v_pk_fma_f32 v[24:25], v[16:17], v[16:17], v[24:25]
	v_pk_fma_f32 v[20:21], v[18:19], v[18:19], v[20:21]
	s_nop 0
	v_mov_b32_dpp v26, v24 quad_perm:[1,0,3,2] row_mask:0xf bank_mask:0xf bound_ctrl:1
	v_mov_b32_dpp v27, v25 quad_perm:[1,0,3,2] row_mask:0xf bank_mask:0xf bound_ctrl:1
	v_pk_add_f32 v[24:25], v[24:25], v[26:27]
	s_nop 1
	v_mov_b32_dpp v26, v24 quad_perm:[2,3,0,1] row_mask:0xf bank_mask:0xf bound_ctrl:1
	v_mov_b32_dpp v27, v25 quad_perm:[2,3,0,1] row_mask:0xf bank_mask:0xf bound_ctrl:1
	v_pk_add_f32 v[24:25], v[24:25], v[26:27]
	s_nop 1
	v_mov_b32_dpp v26, v24 row_half_mirror row_mask:0xf bank_mask:0xf bound_ctrl:1
	v_mov_b32_dpp v27, v25 row_half_mirror row_mask:0xf bank_mask:0xf bound_ctrl:1
	v_pk_add_f32 v[24:25], v[24:25], v[26:27]
	s_nop 1
	v_mov_b32_dpp v26, v24 row_mirror row_mask:0xf bank_mask:0xf bound_ctrl:1
	v_mov_b32_dpp v27, v25 row_mirror row_mask:0xf bank_mask:0xf bound_ctrl:1
	v_pk_add_f32 v[24:25], v[24:25], v[26:27]
	v_mov_b32_dpp v26, v20 quad_perm:[1,0,3,2] row_mask:0xf bank_mask:0xf bound_ctrl:1
	v_mov_b32_dpp v27, v21 quad_perm:[1,0,3,2] row_mask:0xf bank_mask:0xf bound_ctrl:1
	v_pk_add_f32 v[20:21], v[20:21], v[26:27]
	s_nop 1
	v_mov_b32_dpp v26, v20 quad_perm:[2,3,0,1] row_mask:0xf bank_mask:0xf bound_ctrl:1
	v_mov_b32_dpp v27, v21 quad_perm:[2,3,0,1] row_mask:0xf bank_mask:0xf bound_ctrl:1
	v_pk_add_f32 v[20:21], v[20:21], v[26:27]
	s_nop 1
	v_mov_b32_dpp v26, v20 row_half_mirror row_mask:0xf bank_mask:0xf bound_ctrl:1
	v_mov_b32_dpp v27, v21 row_half_mirror row_mask:0xf bank_mask:0xf bound_ctrl:1
	v_pk_add_f32 v[20:21], v[20:21], v[26:27]
	s_nop 1
	v_mov_b32_dpp v26, v20 row_mirror row_mask:0xf bank_mask:0xf bound_ctrl:1
	v_mov_b32_dpp v27, v21 row_mirror row_mask:0xf bank_mask:0xf bound_ctrl:1
	v_pk_add_f32 v[26:27], v[20:21], v[26:27]
	ds_write_b128 v22, v[24:27] offset:49792
	v_pk_mul_f32 v[24:25], v[4:5], v[4:5]
	v_pk_mul_f32 v[20:21], v[6:7], v[6:7]
	v_pk_fma_f32 v[24:25], v[8:9], v[8:9], v[24:25]
	v_pk_fma_f32 v[20:21], v[10:11], v[10:11], v[20:21]
	s_nop 0
	v_mov_b32_dpp v26, v24 quad_perm:[1,0,3,2] row_mask:0xf bank_mask:0xf bound_ctrl:1
	v_mov_b32_dpp v27, v25 quad_perm:[1,0,3,2] row_mask:0xf bank_mask:0xf bound_ctrl:1
	v_pk_add_f32 v[24:25], v[24:25], v[26:27]
	s_nop 1
	v_mov_b32_dpp v26, v24 quad_perm:[2,3,0,1] row_mask:0xf bank_mask:0xf bound_ctrl:1
	v_mov_b32_dpp v27, v25 quad_perm:[2,3,0,1] row_mask:0xf bank_mask:0xf bound_ctrl:1
	v_pk_add_f32 v[24:25], v[24:25], v[26:27]
	s_nop 1
	v_mov_b32_dpp v26, v24 row_half_mirror row_mask:0xf bank_mask:0xf bound_ctrl:1
	v_mov_b32_dpp v27, v25 row_half_mirror row_mask:0xf bank_mask:0xf bound_ctrl:1
	v_pk_add_f32 v[24:25], v[24:25], v[26:27]
	s_nop 1
	v_mov_b32_dpp v26, v24 row_mirror row_mask:0xf bank_mask:0xf bound_ctrl:1
	v_mov_b32_dpp v27, v25 row_mirror row_mask:0xf bank_mask:0xf bound_ctrl:1
	v_pk_add_f32 v[24:25], v[24:25], v[26:27]
	v_mov_b32_dpp v26, v20 quad_perm:[1,0,3,2] row_mask:0xf bank_mask:0xf bound_ctrl:1
	v_mov_b32_dpp v27, v21 quad_perm:[1,0,3,2] row_mask:0xf bank_mask:0xf bound_ctrl:1
	v_pk_add_f32 v[20:21], v[20:21], v[26:27]
	s_nop 1
	v_mov_b32_dpp v26, v20 quad_perm:[2,3,0,1] row_mask:0xf bank_mask:0xf bound_ctrl:1
	v_mov_b32_dpp v27, v21 quad_perm:[2,3,0,1] row_mask:0xf bank_mask:0xf bound_ctrl:1
	v_pk_add_f32 v[20:21], v[20:21], v[26:27]
	s_nop 1
	v_mov_b32_dpp v26, v20 row_half_mirror row_mask:0xf bank_mask:0xf bound_ctrl:1
	v_mov_b32_dpp v27, v21 row_half_mirror row_mask:0xf bank_mask:0xf bound_ctrl:1
	v_pk_add_f32 v[20:21], v[20:21], v[26:27]
	s_nop 1
	v_mov_b32_dpp v26, v20 row_mirror row_mask:0xf bank_mask:0xf bound_ctrl:1
	v_mov_b32_dpp v27, v21 row_mirror row_mask:0xf bank_mask:0xf bound_ctrl:1
	v_pk_add_f32 v[26:27], v[20:21], v[26:27]
	v_lshl_add_u64 v[20:21], v[50:51], 2, s[72:73]
	ds_write_b128 v22, v[24:27] offset:49856
	s_waitcnt lgkmcnt(0)
	s_barrier
	global_load_dword v24, v[20:21], off
	global_load_dword v22, v[20:21], off offset:64
	v_and_or_b32 v20, v132, 14, v46
	v_add_u32_e32 v20, v20, v48
	v_and_b32_e32 v21, 1, v132
	v_cmp_eq_u32_e32 vcc, 0, v21
	v_lshl_add_u32 v25, v21, 1, v44
	v_ashrrev_i32_e32 v21, 31, v20
	s_and_saveexec_b64 s[42:43], s[34:35]
	s_cbranch_execz .LBB0_421
; DEVINL float bf2f(u16 h) { return __uint_as_float(((unsigned)h) << 16); }
; DEVINL float siluf_(float x) { return x * __builtin_amdgcn_rcpf(1.f + __expf(-x)); }
; DEVINL void gla_passC(const Params& p, char* smem, int item) {
;     ...
;   for (int mf = 0; mf < 4; ++mf) {
;     const int t0 = mf * 16 + (lane >> 4) * 4;
;     if (t0 < ci.T) {
;       float rs[4];
; #pragma unroll
;       for (int j = 0; j < 4; ++j) {
;         const int t = t0 + j;
;         rs[j] = rsqrtf((red[t] + red[64 + t] + red[128 + t] + red[192 + t]) * (1.f / 128.f) + EPS);
;       }
; #pragma unroll
;       for (int nf = 0; nf < 2; ++nf) {
;         const int dv = 32 * w + nf * 16 + (lane & 15);
;         float o4[4];
; #pragma unroll
;         for (int j = 0; j < 4; ++j) {
;           float gv = bf2f(graw[mf][nf][j]);
;           o4[j] = o[mf][nf][j] * rs[j] * gn[nf] * siluf_(gv);
;         }
;         store_pairs(mixin, 1024, ci.r0 + t0, ci.h * 128 + dv, o4[0], o4[1], o4[2], o4[3]);
;       }
	ds_read_b128 v[50:53], v23 offset:49664
	ds_read_b128 v[54:57], v23 offset:49920
	ds_read_b128 v[58:61], v23 offset:50176
	ds_read_b128 v[62:65], v23 offset:50432
	s_mov_b32 s0, 0x358637bd
	s_waitcnt lgkmcnt(2)
	v_pk_add_f32 v[26:27], v[50:51], v[54:55]
	s_waitcnt lgkmcnt(1)
	v_pk_add_f32 v[26:27], v[26:27], v[58:59]
	v_mov_b64_e32 v[50:51], s[0:1]
	s_waitcnt lgkmcnt(0)
	v_pk_add_f32 v[26:27], v[26:27], v[62:63]
	s_brev_b32 s0, 60
	v_pk_fma_f32 v[26:27], v[26:27], s[0:1], v[50:51] op_sel_hi:[1,0,0]
	s_nop 0
	v_mul_f32_e32 v44, 0x4b800000, v26
	v_cmp_gt_f32_e64 s[36:37], s33, v26
	v_cmp_gt_f32_e64 s[34:35], s33, v27
	s_nop 0
	v_cndmask_b32_e64 v26, v26, v44, s[36:37]
	v_rsq_f32_e32 v26, v26
	s_nop 0
	v_mul_f32_e32 v44, 0x45800000, v26
	v_cndmask_b32_e64 v44, v26, v44, s[36:37]
	v_mul_f32_e32 v26, 0x4b800000, v27
	v_cndmask_b32_e64 v26, v27, v26, s[34:35]
	v_rsq_f32_e32 v26, v26
	v_mul_f32_e32 v40, v40, v44
	s_waitcnt vmcnt(1)
	v_mul_f32_e32 v40, v24, v40
	v_mul_f32_e32 v36, v36, v44
	v_mul_f32_e32 v27, 0x45800000, v26
	v_cndmask_b32_e64 v46, v26, v27, s[34:35]
	v_pk_add_f32 v[26:27], v[52:53], v[56:57]
	v_mul_f32_e32 v41, v41, v46
	v_pk_add_f32 v[26:27], v[26:27], v[60:61]
	v_mul_f32_e32 v41, v24, v41
	v_pk_add_f32 v[26:27], v[26:27], v[64:65]
	s_waitcnt vmcnt(0)
	v_mul_f32_e32 v36, v22, v36
	v_pk_fma_f32 v[26:27], v[26:27], s[0:1], v[50:51] op_sel_hi:[1,0,0]
	v_lshlrev_b32_e32 v51, 16, v131
	v_mul_f32_e32 v52, 0xbfb8aa3b, v51
	v_exp_f32_e32 v52, v52
	v_mul_f32_e32 v48, 0x4b800000, v26
	v_cmp_gt_f32_e64 s[36:37], s33, v26
	v_cmp_gt_f32_e64 s[34:35], s33, v27
	v_add_f32_e32 v52, 1.0, v52
	v_rcp_f32_e32 v52, v52
	v_cndmask_b32_e64 v26, v26, v48, s[36:37]
	v_rsq_f32_e32 v26, v26
	v_readlane_b32 s0, v194, 19
	v_mul_f32_e32 v51, v52, v51
	v_mul_f32_e32 v40, v51, v40
	v_lshlrev_b32_e32 v51, 16, v113
	v_mul_f32_e32 v52, 0xbfb8aa3b, v51
	v_exp_f32_e32 v52, v52
	v_mul_f32_e32 v48, 0x45800000, v26
	v_cndmask_b32_e64 v48, v26, v48, s[36:37]
	v_mul_f32_e32 v42, v42, v48
	v_add_f32_e32 v52, 1.0, v52
	v_rcp_f32_e32 v52, v52
	v_mul_f32_e32 v42, v24, v42
	v_mul_f32_e32 v26, 0x4b800000, v27
	v_cndmask_b32_e64 v26, v27, v26, s[34:35]
	v_mul_f32_e32 v51, v52, v51
	v_mul_f32_e32 v41, v51, v41
	v_lshlrev_b32_e32 v51, 16, v112
	v_mul_f32_e32 v52, 0xbfb8aa3b, v51
	v_exp_f32_e32 v52, v52
	v_rsq_f32_e32 v26, v26
	v_readlane_b32 s1, v194, 20
	v_mul_f32_e32 v37, v37, v46
	v_add_f32_e32 v52, 1.0, v52
	v_rcp_f32_e32 v52, v52
	v_mul_f32_e32 v27, 0x45800000, v26
	v_cndmask_b32_e64 v50, v26, v27, s[34:35]
	v_mul_f32_e32 v43, v43, v50
	v_mul_f32_e32 v51, v52, v51
	v_mul_f32_e32 v42, v51, v42
	v_lshlrev_b32_e32 v51, 16, v111
	v_mul_f32_e32 v52, 0xbfb8aa3b, v51
	v_exp_f32_e32 v52, v52
	v_mul_f32_e32 v43, v24, v43
	v_add_u32_e32 v26, v25, v74
	v_mov_b32_dpp v53, v42 quad_perm:[1,0,3,2] row_mask:0xf bank_mask:0xf bound_ctrl:1
	v_add_f32_e32 v52, 1.0, v52
	v_rcp_f32_e32 v52, v52
	v_ashrrev_i32_e32 v27, 31, v26
	v_lshlrev_b64 v[26:27], 11, v[26:27]
	v_lshl_add_u64 v[26:27], s[0:1], 0, v[26:27]
	v_mul_f32_e32 v51, v52, v51
	v_mul_f32_e32 v43, v51, v43
	v_mov_b32_dpp v52, v41 quad_perm:[1,0,3,2] row_mask:0xf bank_mask:0xf bound_ctrl:1
	v_mov_b32_dpp v51, v40 quad_perm:[1,0,3,2] row_mask:0xf bank_mask:0xf bound_ctrl:1
	v_cndmask_b32_e32 v42, v42, v51, vcc
	v_cndmask_b32_e32 v40, v53, v40, vcc
	v_mov_b32_dpp v54, v43 quad_perm:[1,0,3,2] row_mask:0xf bank_mask:0xf bound_ctrl:1
	v_add_u32_e32 v42, 0x8000, v42
	v_add_u32_e32 v40, 0x8000, v40
	v_perm_b32 v40, v42, v40, s25
	v_cndmask_b32_e32 v42, v43, v52, vcc
	v_cndmask_b32_e32 v41, v54, v41, vcc
	v_add_u32_e32 v42, 0x8000, v42
	v_add_u32_e32 v41, 0x8000, v41
	v_lshl_add_u64 v[26:27], v[20:21], 1, v[26:27]
	v_perm_b32 v41, v42, v41, s25
	global_store_dword v[26:27], v40, off
	global_store_dword v[26:27], v41, off offset:2048
	v_lshlrev_b32_e32 v40, 16, v110
	v_mul_f32_e32 v41, 0xbfb8aa3b, v40
	v_exp_f32_e32 v41, v41
	v_mul_f32_e32 v37, v22, v37
	v_mul_f32_e32 v38, v38, v48
	v_mul_f32_e32 v38, v22, v38
	v_add_f32_e32 v41, 1.0, v41
	v_rcp_f32_e32 v41, v41
	v_mul_f32_e32 v39, v39, v50
	v_mul_f32_e32 v39, v22, v39
	v_mul_f32_e32 v40, v41, v40
	v_mul_f32_e32 v36, v40, v36
	v_lshlrev_b32_e32 v40, 16, v109
	v_mul_f32_e32 v41, 0xbfb8aa3b, v40
	v_exp_f32_e32 v41, v41
	s_nop 0
	v_add_f32_e32 v41, 1.0, v41
	v_rcp_f32_e32 v41, v41
	s_nop 0
	v_mul_f32_e32 v40, v41, v40
	v_mul_f32_e32 v37, v40, v37
	v_lshlrev_b32_e32 v40, 16, v108
	v_mul_f32_e32 v41, 0xbfb8aa3b, v40
	v_exp_f32_e32 v41, v41
	s_nop 0
	v_add_f32_e32 v41, 1.0, v41
	v_rcp_f32_e32 v41, v41
	s_nop 0
	v_mul_f32_e32 v40, v41, v40
	v_mul_f32_e32 v38, v40, v38
	v_lshlrev_b32_e32 v40, 16, v107
	v_mul_f32_e32 v41, 0xbfb8aa3b, v40
	v_exp_f32_e32 v41, v41
	v_mov_b32_dpp v42, v38 quad_perm:[1,0,3,2] row_mask:0xf bank_mask:0xf bound_ctrl:1
	v_add_f32_e32 v41, 1.0, v41
	v_rcp_f32_e32 v41, v41
	s_nop 0
	v_mul_f32_e32 v40, v41, v40
	v_mul_f32_e32 v39, v40, v39
	s_nop 0
	v_mov_b32_dpp v40, v36 quad_perm:[1,0,3,2] row_mask:0xf bank_mask:0xf bound_ctrl:1
	v_cndmask_b32_e32 v38, v38, v40, vcc
	v_cndmask_b32_e32 v36, v42, v36, vcc
	v_mov_b32_dpp v41, v37 quad_perm:[1,0,3,2] row_mask:0xf bank_mask:0xf bound_ctrl:1
	v_mov_b32_dpp v43, v39 quad_perm:[1,0,3,2] row_mask:0xf bank_mask:0xf bound_ctrl:1
	v_add_u32_e32 v38, 0x8000, v38
	v_add_u32_e32 v36, 0x8000, v36
	v_perm_b32 v36, v38, v36, s25
	v_cndmask_b32_e32 v38, v39, v41, vcc
	v_cndmask_b32_e32 v37, v43, v37, vcc
	v_add_u32_e32 v38, 0x8000, v38
	v_add_u32_e32 v37, 0x8000, v37
	v_perm_b32 v37, v38, v37, s25
	global_store_dword v[26:27], v36, off offset:32
	global_store_dword v[26:27], v37, off offset:2080

; DEVINL void gla_passC(const Params& p, char* smem, int item) {
;     ...
;   const u16* qk = (const u16*)(p.ws + OFF_QK);
;   const u16* vT = (const u16*)(p.ws + OFF_VT);
;   const u16* SpT = (const u16*)(p.ws + OFF_SPT) + (size_t)item * 8192;
;   const u16* gbuf = (const u16*)(p.ws + OFF_GB);
;   u16 qraw[16], kraw16[16];
; #pragma unroll
;   for (int i = 0; i < 16; ++i) {
;     const int t = 16 * w + i;
;     qraw[i] = qk[(size_t)(ci.r0 + t) * 512 + ci.h * 64 + lane];
;     kraw16[i] = qk[(size_t)(ci.r0 + t) * 512 + 256 + ci.h * 64 + lane];
;   }
;   bf16x8 bvv[2][2], bss[2][2];
; #pragma unroll
;   for (int ks = 0; ks < 2; ++ks) {
;     const int kb = ks * 32 + 8 * (lane >> 4);
; #pragma unroll
;     for (int nf = 0; nf < 2; ++nf) {
;       const int dv = 32 * w + nf * 16 + (lane & 15);
;       bvv[ks][nf] = *(const bf16x8*)(vT + (size_t)(ci.h * 128 + dv) * LDT + ci.r0 + kb);
;       bss[ks][nf] = *(const bf16x8*)(SpT + dv * 64 + kb);
;     }
;   }
;   u16 graw[4][2][4];
; #pragma unroll
;   for (int mf = 0; mf < 4; ++mf) {
;     const int t0 = mf * 16 + (lane >> 4) * 4;
; #pragma unroll
;     for (int nf = 0; nf < 2; ++nf)
; #pragma unroll
;       for (int j = 0; j < 4; ++j)
;         graw[mf][nf][j] = gbuf[(size_t)(ci.r0 + t0 + j) * 512 + ci.h * 128 + 32 * w + nf * 16 + (lane & 15)];
;   }
;   float bcum[16];
;   {
;     const float* bc = (const float*)(p.ws + OFF_BCUM) + (size_t)item * 4096;
; #pragma unroll
;     for (int i = 0; i < 16; ++i) bcum[i] = bc[(16 * w + i) * 64 + lane];
;   }
.LBB0_437:
	s_or_b64 exec, exec, s[0:1]
	v_mov_b32_e32 v143, v0
	v_and_b32_e32 v36, 3, v4
	v_ashrrev_i32_e32 v154, 6, v143
	v_lshlrev_b32_e32 v148, 4, v154
	v_add_u32_e32 v4, v148, v50
	v_ashrrev_i32_e32 v5, 31, v4
	v_lshlrev_b64 v[6:7], 10, v[4:5]
	v_and_b32_e32 v152, 63, v143
	v_lshl_add_u64 v[6:7], s[94:95], 0, v[6:7]
	v_lshlrev_b32_e32 v52, 7, v36
	v_mov_b32_e32 v53, v2
	v_lshl_add_u64 v[6:7], v[6:7], 0, v[52:53]
	v_lshlrev_b32_e32 v8, 1, v152
	v_mov_b32_e32 v9, v2
	v_lshl_add_u64 v[84:85], v[6:7], 0, v[8:9]
	v_add_u32_e32 v6, 1, v4
	v_ashrrev_i32_e32 v7, 31, v6
	v_lshlrev_b64 v[6:7], 10, v[6:7]
	v_lshl_add_u64 v[6:7], s[94:95], 0, v[6:7]
	v_lshl_add_u64 v[6:7], v[6:7], 0, v[52:53]
	v_lshl_add_u64 v[76:77], v[6:7], 0, v[8:9]
	v_add_u32_e32 v6, 2, v4
	v_ashrrev_i32_e32 v7, 31, v6
	v_lshlrev_b64 v[6:7], 10, v[6:7]
	v_lshl_add_u64 v[6:7], s[94:95], 0, v[6:7]
	v_lshl_add_u64 v[6:7], v[6:7], 0, v[52:53]
	v_lshl_add_u64 v[66:67], v[6:7], 0, v[8:9]
	v_add_u32_e32 v6, 3, v4
	v_ashrrev_i32_e32 v7, 31, v6
	v_lshlrev_b64 v[6:7], 10, v[6:7]
	v_lshl_add_u64 v[6:7], s[94:95], 0, v[6:7]
	v_lshl_add_u64 v[6:7], v[6:7], 0, v[52:53]
	v_lshl_add_u64 v[40:41], v[6:7], 0, v[8:9]
	v_add_u32_e32 v6, 4, v4
	v_ashrrev_i32_e32 v7, 31, v6
	v_lshlrev_b64 v[6:7], 10, v[6:7]
	v_lshl_add_u64 v[6:7], s[94:95], 0, v[6:7]
	v_lshl_add_u64 v[6:7], v[6:7], 0, v[52:53]
	v_lshl_add_u64 v[42:43], v[6:7], 0, v[8:9]
	v_add_u32_e32 v6, 5, v4
	v_ashrrev_i32_e32 v7, 31, v6
	v_lshlrev_b64 v[6:7], 10, v[6:7]
	v_lshl_add_u64 v[6:7], s[94:95], 0, v[6:7]
	v_lshl_add_u64 v[6:7], v[6:7], 0, v[52:53]
	v_lshl_add_u64 v[58:59], v[6:7], 0, v[8:9]
	v_add_u32_e32 v6, 6, v4
	v_ashrrev_i32_e32 v7, 31, v6
	v_lshlrev_b64 v[6:7], 10, v[6:7]
	v_lshl_add_u64 v[6:7], s[94:95], 0, v[6:7]
	v_lshl_add_u64 v[6:7], v[6:7], 0, v[52:53]
	v_lshl_add_u64 v[60:61], v[6:7], 0, v[8:9]
	v_add_u32_e32 v6, 7, v4
	v_ashrrev_i32_e32 v7, 31, v6
	v_lshlrev_b64 v[6:7], 10, v[6:7]
	v_lshl_add_u64 v[6:7], s[94:95], 0, v[6:7]
	v_lshl_add_u64 v[6:7], v[6:7], 0, v[52:53]
	v_lshl_add_u64 v[62:63], v[6:7], 0, v[8:9]
	v_add_u32_e32 v6, 8, v4
	v_ashrrev_i32_e32 v7, 31, v6
	v_lshlrev_b64 v[6:7], 10, v[6:7]
	v_lshl_add_u64 v[6:7], s[94:95], 0, v[6:7]
	v_lshl_add_u64 v[6:7], v[6:7], 0, v[52:53]
	v_lshl_add_u64 v[64:65], v[6:7], 0, v[8:9]
	v_add_u32_e32 v6, 9, v4
	v_ashrrev_i32_e32 v7, 31, v6
	v_lshlrev_b64 v[6:7], 10, v[6:7]
	v_lshl_add_u64 v[6:7], s[94:95], 0, v[6:7]
	v_lshl_add_u64 v[6:7], v[6:7], 0, v[52:53]
	v_lshl_add_u64 v[68:69], v[6:7], 0, v[8:9]
	v_add_u32_e32 v6, 10, v4
	v_ashrrev_i32_e32 v7, 31, v6
	v_lshlrev_b64 v[6:7], 10, v[6:7]
	v_lshl_add_u64 v[6:7], s[94:95], 0, v[6:7]
	v_lshl_add_u64 v[6:7], v[6:7], 0, v[52:53]
	v_lshl_add_u64 v[70:71], v[6:7], 0, v[8:9]
	v_add_u32_e32 v6, 11, v4
	v_ashrrev_i32_e32 v7, 31, v6
	v_lshlrev_b64 v[6:7], 10, v[6:7]
	v_lshl_add_u64 v[6:7], s[94:95], 0, v[6:7]
	v_lshl_add_u64 v[6:7], v[6:7], 0, v[52:53]
	v_lshl_add_u64 v[72:73], v[6:7], 0, v[8:9]
	v_add_u32_e32 v6, 12, v4
	v_ashrrev_i32_e32 v7, 31, v6
	v_lshlrev_b64 v[6:7], 10, v[6:7]
	v_lshl_add_u64 v[6:7], s[94:95], 0, v[6:7]
	v_lshl_add_u64 v[6:7], v[6:7], 0, v[52:53]
	v_lshl_add_u64 v[74:75], v[6:7], 0, v[8:9]
	v_add_u32_e32 v6, 13, v4
	v_ashrrev_i32_e32 v7, 31, v6
	v_lshlrev_b64 v[6:7], 10, v[6:7]
	v_lshl_add_u64 v[6:7], s[94:95], 0, v[6:7]
	v_lshl_add_u64 v[6:7], v[6:7], 0, v[52:53]
	v_lshl_add_u64 v[78:79], v[6:7], 0, v[8:9]
	v_add_u32_e32 v6, 14, v4
	v_add_u32_e32 v4, 15, v4
	v_ashrrev_i32_e32 v5, 31, v4
	v_ashrrev_i32_e32 v7, 31, v6
	v_lshlrev_b64 v[4:5], 10, v[4:5]
	v_lshlrev_b64 v[6:7], 10, v[6:7]
	v_lshl_add_u64 v[4:5], s[94:95], 0, v[4:5]
	v_lshlrev_b32_e32 v54, 5, v154
	v_and_b32_e32 v149, 15, v143
	v_readlane_b32 s0, v194, 35
	v_lshl_add_u64 v[6:7], s[94:95], 0, v[6:7]
	v_lshl_add_u64 v[4:5], v[4:5], 0, v[52:53]
	v_or_b32_e32 v56, v54, v149
	v_ashrrev_i32_e32 v51, 31, v50
	v_readlane_b32 s1, v194, 36
	v_lshl_add_u64 v[6:7], v[6:7], 0, v[52:53]
	v_lshl_add_u64 v[82:83], v[4:5], 0, v[8:9]
	v_lshl_add_u64 v[4:5], v[50:51], 1, s[0:1]
	v_and_b32_e32 v38, 48, v143
	v_mov_b32_e32 v39, v2
	v_or_b32_e32 v10, 16, v56
	v_lshl_add_u64 v[80:81], v[6:7], 0, v[8:9]
	v_add_u32_e32 v6, v56, v52
	v_lshl_add_u64 v[4:5], v[4:5], 0, v[38:39]
	v_add_u32_e32 v11, v10, v52
	v_lshrrev_b32_e32 v37, 2, v143
	v_mad_i64_i32 v[6:7], s[0:1], v6, s88, v[4:5]
	v_lshlrev_b32_e32 v8, 6, v56
	v_mad_i64_i32 v[12:13], s[0:1], v11, s88, v[4:5]
	v_lshlrev_b32_e32 v4, 6, v10
	v_and_b32_e32 v102, 12, v37
	v_lshlrev_b32_e32 v36, 8, v36
	v_mov_b32_e32 v37, v2
	v_ashrrev_i32_e32 v9, 31, v8
	v_ashrrev_i32_e32 v5, 31, v4
	v_add_u32_e32 v88, v102, v50
	v_ashrrev_i32_e32 v55, 31, v54
	v_lshl_add_u64 v[36:37], s[92:93], 0, v[36:37]
	v_lshlrev_b64 v[8:9], 1, v[8:9]
	v_lshlrev_b64 v[4:5], 1, v[4:5]
	v_lshl_add_u64 v[90:91], v[54:55], 1, v[36:37]
	v_lshlrev_b32_e32 v36, 1, v149
	v_mov_b32_e32 v37, v2
	v_ashrrev_i32_e32 v89, 31, v88
	v_or_b32_e32 v8, v8, v38
	v_or_b32_e32 v4, v4, v38
	v_lshl_add_u64 v[150:151], v[90:91], 0, v[36:37]
	v_lshlrev_b64 v[90:91], 10, v[88:89]
	v_lshl_add_u64 v[8:9], v[46:47], 0, v[8:9]
	v_lshl_add_u64 v[14:15], v[46:47], 0, v[4:5]
	v_lshl_add_u64 v[90:91], v[150:151], 0, v[90:91]
	global_load_dwordx4 v[20:23], v[6:7], off
	global_load_dwordx4 v[24:27], v[8:9], off
	global_load_dwordx4 v[28:31], v[12:13], off
	global_load_dwordx4 v[32:35], v[14:15], off
	s_nop 0
	global_load_dwordx4 v[4:7], v[6:7], off offset:64
	s_nop 0
	global_load_dwordx4 v[8:11], v[8:9], off offset:64
	s_nop 0
	global_load_dwordx4 v[16:19], v[12:13], off offset:64
	s_nop 0
	global_load_dwordx4 v[12:15], v[14:15], off offset:64
	s_nop 0
	global_load_ushort v147, v[90:91], off
; DEVINL void gla_passC(const Params& p, char* smem, int item) {
;     ...
;   for (int i = 0; i < 16; ++i) {
;     const int t = 16 * w + i;
;     qraw[i] = qk[(size_t)(ci.r0 + t) * 512 + ci.h * 64 + lane];
;     kraw16[i] = qk[(size_t)(ci.r0 + t) * 512 + 256 + ci.h * 64 + lane];
;   }
;   bf16x8 bvv[2][2], bss[2][2];
; #pragma unroll
;   for (int ks = 0; ks < 2; ++ks) {
;     const int kb = ks * 32 + 8 * (lane >> 4);
; #pragma unroll
;     for (int nf = 0; nf < 2; ++nf) {
;       const int dv = 32 * w + nf * 16 + (lane & 15);
;       bvv[ks][nf] = *(const bf16x8*)(vT + (size_t)(ci.h * 128 + dv) * LDT + ci.r0 + kb);
;       bss[ks][nf] = *(const bf16x8*)(SpT + dv * 64 + kb);
;     }
;   }
;   u16 graw[4][2][4];
; #pragma unroll
;   for (int mf = 0; mf < 4; ++mf) {
;     const int t0 = mf * 16 + (lane >> 4) * 4;
; #pragma unroll
;     for (int nf = 0; nf < 2; ++nf)
; #pragma unroll
;       for (int j = 0; j < 4; ++j)
;         graw[mf][nf][j] = gbuf[(size_t)(ci.r0 + t0 + j) * 512 + ci.h * 128 + 32 * w + nf * 16 + (lane & 15)];
;   }
;   float bcum[16];
;   {
;     const float* bc = (const float*)(p.ws + OFF_BCUM) + (size_t)item * 4096;
; #pragma unroll
;     for (int i = 0; i < 16; ++i) bcum[i] = bc[(16 * w + i) * 64 + lane];
;   }
;   __syncthreads();
	global_load_ushort v146, v[90:91], off offset:1024
	global_load_ushort v145, v[90:91], off offset:2048
	global_load_ushort v144, v[90:91], off offset:3072
	global_load_ushort v142, v[90:91], off offset:32
	global_load_ushort v141, v[90:91], off offset:1056
	global_load_ushort v140, v[90:91], off offset:2080
	global_load_ushort v139, v[90:91], off offset:3104
	v_add_u32_e32 v90, 16, v88
	v_add_u32_e32 v106, 17, v88
	v_add_u32_e32 v108, 18, v88
	v_add_u32_e32 v110, 19, v88
	v_ashrrev_i32_e32 v91, 31, v90
	v_ashrrev_i32_e32 v107, 31, v106
	v_ashrrev_i32_e32 v109, 31, v108
	v_ashrrev_i32_e32 v111, 31, v110
	v_lshlrev_b64 v[90:91], 10, v[90:91]
	v_lshlrev_b64 v[106:107], 10, v[106:107]
	v_lshlrev_b64 v[108:109], 10, v[108:109]
	v_lshlrev_b64 v[110:111], 10, v[110:111]
	v_lshl_add_u64 v[90:91], v[150:151], 0, v[90:91]
	v_lshl_add_u64 v[106:107], v[150:151], 0, v[106:107]
	v_lshl_add_u64 v[108:109], v[150:151], 0, v[108:109]
	v_lshl_add_u64 v[110:111], v[150:151], 0, v[110:111]
	global_load_ushort v138, v[90:91], off
	global_load_ushort v137, v[106:107], off
	global_load_ushort v136, v[108:109], off
	global_load_ushort v135, v[110:111], off
	global_load_ushort v134, v[90:91], off offset:32
	global_load_ushort v133, v[106:107], off offset:32
	global_load_ushort v132, v[108:109], off offset:32
	global_load_ushort v131, v[110:111], off offset:32
	v_add_u32_e32 v108, 34, v88
	v_ashrrev_i32_e32 v109, 31, v108
	v_lshlrev_b64 v[108:109], 10, v[108:109]
	v_add_u32_e32 v90, 32, v88
	v_add_u32_e32 v106, 33, v88
	v_lshl_add_u64 v[156:157], v[150:151], 0, v[108:109]
	v_add_u32_e32 v108, 35, v88
	v_ashrrev_i32_e32 v91, 31, v90
	v_ashrrev_i32_e32 v107, 31, v106
	v_ashrrev_i32_e32 v109, 31, v108
	v_lshlrev_b64 v[90:91], 10, v[90:91]
	v_lshlrev_b64 v[106:107], 10, v[106:107]
	v_lshlrev_b64 v[108:109], 10, v[108:109]
	v_lshl_add_u64 v[90:91], v[150:151], 0, v[90:91]
	v_lshl_add_u64 v[106:107], v[150:151], 0, v[106:107]
	v_lshl_add_u64 v[158:159], v[150:151], 0, v[108:109]
	global_load_ushort v113, v[90:91], off
	global_load_ushort v112, v[106:107], off
	global_load_ushort v111, v[156:157], off
	global_load_ushort v110, v[158:159], off
	global_load_ushort v109, v[90:91], off offset:32
	global_load_ushort v108, v[106:107], off offset:32
	s_nop 0
	global_load_ushort v107, v[156:157], off offset:32
	global_load_ushort v106, v[158:159], off offset:32
	v_add_u32_e32 v90, 48, v88
	v_ashrrev_i32_e32 v91, 31, v90
	v_lshlrev_b64 v[90:91], 10, v[90:91]
	v_lshl_add_u64 v[156:157], v[150:151], 0, v[90:91]
	v_add_u32_e32 v90, 49, v88
	v_add_u32_e32 v160, 50, v88
	v_add_u32_e32 v88, 51, v88
	v_ashrrev_i32_e32 v91, 31, v90
	v_ashrrev_i32_e32 v161, 31, v160
	v_ashrrev_i32_e32 v89, 31, v88
	v_lshlrev_b64 v[90:91], 10, v[90:91]
	v_lshlrev_b64 v[160:161], 10, v[160:161]
	v_lshlrev_b64 v[88:89], 10, v[88:89]
	v_lshl_add_u64 v[158:159], v[150:151], 0, v[90:91]
	v_lshl_add_u64 v[160:161], v[150:151], 0, v[160:161]
	v_lshl_add_u64 v[150:151], v[150:151], 0, v[88:89]
	global_load_ushort v105, v[156:157], off
	global_load_ushort v91, v[158:159], off
	global_load_ushort v90, v[160:161], off
	global_load_ushort v89, v[150:151], off
	global_load_ushort v88, v[156:157], off offset:32
	global_load_ushort v55, v[158:159], off offset:32
	global_load_ushort v53, v[160:161], off offset:32
	global_load_ushort v51, v[150:151], off offset:32
	v_lshl_or_b32 v150, v154, 10, v152
	v_ashrrev_i32_e32 v151, 31, v150
	v_lshl_add_u64 v[150:151], v[150:151], 2, v[46:47]
	s_mov_b32 s0, 0x4be0000
	v_add_co_u32_e32 v162, vcc, s0, v150
	s_movk_i32 s0, 0x480
	s_nop 0
	v_addc_co_u32_e32 v163, vcc, 0, v151, vcc
	global_load_dword v161, v[162:163], off
	global_load_dword v164, v[162:163], off offset:256
	global_load_dword v165, v[162:163], off offset:512
	global_load_dword v166, v[162:163], off offset:768
	global_load_dword v167, v[162:163], off offset:1024
	global_load_dword v160, v[162:163], off offset:1280
	global_load_dword v159, v[162:163], off offset:1536
	global_load_dword v158, v[162:163], off offset:1792
	global_load_dword v157, v[162:163], off offset:2048
	global_load_dword v156, v[162:163], off offset:2304
	global_load_dword v155, v[162:163], off offset:2560
	global_load_dword v153, v[162:163], off offset:2816
	global_load_dword v151, v[162:163], off offset:3072
	global_load_dword v150, v[162:163], off offset:3328
	global_load_dword v39, v[162:163], off offset:3584
	global_load_dword v37, v[162:163], off offset:3840
	s_nop 0
	global_load_ushort v162, v[84:85], off
	s_nop 0
	global_load_ushort v84, v[84:85], off offset:512
	s_nop 0
	global_load_ushort v85, v[76:77], off
	s_nop 0
	global_load_ushort v76, v[76:77], off offset:512
	s_nop 0
	global_load_ushort v77, v[66:67], off
	s_nop 0
	global_load_ushort v66, v[66:67], off offset:512
	s_nop 0
	global_load_ushort v67, v[40:41], off
	global_load_ushort v163, v[40:41], off offset:512
	global_load_ushort v168, v[42:43], off
	global_load_ushort v169, v[42:43], off offset:512
	global_load_ushort v170, v[58:59], off
	global_load_ushort v171, v[58:59], off offset:512
	global_load_ushort v172, v[60:61], off
	global_load_ushort v173, v[60:61], off offset:512
	global_load_ushort v174, v[62:63], off
	global_load_ushort v175, v[62:63], off offset:512
	global_load_ushort v176, v[64:65], off
	s_nop 0
	global_load_ushort v65, v[64:65], off offset:512
	s_nop 0
	global_load_ushort v177, v[68:69], off
	s_nop 0
	global_load_ushort v68, v[68:69], off offset:512
	s_nop 0
	global_load_ushort v69, v[70:71], off
	s_nop 0
	global_load_ushort v70, v[70:71], off offset:512
	s_nop 0
	global_load_ushort v64, v[72:73], off
	global_load_ushort v63, v[72:73], off offset:512
	global_load_ushort v62, v[74:75], off
	global_load_ushort v61, v[74:75], off offset:512
	global_load_ushort v60, v[78:79], off
	global_load_ushort v59, v[78:79], off offset:512
	global_load_ushort v43, v[80:81], off
	global_load_ushort v42, v[80:81], off offset:512
	global_load_ushort v41, v[82:83], off
	global_load_ushort v40, v[82:83], off offset:512
	v_cmp_lt_i32_e32 vcc, v148, v45
	s_waitcnt vmcnt(63) expcnt(7) lgkmcnt(15)
	s_barrier
; DEVINL u16 f2bf(float f) { return (u16)((__float_as_uint(f) + 0x8000u) >> 16); }
; DEVINL float bf2f(u16 h) { return __uint_as_float(((unsigned)h) << 16); }
; DEVINL void gla_passC(const Params& p, char* smem, int item) {
;     ...
;   for (int i = 0; i < 16; ++i) {
;     const int t = 16 * w + i;
;     const float qv = (t < ci.T) ? bf2f(qraw[i]) : 0.f, kv = (t < ci.T) ? bf2f(kraw16[i]) : 0.f;
;     const float bt = bcum[i];
;     Qd[t * 72 + lane] = f2bf(qv * __expf(bt));
;     Ki[t * 72 + lane] = f2bf(kv * __expf(-bt));
;   }
	s_movk_i32 s34, 0x90
	v_or_b32_e32 v78, 32, v149
	v_or_b32_e32 v79, 48, v149
	v_ashrrev_i32_e32 v57, 31, v56
	s_waitcnt vmcnt(47)
	v_mul_f32_e32 v72, 0x3fb8aa3b, v161
	v_exp_f32_e32 v72, v72
	s_waitcnt vmcnt(46)
	v_mul_f32_e32 v73, 0x3fb8aa3b, v164
	v_exp_f32_e32 v73, v73
	s_waitcnt vmcnt(31)
	v_lshlrev_b32_e32 v58, 16, v162
	v_cndmask_b32_e32 v58, 0, v58, vcc
	v_mul_f32_e32 v58, v58, v72
	v_mul_lo_u32 v72, v154, s0
	v_or_b32_e32 v72, v72, v152
	v_add_u32_e32 v58, 0x8000, v58
	v_lshlrev_b32_e32 v72, 1, v72
	ds_write_b16_d16_hi v72, v58 offset:22016
	v_mul_f32_e32 v58, 0xbfb8aa3b, v161
	v_exp_f32_e32 v58, v58
	s_waitcnt vmcnt(30)
	v_lshlrev_b32_e32 v71, 16, v84
	v_cndmask_b32_e32 v71, 0, v71, vcc
	s_movk_i32 s0, 0x48
	v_mul_f32_e32 v58, v71, v58
	v_add_u32_e32 v58, 0x8000, v58
	ds_write_b16_d16_hi v72, v58 offset:31232
	v_or_b32_e32 v58, 1, v148
	v_cmp_lt_i32_e32 vcc, v58, v45
	s_waitcnt vmcnt(29)
	v_lshlrev_b32_e32 v71, 16, v85
	v_mul_lo_u32 v58, v58, s0
	v_cndmask_b32_e32 v71, 0, v71, vcc
	v_mul_f32_e32 v71, v71, v73
	v_add_u32_e32 v71, 0x8000, v71
	v_add_lshl_u32 v58, v58, v152, 1
	ds_write_b16_d16_hi v58, v71 offset:22016
	v_mul_f32_e32 v71, 0xbfb8aa3b, v164
	v_exp_f32_e32 v71, v71
	s_waitcnt vmcnt(28)
	v_lshlrev_b32_e32 v72, 16, v76
	v_cndmask_b32_e32 v72, 0, v72, vcc
	s_waitcnt vmcnt(26)
	v_lshlrev_b32_e32 v66, 16, v66
	v_mul_f32_e32 v71, v72, v71
	v_mul_f32_e32 v72, 0x3fb8aa3b, v165
	v_add_u32_e32 v71, 0x8000, v71
	v_exp_f32_e32 v72, v72
	ds_write_b16_d16_hi v58, v71 offset:31232
	v_or_b32_e32 v71, 2, v148
	v_cmp_lt_i32_e32 vcc, v71, v45
	v_lshlrev_b32_e32 v71, 16, v77
	s_waitcnt vmcnt(14)
	v_lshlrev_b32_e32 v65, 16, v65
	v_cndmask_b32_e32 v71, 0, v71, vcc
	v_mul_f32_e32 v71, v71, v72
	v_add_u32_e32 v71, 0x8000, v71
	ds_write_b16_d16_hi v58, v71 offset:22160
	v_mul_f32_e32 v71, 0xbfb8aa3b, v165
	v_exp_f32_e32 v71, v71
	v_cndmask_b32_e32 v66, 0, v66, vcc
	s_waitcnt vmcnt(9)
	v_lshlrev_b32_e32 v64, 16, v64
	s_waitcnt vmcnt(8)
	v_lshlrev_b32_e32 v63, 16, v63
	v_mul_f32_e32 v66, v66, v71
	v_mul_f32_e32 v71, 0x3fb8aa3b, v166
	v_add_u32_e32 v66, 0x8000, v66
	v_exp_f32_e32 v71, v71
	ds_write_b16_d16_hi v58, v66 offset:31376
	v_or_b32_e32 v66, 3, v148
	v_cmp_lt_i32_e32 vcc, v66, v45
	v_lshlrev_b32_e32 v66, 16, v67
	v_lshlrev_b32_e32 v67, 16, v163
	v_cndmask_b32_e32 v66, 0, v66, vcc
	v_mul_f32_e32 v66, v66, v71
	v_add_u32_e32 v66, 0x8000, v66
	ds_write_b16_d16_hi v58, v66 offset:22304
	v_mul_f32_e32 v66, 0xbfb8aa3b, v166
	v_exp_f32_e32 v66, v66
	v_cndmask_b32_e32 v67, 0, v67, vcc
	v_mul_f32_e32 v71, 0x3fb8aa3b, v167
	v_exp_f32_e32 v71, v71
	v_mul_f32_e32 v66, v67, v66
	v_add_u32_e32 v66, 0x8000, v66
	ds_write_b16_d16_hi v58, v66 offset:31520
	v_or_b32_e32 v66, 4, v148
	v_cmp_lt_i32_e32 vcc, v66, v45
	v_lshlrev_b32_e32 v66, 16, v168
	v_lshlrev_b32_e32 v67, 16, v169
	v_cndmask_b32_e32 v66, 0, v66, vcc
	v_mul_f32_e32 v66, v66, v71
	v_add_u32_e32 v66, 0x8000, v66
	ds_write_b16_d16_hi v58, v66 offset:22448
	v_mul_f32_e32 v66, 0xbfb8aa3b, v167
	v_exp_f32_e32 v66, v66
	v_cndmask_b32_e32 v67, 0, v67, vcc
	v_mul_f32_e32 v71, 0x3fb8aa3b, v160
	v_exp_f32_e32 v71, v71
	v_mul_f32_e32 v66, v67, v66
	v_add_u32_e32 v66, 0x8000, v66
	ds_write_b16_d16_hi v58, v66 offset:31664
	v_or_b32_e32 v66, 5, v148
	v_cmp_lt_i32_e32 vcc, v66, v45
	v_lshlrev_b32_e32 v66, 16, v170
	v_lshlrev_b32_e32 v67, 16, v171
	v_cndmask_b32_e32 v66, 0, v66, vcc
	v_mul_f32_e32 v66, v66, v71
	v_add_u32_e32 v66, 0x8000, v66
	ds_write_b16_d16_hi v58, v66 offset:22592
	v_mul_f32_e32 v66, 0xbfb8aa3b, v160
	v_exp_f32_e32 v66, v66
	v_cndmask_b32_e32 v67, 0, v67, vcc
	v_mul_f32_e32 v71, 0x3fb8aa3b, v159
	v_exp_f32_e32 v71, v71
	v_mul_f32_e32 v66, v67, v66
	v_add_u32_e32 v66, 0x8000, v66
	ds_write_b16_d16_hi v58, v66 offset:31808
	v_or_b32_e32 v66, 6, v148
	v_cmp_lt_i32_e32 vcc, v66, v45
	v_lshlrev_b32_e32 v66, 16, v172
	v_lshlrev_b32_e32 v67, 16, v173
	v_cndmask_b32_e32 v66, 0, v66, vcc
	v_mul_f32_e32 v66, v66, v71
	v_add_u32_e32 v66, 0x8000, v66
	ds_write_b16_d16_hi v58, v66 offset:22736
	v_mul_f32_e32 v66, 0xbfb8aa3b, v159
	v_exp_f32_e32 v66, v66
	v_cndmask_b32_e32 v67, 0, v67, vcc
	v_mul_f32_e32 v71, 0x3fb8aa3b, v158
	v_exp_f32_e32 v71, v71
	v_mul_f32_e32 v66, v67, v66
	v_add_u32_e32 v66, 0x8000, v66
	ds_write_b16_d16_hi v58, v66 offset:31952
	v_or_b32_e32 v66, 7, v148
	v_cmp_lt_i32_e32 vcc, v66, v45
	v_lshlrev_b32_e32 v66, 16, v174
	v_lshlrev_b32_e32 v67, 16, v175
	v_cndmask_b32_e32 v66, 0, v66, vcc
	v_mul_f32_e32 v66, v66, v71
	v_add_u32_e32 v66, 0x8000, v66
	ds_write_b16_d16_hi v58, v66 offset:22880
	v_mul_f32_e32 v66, 0xbfb8aa3b, v158
	v_exp_f32_e32 v66, v66
	v_cndmask_b32_e32 v67, 0, v67, vcc
	s_waitcnt vmcnt(7)
	v_lshlrev_b32_e32 v62, 16, v62
	s_waitcnt vmcnt(6)
	v_lshlrev_b32_e32 v61, 16, v61
	v_mul_f32_e32 v66, v67, v66
	v_mul_f32_e32 v67, 0x3fb8aa3b, v157
	v_add_u32_e32 v66, 0x8000, v66
	v_exp_f32_e32 v67, v67
	ds_write_b16_d16_hi v58, v66 offset:32096
	v_or_b32_e32 v66, 8, v148
	v_cmp_lt_i32_e32 vcc, v66, v45
	v_lshlrev_b32_e32 v66, 16, v176
	s_waitcnt vmcnt(5)
; DEVINL u16 f2bf(float f) { return (u16)((__float_as_uint(f) + 0x8000u) >> 16); }
; DEVINL float bf2f(u16 h) { return __uint_as_float(((unsigned)h) << 16); }
; DEVINL f32x4 mfma16(bf16x8 a, bf16x8 b, f32x4 c) { return __builtin_amdgcn_mfma_f32_16x16x32_bf16(a, b, c, 0, 0, 0); }
; DEVINL void gla_passC(const Params& p, char* smem, int item) {
;     ...
;   for (int i = 0; i < 16; ++i) {
;     const int t = 16 * w + i;
;     const float qv = (t < ci.T) ? bf2f(qraw[i]) : 0.f, kv = (t < ci.T) ? bf2f(kraw16[i]) : 0.f;
;     const float bt = bcum[i];
;     Qd[t * 72 + lane] = f2bf(qv * __expf(bt));
;     Ki[t * 72 + lane] = f2bf(kv * __expf(-bt));
;   }
;   __syncthreads();
;   {
;     f32x4 at[4];
; #pragma unroll
;     for (int nf = 0; nf < 4; ++nf) at[nf] = f32x4{0, 0, 0, 0};
; #pragma unroll
;     for (int ks = 0; ks < 2; ++ks) {
;       bf16x8 a = *(const bf16x8*)(Qd + (16 * w + (lane & 15)) * 72 + ks * 32 + 8 * (lane >> 4));
; #pragma unroll
;       for (int nf = 0; nf < 4; ++nf) {
;         bf16x8 b = *(const bf16x8*)(Ki + (nf * 16 + (lane & 15)) * 72 + ks * 32 + 8 * (lane >> 4));
;         at[nf] = mfma16(a, b, at[nf]);
;       }
;     }
; #pragma unroll
;     for (int nf = 0; nf < 4; ++nf)
; #pragma unroll
;       for (int j = 0; j < 4; ++j) {
;         int t = 16 * w + (lane >> 4) * 4 + j, s = nf * 16 + (lane & 15);
;         Att[t * 72 + s] = f2bf((s <= t) ? at[nf][j] : 0.f);
	v_lshlrev_b32_e32 v60, 16, v60
	v_cndmask_b32_e32 v66, 0, v66, vcc
	v_mul_f32_e32 v66, v66, v67
	v_add_u32_e32 v66, 0x8000, v66
	ds_write_b16_d16_hi v58, v66 offset:23024
	v_mul_f32_e32 v66, 0xbfb8aa3b, v157
	v_exp_f32_e32 v66, v66
	v_cndmask_b32_e32 v65, 0, v65, vcc
	v_mul_f32_e32 v67, 0x3fb8aa3b, v156
	v_exp_f32_e32 v67, v67
	v_mul_f32_e32 v65, v65, v66
	v_add_u32_e32 v65, 0x8000, v65
	ds_write_b16_d16_hi v58, v65 offset:32240
	v_or_b32_e32 v65, 9, v148
	v_cmp_lt_i32_e32 vcc, v65, v45
	v_lshlrev_b32_e32 v65, 16, v177
	v_lshlrev_b32_e32 v66, 16, v68
	v_cndmask_b32_e32 v65, 0, v65, vcc
	v_mul_f32_e32 v65, v65, v67
	v_add_u32_e32 v65, 0x8000, v65
	ds_write_b16_d16_hi v58, v65 offset:23168
	v_mul_f32_e32 v65, 0xbfb8aa3b, v156
	v_exp_f32_e32 v65, v65
	v_cndmask_b32_e32 v66, 0, v66, vcc
	v_mul_f32_e32 v67, 0x3fb8aa3b, v155
	v_exp_f32_e32 v67, v67
	v_mul_f32_e32 v65, v66, v65
	v_add_u32_e32 v65, 0x8000, v65
	ds_write_b16_d16_hi v58, v65 offset:32384
	v_or_b32_e32 v65, 10, v148
	v_cmp_lt_i32_e32 vcc, v65, v45
	v_lshlrev_b32_e32 v65, 16, v69
	v_lshlrev_b32_e32 v66, 16, v70
	v_cndmask_b32_e32 v65, 0, v65, vcc
	v_mul_f32_e32 v65, v65, v67
	v_add_u32_e32 v65, 0x8000, v65
	ds_write_b16_d16_hi v58, v65 offset:23312
	v_mul_f32_e32 v65, 0xbfb8aa3b, v155
	v_exp_f32_e32 v65, v65
	v_cndmask_b32_e32 v66, 0, v66, vcc
	s_waitcnt vmcnt(4)
	v_lshlrev_b32_e32 v59, 16, v59
	s_waitcnt vmcnt(2)
	v_lshlrev_b32_e32 v42, 16, v42
	v_mul_f32_e32 v65, v66, v65
	v_add_u32_e32 v65, 0x8000, v65
	ds_write_b16_d16_hi v58, v65 offset:32528
	v_or_b32_e32 v65, 11, v148
	v_cmp_lt_i32_e32 vcc, v65, v45
	v_mul_f32_e32 v65, 0x3fb8aa3b, v153
	v_exp_f32_e32 v65, v65
	v_cndmask_b32_e32 v64, 0, v64, vcc
	v_cndmask_b32_e32 v63, 0, v63, vcc
	v_lshlrev_b32_e32 v43, 16, v43
	v_mul_f32_e32 v64, v64, v65
	v_add_u32_e32 v64, 0x8000, v64
	ds_write_b16_d16_hi v58, v64 offset:23456
	v_mul_f32_e32 v64, 0xbfb8aa3b, v153
	v_exp_f32_e32 v64, v64
	s_waitcnt vmcnt(0)
	v_lshlrev_b32_e32 v40, 16, v40
	v_mul_f32_e32 v63, v63, v64
	v_add_u32_e32 v63, 0x8000, v63
	ds_write_b16_d16_hi v58, v63 offset:32672
	v_or_b32_e32 v63, 12, v148
	v_cmp_lt_i32_e32 vcc, v63, v45
	v_mul_f32_e32 v63, 0x3fb8aa3b, v151
	v_exp_f32_e32 v63, v63
	v_cndmask_b32_e32 v62, 0, v62, vcc
	v_cndmask_b32_e32 v61, 0, v61, vcc
	v_mul_f32_e32 v62, v62, v63
	v_add_u32_e32 v62, 0x8000, v62
	ds_write_b16_d16_hi v58, v62 offset:23600
	v_mul_f32_e32 v62, 0xbfb8aa3b, v151
	v_exp_f32_e32 v62, v62
	s_nop 0
	v_mul_f32_e32 v61, v61, v62
	v_add_u32_e32 v61, 0x8000, v61
	ds_write_b16_d16_hi v58, v61 offset:32816
	v_or_b32_e32 v61, 13, v148
	v_cmp_lt_i32_e32 vcc, v61, v45
	v_mul_f32_e32 v61, 0x3fb8aa3b, v150
	v_exp_f32_e32 v61, v61
	v_cndmask_b32_e32 v60, 0, v60, vcc
	v_cndmask_b32_e32 v59, 0, v59, vcc
	v_mul_f32_e32 v60, v60, v61
	v_add_u32_e32 v60, 0x8000, v60
	ds_write_b16_d16_hi v58, v60 offset:23744
	v_mul_f32_e32 v60, 0xbfb8aa3b, v150
	v_exp_f32_e32 v60, v60
	s_nop 0
	v_mul_f32_e32 v59, v59, v60
	v_add_u32_e32 v59, 0x8000, v59
	ds_write_b16_d16_hi v58, v59 offset:32960
	v_or_b32_e32 v59, 14, v148
	v_cmp_lt_i32_e32 vcc, v59, v45
	v_mul_f32_e32 v59, 0x3fb8aa3b, v39
	v_mul_f32_e32 v39, 0xbfb8aa3b, v39
	v_exp_f32_e32 v39, v39
	v_cndmask_b32_e32 v42, 0, v42, vcc
	v_cndmask_b32_e32 v43, 0, v43, vcc
	v_exp_f32_e32 v59, v59
	v_mul_f32_e32 v39, v42, v39
	v_add_u32_e32 v39, 0x8000, v39
	ds_write_b16_d16_hi v58, v39 offset:33104
	v_or_b32_e32 v39, 15, v148
	v_cmp_lt_i32_e32 vcc, v39, v45
	v_lshlrev_b32_e32 v39, 16, v41
	v_mul_f32_e32 v41, 0x3fb8aa3b, v37
	v_mul_f32_e32 v37, 0xbfb8aa3b, v37
	v_exp_f32_e32 v37, v37
	v_exp_f32_e32 v41, v41
	v_cndmask_b32_e32 v40, 0, v40, vcc
	v_cndmask_b32_e32 v39, 0, v39, vcc
	v_mul_f32_e32 v37, v40, v37
	v_mul_f32_e32 v39, v39, v41
	v_add_u32_e32 v37, 0x8000, v37
	v_mul_f32_e32 v43, v43, v59
	v_add_u32_e32 v39, 0x8000, v39
	ds_write_b16_d16_hi v58, v37 offset:33248
	v_or_b32_e32 v37, v148, v149
	v_add_u32_e32 v43, 0x8000, v43
	v_mad_u64_u32 v[74:75], s[0:1], v37, s34, v[38:39]
	ds_write_b16_d16_hi v58, v43 offset:23888
	ds_write_b16_d16_hi v58, v39 offset:24032
	s_waitcnt lgkmcnt(0)
	s_barrier
	ds_read_b128 v[40:43], v74 offset:22016
	v_mul_u32_u24_e32 v37, 0x48, v149
	v_lshl_add_u32 v150, v37, 1, v38
	ds_read_b128 v[58:61], v150 offset:31232
	ds_read_b128 v[62:65], v150 offset:33536
	ds_read_b128 v[66:69], v150 offset:35840
	ds_read_b128 v[70:73], v150 offset:38144
	s_waitcnt lgkmcnt(3)
	v_mfma_f32_16x16x32_bf16 v[58:61], v[40:43], v[58:61], 0
	v_or_b32_e32 v37, 16, v149
	s_waitcnt lgkmcnt(2)
	v_mfma_f32_16x16x32_bf16 v[62:65], v[40:43], v[62:65], 0
	s_waitcnt lgkmcnt(1)
	v_mfma_f32_16x16x32_bf16 v[66:69], v[40:43], v[66:69], 0
	s_waitcnt lgkmcnt(0)
	v_mfma_f32_16x16x32_bf16 v[38:41], v[40:43], v[70:73], 0
	ds_read_b128 v[70:73], v74 offset:22080
	ds_read_b128 v[74:77], v150 offset:31296
	v_or_b32_e32 v42, v148, v102
	v_cmp_le_i32_e32 vcc, v149, v42
	s_waitcnt lgkmcnt(0)
	v_mfma_f32_16x16x32_bf16 v[58:61], v[70:73], v[74:77], v[58:61]
	ds_read_b128 v[74:77], v150 offset:33600
	s_waitcnt lgkmcnt(0)
	v_mfma_f32_16x16x32_bf16 v[62:65], v[70:73], v[74:77], v[62:65]
	ds_read_b128 v[74:77], v150 offset:35904
	s_nop 3
	v_add_u32_e32 v43, 0x8000, v58
	v_lshrrev_b32_e32 v43, 16, v43
	v_mul_lo_u32 v58, v42, s34
	v_cndmask_b32_e32 v43, 0, v43, vcc
	v_or_b32_e32 v36, v58, v36
	s_waitcnt lgkmcnt(0)
; DEVINL u16 f2bf(float f) { return (u16)((__float_as_uint(f) + 0x8000u) >> 16); }
; DEVINL f32x4 mfma16(bf16x8 a, bf16x8 b, f32x4 c) { return __builtin_amdgcn_mfma_f32_16x16x32_bf16(a, b, c, 0, 0, 0); }
; DEVINL void gla_passC(const Params& p, char* smem, int item) {
;     ...
; #pragma unroll
;     for (int nf = 0; nf < 4; ++nf)
; #pragma unroll
;       for (int j = 0; j < 4; ++j) {
;         int t = 16 * w + (lane >> 4) * 4 + j, s = nf * 16 + (lane & 15);
;         Att[t * 72 + s] = f2bf((s <= t) ? at[nf][j] : 0.f);
;       }
;   }
;   __syncthreads();
;   f32x4 o[4][2];
; #pragma unroll
;   for (int a = 0; a < 4; ++a) { o[a][0] = f32x4{0, 0, 0, 0}; o[a][1] = f32x4{0, 0, 0, 0}; }
; #pragma unroll
;   for (int ks = 0; ks < 2; ++ks) {
;     const int kb = ks * 32 + 8 * (lane >> 4);
;     bf16x8 bv[2], bs[2];
; #pragma unroll
;     for (int nf = 0; nf < 2; ++nf) { bv[nf] = bvv[ks][nf]; bs[nf] = bss[ks][nf]; }
; #pragma unroll
;     for (int mf = 0; mf < 4; ++mf) {
;       bf16x8 aa = *(const bf16x8*)(Att + (mf * 16 + (lane & 15)) * 72 + kb);
;       bf16x8 aq = *(const bf16x8*)(Qd + (mf * 16 + (lane & 15)) * 72 + kb);
; #pragma unroll
;       for (int nf = 0; nf < 2; ++nf) {
;         o[mf][nf] = mfma16(aa, bv[nf], o[mf][nf]);
;         o[mf][nf] = mfma16(aq, bs[nf], o[mf][nf]);
;       }
;     }
;   }
	v_mfma_f32_16x16x32_bf16 v[66:69], v[70:73], v[74:77], v[66:69]
	ds_read_b128 v[74:77], v150 offset:38208
	ds_write_b16 v36, v43 offset:40448
	v_or_b32_e32 v43, 1, v42
	v_add_u32_e32 v58, 0x8000, v59
	v_lshrrev_b32_e32 v58, 16, v58
	v_cmp_le_i32_e32 vcc, v149, v43
	v_add_u32_e32 v59, 0x8000, v60
	v_lshrrev_b32_e32 v59, 16, v59
	v_cndmask_b32_e32 v58, 0, v58, vcc
	ds_write_b16 v36, v58 offset:40592
	v_or_b32_e32 v58, 2, v42
	v_cmp_le_i32_e32 vcc, v149, v58
	v_add_u32_e32 v60, 0x8000, v61
	v_lshrrev_b32_e32 v60, 16, v60
	v_cndmask_b32_e32 v59, 0, v59, vcc
	ds_write_b16 v36, v59 offset:40736
	v_or_b32_e32 v59, 3, v42
	v_cmp_le_i32_e32 vcc, v149, v59
	s_waitcnt lgkmcnt(3)
	v_mfma_f32_16x16x32_bf16 v[38:41], v[70:73], v[74:77], v[38:41]
	v_cmp_lt_u32_e64 s[34:35], v102, v45
	v_cndmask_b32_e32 v60, 0, v60, vcc
	ds_write_b16 v36, v60 offset:40880
	v_add_u32_e32 v60, 0x8000, v62
	v_lshrrev_b32_e32 v60, 16, v60
	v_cmp_le_i32_e32 vcc, v37, v42
	s_nop 1
	v_cndmask_b32_e32 v60, 0, v60, vcc
	ds_write_b16 v36, v60 offset:40480
	v_add_u32_e32 v60, 0x8000, v63
	v_lshrrev_b32_e32 v60, 16, v60
	v_cmp_le_i32_e32 vcc, v37, v43
	s_nop 1
	v_cndmask_b32_e32 v60, 0, v60, vcc
	ds_write_b16 v36, v60 offset:40624
	v_add_u32_e32 v60, 0x8000, v64
	v_lshrrev_b32_e32 v60, 16, v60
	v_cmp_le_i32_e32 vcc, v37, v58
	s_nop 1
	v_cndmask_b32_e32 v60, 0, v60, vcc
	ds_write_b16 v36, v60 offset:40768
	v_add_u32_e32 v60, 0x8000, v65
	v_lshrrev_b32_e32 v60, 16, v60
	v_cmp_le_i32_e32 vcc, v37, v59
	s_nop 1
	v_cndmask_b32_e32 v37, 0, v60, vcc
	ds_write_b16 v36, v37 offset:40912
	v_add_u32_e32 v37, 0x8000, v66
	v_lshrrev_b32_e32 v37, 16, v37
	v_cmp_le_i32_e32 vcc, v78, v42
	s_nop 1
	v_cndmask_b32_e32 v37, 0, v37, vcc
	ds_write_b16 v36, v37 offset:40512
	v_add_u32_e32 v37, 0x8000, v67
	v_lshrrev_b32_e32 v37, 16, v37
	v_cmp_le_i32_e32 vcc, v78, v43
	s_nop 1
	v_cndmask_b32_e32 v37, 0, v37, vcc
	ds_write_b16 v36, v37 offset:40656
	v_add_u32_e32 v37, 0x8000, v68
	v_lshrrev_b32_e32 v37, 16, v37
	v_cmp_le_i32_e32 vcc, v78, v58
	s_nop 1
	v_cndmask_b32_e32 v37, 0, v37, vcc
	ds_write_b16 v36, v37 offset:40800
	v_add_u32_e32 v37, 0x8000, v69
	v_lshrrev_b32_e32 v37, 16, v37
	v_cmp_le_i32_e32 vcc, v78, v59
	s_nop 1
	v_cndmask_b32_e32 v37, 0, v37, vcc
	ds_write_b16 v36, v37 offset:40944
	v_add_u32_e32 v37, 0x8000, v38
	v_lshrrev_b32_e32 v37, 16, v37
	v_cmp_le_i32_e32 vcc, v79, v42
	s_nop 1
	v_cndmask_b32_e32 v37, 0, v37, vcc
	ds_write_b16 v36, v37 offset:40544
	v_add_u32_e32 v37, 0x8000, v39
	v_lshrrev_b32_e32 v37, 16, v37
	v_cmp_le_i32_e32 vcc, v79, v43
	s_nop 1
	v_cndmask_b32_e32 v37, 0, v37, vcc
	ds_write_b16 v36, v37 offset:40688
	v_add_u32_e32 v37, 0x8000, v40
	v_lshrrev_b32_e32 v37, 16, v37
	v_cmp_le_i32_e32 vcc, v79, v58
	s_nop 1
	v_cndmask_b32_e32 v37, 0, v37, vcc
	ds_write_b16 v36, v37 offset:40832
	v_add_u32_e32 v37, 0x8000, v41
	v_lshrrev_b32_e32 v37, 16, v37
	v_cmp_le_i32_e32 vcc, v79, v59
	s_nop 1
	v_cndmask_b32_e32 v37, 0, v37, vcc
	ds_write_b16 v36, v37 offset:40976
	s_waitcnt lgkmcnt(0)
	s_barrier
	ds_read_b128 v[36:39], v150 offset:40448
	ds_read_b128 v[40:43], v150 offset:22016
	s_waitcnt lgkmcnt(1)
	v_mfma_f32_16x16x32_bf16 v[58:61], v[36:39], v[20:23], 0
	v_mfma_f32_16x16x32_bf16 v[36:39], v[36:39], v[28:31], 0
	s_waitcnt lgkmcnt(0)
	v_mfma_f32_16x16x32_bf16 v[58:61], v[40:43], v[24:27], v[58:61]
	v_mfma_f32_16x16x32_bf16 v[36:39], v[40:43], v[32:35], v[36:39]
	ds_read_b128 v[40:43], v150 offset:42752
	ds_read_b128 v[62:65], v150 offset:24320
	s_waitcnt lgkmcnt(1)
	v_mfma_f32_16x16x32_bf16 v[66:69], v[40:43], v[20:23], 0
	v_mfma_f32_16x16x32_bf16 v[40:43], v[40:43], v[28:31], 0
	s_waitcnt lgkmcnt(0)
	v_mfma_f32_16x16x32_bf16 v[66:69], v[62:65], v[24:27], v[66:69]
	v_mfma_f32_16x16x32_bf16 v[62:65], v[62:65], v[32:35], v[40:43]
	s_nop 4
	ds_read_b128 v[40:43], v150 offset:45056
	ds_read_b128 v[70:73], v150 offset:26624
	s_waitcnt lgkmcnt(1)
	v_mfma_f32_16x16x32_bf16 v[74:77], v[40:43], v[20:23], 0
	v_mfma_f32_16x16x32_bf16 v[40:43], v[40:43], v[28:31], 0
	s_waitcnt lgkmcnt(0)
	v_mfma_f32_16x16x32_bf16 v[74:77], v[70:73], v[24:27], v[74:77]
	v_mfma_f32_16x16x32_bf16 v[70:73], v[70:73], v[32:35], v[40:43]
	s_nop 4
	ds_read_b128 v[40:43], v150 offset:47360
	ds_read_b128 v[78:81], v150 offset:28928
	s_waitcnt lgkmcnt(1)
	v_mfma_f32_16x16x32_bf16 v[20:23], v[40:43], v[20:23], 0
	s_waitcnt lgkmcnt(0)
	v_mfma_f32_16x16x32_bf16 v[82:85], v[78:81], v[24:27], v[20:23]
	v_mfma_f32_16x16x32_bf16 v[20:23], v[40:43], v[28:31], 0
	v_mfma_f32_16x16x32_bf16 v[78:81], v[78:81], v[32:35], v[20:23]
	s_nop 6
	ds_read_b128 v[20:23], v150 offset:40512
	ds_read_b128 v[24:27], v150 offset:22080
	s_waitcnt lgkmcnt(1)
	v_mfma_f32_16x16x32_bf16 v[28:31], v[20:23], v[4:7], v[58:61]
	v_mfma_f32_16x16x32_bf16 v[20:23], v[20:23], v[16:19], v[36:39]
	s_waitcnt lgkmcnt(0)
	v_mfma_f32_16x16x32_bf16 v[40:43], v[24:27], v[8:11], v[28:31]
	v_mfma_f32_16x16x32_bf16 v[36:39], v[24:27], v[12:15], v[20:23]
	s_nop 4
	ds_read_b128 v[20:23], v150 offset:42816
	ds_read_b128 v[24:27], v150 offset:24384
	s_waitcnt lgkmcnt(1)
	v_mfma_f32_16x16x32_bf16 v[28:31], v[20:23], v[4:7], v[66:69]
	v_mfma_f32_16x16x32_bf16 v[20:23], v[20:23], v[16:19], v[62:65]
	s_waitcnt lgkmcnt(0)
	v_mfma_f32_16x16x32_bf16 v[32:35], v[24:27], v[8:11], v[28:31]
	v_mfma_f32_16x16x32_bf16 v[28:31], v[24:27], v[12:15], v[20:23]
	s_nop 4
	ds_read_b128 v[20:23], v150 offset:45120
	ds_read_b128 v[58:61], v150 offset:26688
	s_waitcnt lgkmcnt(1)
	v_mfma_f32_16x16x32_bf16 v[24:27], v[20:23], v[4:7], v[74:77]
	v_mfma_f32_16x16x32_bf16 v[20:23], v[20:23], v[16:19], v[70:73]
	s_waitcnt lgkmcnt(0)
; DEVINL f32x4 mfma16(bf16x8 a, bf16x8 b, f32x4 c) { return __builtin_amdgcn_mfma_f32_16x16x32_bf16(a, b, c, 0, 0, 0); }
; DEVINL void gla_passC(const Params& p, char* smem, int item) {
;     ...
;     for (int mf = 0; mf < 4; ++mf) {
;       bf16x8 aa = *(const bf16x8*)(Att + (mf * 16 + (lane & 15)) * 72 + kb);
;       bf16x8 aq = *(const bf16x8*)(Qd + (mf * 16 + (lane & 15)) * 72 + kb);
; #pragma unroll
;       for (int nf = 0; nf < 2; ++nf) {
;         o[mf][nf] = mfma16(aa, bv[nf], o[mf][nf]);
;         o[mf][nf] = mfma16(aq, bs[nf], o[mf][nf]);
;       }
;     }
;   }
; #pragma unroll
;   for (int mf = 0; mf < 4; ++mf)
; #pragma unroll
;     for (int j = 0; j < 4; ++j) {
;       const float s = red16(o[mf][0][j] * o[mf][0][j] + o[mf][1][j] * o[mf][1][j]);
;       red[w * 64 + mf * 16 + (lane >> 4) * 4 + j] = s;
;     }
	v_mfma_f32_16x16x32_bf16 v[24:27], v[58:61], v[8:11], v[24:27]
	v_mfma_f32_16x16x32_bf16 v[20:23], v[58:61], v[12:15], v[20:23]
	ds_read_b128 v[58:61], v150 offset:47424
	ds_read_b128 v[62:65], v150 offset:28992
	s_waitcnt lgkmcnt(1)
	v_mfma_f32_16x16x32_bf16 v[4:7], v[58:61], v[4:7], v[82:85]
	s_waitcnt lgkmcnt(0)
	v_mfma_f32_16x16x32_bf16 v[8:11], v[62:65], v[8:11], v[4:7]
	v_mfma_f32_16x16x32_bf16 v[4:7], v[58:61], v[16:19], v[78:81]
	v_mul_f32_e64 v16, v36, v36
	v_mul_f32_e64 v17, v37, v37
	v_pk_fma_f32 v[16:17], v[40:41], v[40:41], v[16:17]
	v_mfma_f32_16x16x32_bf16 v[4:7], v[62:65], v[12:15], v[4:7]
	v_and_b32_e32 v12, 0x3fffffc0, v143
	v_mov_b32_dpp v18, v16 quad_perm:[1,0,3,2] row_mask:0xf bank_mask:0xf bound_ctrl:1
	v_mov_b32_dpp v19, v17 quad_perm:[1,0,3,2] row_mask:0xf bank_mask:0xf bound_ctrl:1
	v_pk_add_f32 v[16:17], v[16:17], v[18:19]
	v_lshlrev_b32_e32 v15, 2, v102
	v_lshl_or_b32 v14, v12, 2, v15
	v_mov_b32_dpp v18, v16 quad_perm:[2,3,0,1] row_mask:0xf bank_mask:0xf bound_ctrl:1
	v_mov_b32_dpp v19, v17 quad_perm:[2,3,0,1] row_mask:0xf bank_mask:0xf bound_ctrl:1
	v_pk_add_f32 v[16:17], v[16:17], v[18:19]
	v_pk_mul_f32 v[12:13], v[38:39], v[38:39]
	s_nop 0
	v_mov_b32_dpp v18, v16 row_half_mirror row_mask:0xf bank_mask:0xf bound_ctrl:1
	v_mov_b32_dpp v19, v17 row_half_mirror row_mask:0xf bank_mask:0xf bound_ctrl:1
	v_pk_add_f32 v[16:17], v[16:17], v[18:19]
	v_pk_fma_f32 v[12:13], v[42:43], v[42:43], v[12:13]
	s_nop 0
	v_mov_b32_dpp v18, v16 row_mirror row_mask:0xf bank_mask:0xf bound_ctrl:1
	v_mov_b32_dpp v19, v17 row_mirror row_mask:0xf bank_mask:0xf bound_ctrl:1
	v_pk_add_f32 v[16:17], v[16:17], v[18:19]
	v_mov_b32_dpp v18, v12 quad_perm:[1,0,3,2] row_mask:0xf bank_mask:0xf bound_ctrl:1
	v_mov_b32_dpp v19, v13 quad_perm:[1,0,3,2] row_mask:0xf bank_mask:0xf bound_ctrl:1
	v_pk_add_f32 v[12:13], v[12:13], v[18:19]
	s_nop 1
	v_mov_b32_dpp v18, v12 quad_perm:[2,3,0,1] row_mask:0xf bank_mask:0xf bound_ctrl:1
	v_mov_b32_dpp v19, v13 quad_perm:[2,3,0,1] row_mask:0xf bank_mask:0xf bound_ctrl:1
	v_pk_add_f32 v[12:13], v[12:13], v[18:19]
	s_nop 1
	v_mov_b32_dpp v18, v12 row_half_mirror row_mask:0xf bank_mask:0xf bound_ctrl:1
	v_mov_b32_dpp v19, v13 row_half_mirror row_mask:0xf bank_mask:0xf bound_ctrl:1
	v_pk_add_f32 v[12:13], v[12:13], v[18:19]
	s_nop 1
	v_mov_b32_dpp v18, v12 row_mirror row_mask:0xf bank_mask:0xf bound_ctrl:1
	v_mov_b32_dpp v19, v13 row_mirror row_mask:0xf bank_mask:0xf bound_ctrl:1
	v_pk_add_f32 v[18:19], v[12:13], v[18:19]
	ds_write_b128 v14, v[16:19] offset:49664
	v_pk_mul_f32 v[16:17], v[28:29], v[28:29]
	v_pk_mul_f32 v[12:13], v[30:31], v[30:31]
	v_pk_fma_f32 v[16:17], v[32:33], v[32:33], v[16:17]
	v_pk_fma_f32 v[12:13], v[34:35], v[34:35], v[12:13]
	s_nop 0
	v_mov_b32_dpp v18, v16 quad_perm:[1,0,3,2] row_mask:0xf bank_mask:0xf bound_ctrl:1
	v_mov_b32_dpp v19, v17 quad_perm:[1,0,3,2] row_mask:0xf bank_mask:0xf bound_ctrl:1
	v_pk_add_f32 v[16:17], v[16:17], v[18:19]
	s_nop 1
	v_mov_b32_dpp v18, v16 quad_perm:[2,3,0,1] row_mask:0xf bank_mask:0xf bound_ctrl:1
	v_mov_b32_dpp v19, v17 quad_perm:[2,3,0,1] row_mask:0xf bank_mask:0xf bound_ctrl:1
	v_pk_add_f32 v[16:17], v[16:17], v[18:19]
	s_nop 1
	v_mov_b32_dpp v18, v16 row_half_mirror row_mask:0xf bank_mask:0xf bound_ctrl:1
	v_mov_b32_dpp v19, v17 row_half_mirror row_mask:0xf bank_mask:0xf bound_ctrl:1
	v_pk_add_f32 v[16:17], v[16:17], v[18:19]
	s_nop 1
	v_mov_b32_dpp v18, v16 row_mirror row_mask:0xf bank_mask:0xf bound_ctrl:1
	v_mov_b32_dpp v19, v17 row_mirror row_mask:0xf bank_mask:0xf bound_ctrl:1
	v_pk_add_f32 v[16:17], v[16:17], v[18:19]
	v_mov_b32_dpp v18, v12 quad_perm:[1,0,3,2] row_mask:0xf bank_mask:0xf bound_ctrl:1
	v_mov_b32_dpp v19, v13 quad_perm:[1,0,3,2] row_mask:0xf bank_mask:0xf bound_ctrl:1
	v_pk_add_f32 v[12:13], v[12:13], v[18:19]
	s_nop 1
	v_mov_b32_dpp v18, v12 quad_perm:[2,3,0,1] row_mask:0xf bank_mask:0xf bound_ctrl:1
	v_mov_b32_dpp v19, v13 quad_perm:[2,3,0,1] row_mask:0xf bank_mask:0xf bound_ctrl:1
	v_pk_add_f32 v[12:13], v[12:13], v[18:19]
	s_nop 1
	v_mov_b32_dpp v18, v12 row_half_mirror row_mask:0xf bank_mask:0xf bound_ctrl:1
	v_mov_b32_dpp v19, v13 row_half_mirror row_mask:0xf bank_mask:0xf bound_ctrl:1
	v_pk_add_f32 v[12:13], v[12:13], v[18:19]
	s_nop 1
	v_mov_b32_dpp v18, v12 row_mirror row_mask:0xf bank_mask:0xf bound_ctrl:1
	v_mov_b32_dpp v19, v13 row_mirror row_mask:0xf bank_mask:0xf bound_ctrl:1
	v_pk_add_f32 v[18:19], v[12:13], v[18:19]
	ds_write_b128 v14, v[16:19] offset:49728
	v_pk_mul_f32 v[16:17], v[20:21], v[20:21]
	v_pk_mul_f32 v[12:13], v[22:23], v[22:23]
	v_pk_fma_f32 v[16:17], v[24:25], v[24:25], v[16:17]
	v_pk_fma_f32 v[12:13], v[26:27], v[26:27], v[12:13]
	s_nop 0
	v_mov_b32_dpp v18, v16 quad_perm:[1,0,3,2] row_mask:0xf bank_mask:0xf bound_ctrl:1
	v_mov_b32_dpp v19, v17 quad_perm:[1,0,3,2] row_mask:0xf bank_mask:0xf bound_ctrl:1
	v_pk_add_f32 v[16:17], v[16:17], v[18:19]
	s_nop 1
	v_mov_b32_dpp v18, v16 quad_perm:[2,3,0,1] row_mask:0xf bank_mask:0xf bound_ctrl:1
	v_mov_b32_dpp v19, v17 quad_perm:[2,3,0,1] row_mask:0xf bank_mask:0xf bound_ctrl:1
	v_pk_add_f32 v[16:17], v[16:17], v[18:19]
	s_nop 1
	v_mov_b32_dpp v18, v16 row_half_mirror row_mask:0xf bank_mask:0xf bound_ctrl:1
	v_mov_b32_dpp v19, v17 row_half_mirror row_mask:0xf bank_mask:0xf bound_ctrl:1
	v_pk_add_f32 v[16:17], v[16:17], v[18:19]
	s_nop 1
	v_mov_b32_dpp v18, v16 row_mirror row_mask:0xf bank_mask:0xf bound_ctrl:1
	v_mov_b32_dpp v19, v17 row_mirror row_mask:0xf bank_mask:0xf bound_ctrl:1
	v_pk_add_f32 v[16:17], v[16:17], v[18:19]
	v_mov_b32_dpp v18, v12 quad_perm:[1,0,3,2] row_mask:0xf bank_mask:0xf bound_ctrl:1
	v_mov_b32_dpp v19, v13 quad_perm:[1,0,3,2] row_mask:0xf bank_mask:0xf bound_ctrl:1
; DEVINL void gla_passC(const Params& p, char* smem, int item) {
;     ...
; #pragma unroll
;   for (int mf = 0; mf < 4; ++mf)
; #pragma unroll
;     for (int j = 0; j < 4; ++j) {
;       const float s = red16(o[mf][0][j] * o[mf][0][j] + o[mf][1][j] * o[mf][1][j]);
;       red[w * 64 + mf * 16 + (lane >> 4) * 4 + j] = s;
;     }
;   __syncthreads();
;   u16* mixin = (u16*)(p.ws + OFF_MIXIN);
;   float gn[2];
; #pragma unroll
;   for (int nf = 0; nf < 2; ++nf) gn[nf] = p.gla_norm[32 * w + nf * 16 + (lane & 15)];
; #pragma unroll
;   for (int mf = 0; mf < 4; ++mf) {
;     const int t0 = mf * 16 + (lane >> 4) * 4;
;     if (t0 < ci.T) {
	v_pk_add_f32 v[12:13], v[12:13], v[18:19]
	s_nop 1
	v_mov_b32_dpp v18, v12 quad_perm:[2,3,0,1] row_mask:0xf bank_mask:0xf bound_ctrl:1
	v_mov_b32_dpp v19, v13 quad_perm:[2,3,0,1] row_mask:0xf bank_mask:0xf bound_ctrl:1
	v_pk_add_f32 v[12:13], v[12:13], v[18:19]
	s_nop 1
	v_mov_b32_dpp v18, v12 row_half_mirror row_mask:0xf bank_mask:0xf bound_ctrl:1
	v_mov_b32_dpp v19, v13 row_half_mirror row_mask:0xf bank_mask:0xf bound_ctrl:1
	v_pk_add_f32 v[12:13], v[12:13], v[18:19]
	s_nop 1
	v_mov_b32_dpp v18, v12 row_mirror row_mask:0xf bank_mask:0xf bound_ctrl:1
	v_mov_b32_dpp v19, v13 row_mirror row_mask:0xf bank_mask:0xf bound_ctrl:1
	v_pk_add_f32 v[18:19], v[12:13], v[18:19]
	ds_write_b128 v14, v[16:19] offset:49792
	v_pk_mul_f32 v[16:17], v[4:5], v[4:5]
	v_pk_mul_f32 v[12:13], v[6:7], v[6:7]
	v_pk_fma_f32 v[16:17], v[8:9], v[8:9], v[16:17]
	v_pk_fma_f32 v[12:13], v[10:11], v[10:11], v[12:13]
	s_nop 0
	v_mov_b32_dpp v18, v16 quad_perm:[1,0,3,2] row_mask:0xf bank_mask:0xf bound_ctrl:1
	v_mov_b32_dpp v19, v17 quad_perm:[1,0,3,2] row_mask:0xf bank_mask:0xf bound_ctrl:1
	v_pk_add_f32 v[16:17], v[16:17], v[18:19]
	s_nop 1
	v_mov_b32_dpp v18, v16 quad_perm:[2,3,0,1] row_mask:0xf bank_mask:0xf bound_ctrl:1
	v_mov_b32_dpp v19, v17 quad_perm:[2,3,0,1] row_mask:0xf bank_mask:0xf bound_ctrl:1
	v_pk_add_f32 v[16:17], v[16:17], v[18:19]
	s_nop 1
	v_mov_b32_dpp v18, v16 row_half_mirror row_mask:0xf bank_mask:0xf bound_ctrl:1
	v_mov_b32_dpp v19, v17 row_half_mirror row_mask:0xf bank_mask:0xf bound_ctrl:1
	v_pk_add_f32 v[16:17], v[16:17], v[18:19]
	s_nop 1
	v_mov_b32_dpp v18, v16 row_mirror row_mask:0xf bank_mask:0xf bound_ctrl:1
	v_mov_b32_dpp v19, v17 row_mirror row_mask:0xf bank_mask:0xf bound_ctrl:1
	v_pk_add_f32 v[16:17], v[16:17], v[18:19]
	v_mov_b32_dpp v18, v12 quad_perm:[1,0,3,2] row_mask:0xf bank_mask:0xf bound_ctrl:1
	v_mov_b32_dpp v19, v13 quad_perm:[1,0,3,2] row_mask:0xf bank_mask:0xf bound_ctrl:1
	v_pk_add_f32 v[12:13], v[12:13], v[18:19]
	s_nop 1
	v_mov_b32_dpp v18, v12 quad_perm:[2,3,0,1] row_mask:0xf bank_mask:0xf bound_ctrl:1
	v_mov_b32_dpp v19, v13 quad_perm:[2,3,0,1] row_mask:0xf bank_mask:0xf bound_ctrl:1
	v_pk_add_f32 v[12:13], v[12:13], v[18:19]
	s_nop 1
	v_mov_b32_dpp v18, v12 row_half_mirror row_mask:0xf bank_mask:0xf bound_ctrl:1
	v_mov_b32_dpp v19, v13 row_half_mirror row_mask:0xf bank_mask:0xf bound_ctrl:1
	v_pk_add_f32 v[12:13], v[12:13], v[18:19]
	s_nop 1
	v_mov_b32_dpp v18, v12 row_mirror row_mask:0xf bank_mask:0xf bound_ctrl:1
	v_mov_b32_dpp v19, v13 row_mirror row_mask:0xf bank_mask:0xf bound_ctrl:1
	v_pk_add_f32 v[18:19], v[12:13], v[18:19]
	v_lshl_add_u64 v[12:13], v[56:57], 2, s[72:73]
	ds_write_b128 v14, v[16:19] offset:49856
	s_waitcnt lgkmcnt(0)
	s_barrier
	global_load_dword v16, v[12:13], off
	global_load_dword v14, v[12:13], off offset:64
	v_and_or_b32 v12, v143, 14, v52
	v_add_u32_e32 v12, v12, v54
	v_and_b32_e32 v13, 1, v143
	v_cmp_eq_u32_e32 vcc, 0, v13
	v_lshl_add_u32 v17, v13, 1, v50
	v_ashrrev_i32_e32 v13, 31, v12
	s_and_saveexec_b64 s[44:45], s[34:35]
	s_cbranch_execz .LBB0_439
; DEVINL float bf2f(u16 h) { return __uint_as_float(((unsigned)h) << 16); }
; DEVINL float siluf_(float x) { return x * __builtin_amdgcn_rcpf(1.f + __expf(-x)); }
; DEVINL void gla_passC(const Params& p, char* smem, int item) {
;     ...
;   for (int mf = 0; mf < 4; ++mf) {
;     const int t0 = mf * 16 + (lane >> 4) * 4;
;     if (t0 < ci.T) {
;       float rs[4];
; #pragma unroll
;       for (int j = 0; j < 4; ++j) {
;         const int t = t0 + j;
;         rs[j] = rsqrtf((red[t] + red[64 + t] + red[128 + t] + red[192 + t]) * (1.f / 128.f) + EPS);
;       }
; #pragma unroll
;       for (int nf = 0; nf < 2; ++nf) {
;         const int dv = 32 * w + nf * 16 + (lane & 15);
;         float o4[4];
; #pragma unroll
;         for (int j = 0; j < 4; ++j) {
;           float gv = bf2f(graw[mf][nf][j]);
;           o4[j] = o[mf][nf][j] * rs[j] * gn[nf] * siluf_(gv);
;         }
;         store_pairs(mixin, 1024, ci.r0 + t0, ci.h * 128 + dv, o4[0], o4[1], o4[2], o4[3]);
;       }
	ds_read_b128 v[56:59], v15 offset:49664
	ds_read_b128 v[60:63], v15 offset:49920
	ds_read_b128 v[64:67], v15 offset:50176
	ds_read_b128 v[68:71], v15 offset:50432
	s_mov_b32 s0, 0x358637bd
	s_waitcnt lgkmcnt(2)
	v_pk_add_f32 v[18:19], v[56:57], v[60:61]
	s_waitcnt lgkmcnt(1)
	v_pk_add_f32 v[18:19], v[18:19], v[64:65]
	v_mov_b64_e32 v[56:57], s[0:1]
	s_waitcnt lgkmcnt(0)
	v_pk_add_f32 v[18:19], v[18:19], v[68:69]
	s_brev_b32 s0, 60
	v_pk_fma_f32 v[18:19], v[18:19], s[0:1], v[56:57] op_sel_hi:[1,0,0]
	s_nop 0
	v_mul_f32_e32 v50, 0x4b800000, v18
	v_cmp_gt_f32_e64 s[36:37], s33, v18
	v_cmp_gt_f32_e64 s[34:35], s33, v19
	s_nop 0
	v_cndmask_b32_e64 v18, v18, v50, s[36:37]
	v_rsq_f32_e32 v18, v18
	s_nop 0
	v_mul_f32_e32 v50, 0x45800000, v18
	v_cndmask_b32_e64 v50, v18, v50, s[36:37]
	v_mul_f32_e32 v18, 0x4b800000, v19
	v_cndmask_b32_e64 v18, v19, v18, s[34:35]
	v_rsq_f32_e32 v18, v18
	v_mul_f32_e32 v40, v40, v50
	s_waitcnt vmcnt(1)
	v_mul_f32_e32 v40, v16, v40
	v_mul_f32_e32 v36, v36, v50
	v_mul_f32_e32 v19, 0x45800000, v18
	v_cndmask_b32_e64 v52, v18, v19, s[34:35]
	v_pk_add_f32 v[18:19], v[58:59], v[62:63]
	v_mul_f32_e32 v41, v41, v52
	v_pk_add_f32 v[18:19], v[18:19], v[66:67]
	v_mul_f32_e32 v41, v16, v41
	v_pk_add_f32 v[18:19], v[18:19], v[70:71]
	s_waitcnt vmcnt(0)
	v_mul_f32_e32 v36, v14, v36
	v_pk_fma_f32 v[18:19], v[18:19], s[0:1], v[56:57] op_sel_hi:[1,0,0]
	v_lshlrev_b32_e32 v57, 16, v147
	v_mul_f32_e32 v58, 0xbfb8aa3b, v57
	v_exp_f32_e32 v58, v58
	v_mul_f32_e32 v54, 0x4b800000, v18
	v_cmp_gt_f32_e64 s[36:37], s33, v18
	v_cmp_gt_f32_e64 s[34:35], s33, v19
	v_add_f32_e32 v58, 1.0, v58
	v_rcp_f32_e32 v58, v58
	v_cndmask_b32_e64 v18, v18, v54, s[36:37]
	v_rsq_f32_e32 v18, v18
	v_readlane_b32 s0, v194, 19
	v_mul_f32_e32 v57, v58, v57
	v_mul_f32_e32 v40, v57, v40
	v_lshlrev_b32_e32 v57, 16, v146
	v_mul_f32_e32 v58, 0xbfb8aa3b, v57
	v_exp_f32_e32 v58, v58
	v_mul_f32_e32 v54, 0x45800000, v18
	v_cndmask_b32_e64 v54, v18, v54, s[36:37]
	v_mul_f32_e32 v42, v42, v54
	v_add_f32_e32 v58, 1.0, v58
	v_rcp_f32_e32 v58, v58
	v_mul_f32_e32 v42, v16, v42
	v_mul_f32_e32 v18, 0x4b800000, v19
	v_cndmask_b32_e64 v18, v19, v18, s[34:35]
	v_mul_f32_e32 v57, v58, v57
	v_mul_f32_e32 v41, v57, v41
	v_lshlrev_b32_e32 v57, 16, v145
	v_mul_f32_e32 v58, 0xbfb8aa3b, v57
	v_exp_f32_e32 v58, v58
	v_rsq_f32_e32 v18, v18
	v_readlane_b32 s1, v194, 20
	v_mul_f32_e32 v37, v37, v52
	v_add_f32_e32 v58, 1.0, v58
	v_rcp_f32_e32 v58, v58
	v_mul_f32_e32 v19, 0x45800000, v18
	v_cndmask_b32_e64 v56, v18, v19, s[34:35]
	v_mul_f32_e32 v43, v43, v56
	v_mul_f32_e32 v57, v58, v57
	v_mul_f32_e32 v42, v57, v42
	v_lshlrev_b32_e32 v57, 16, v144
	v_mul_f32_e32 v58, 0xbfb8aa3b, v57
	v_exp_f32_e32 v58, v58
	v_mul_f32_e32 v43, v16, v43
	v_add_u32_e32 v18, v17, v102
	v_mov_b32_dpp v59, v42 quad_perm:[1,0,3,2] row_mask:0xf bank_mask:0xf bound_ctrl:1
	v_add_f32_e32 v58, 1.0, v58
	v_rcp_f32_e32 v58, v58
	v_ashrrev_i32_e32 v19, 31, v18
	v_lshlrev_b64 v[18:19], 11, v[18:19]
	v_lshl_add_u64 v[18:19], s[0:1], 0, v[18:19]
	v_mul_f32_e32 v57, v58, v57
	v_mul_f32_e32 v43, v57, v43
	v_mov_b32_dpp v58, v41 quad_perm:[1,0,3,2] row_mask:0xf bank_mask:0xf bound_ctrl:1
	v_mov_b32_dpp v57, v40 quad_perm:[1,0,3,2] row_mask:0xf bank_mask:0xf bound_ctrl:1
	v_cndmask_b32_e32 v42, v42, v57, vcc
	v_cndmask_b32_e32 v40, v59, v40, vcc
	v_mov_b32_dpp v60, v43 quad_perm:[1,0,3,2] row_mask:0xf bank_mask:0xf bound_ctrl:1
	v_add_u32_e32 v42, 0x8000, v42
	v_add_u32_e32 v40, 0x8000, v40
	v_perm_b32 v40, v42, v40, s25
	v_cndmask_b32_e32 v42, v43, v58, vcc
	v_cndmask_b32_e32 v41, v60, v41, vcc
	v_add_u32_e32 v42, 0x8000, v42
	v_add_u32_e32 v41, 0x8000, v41
	v_lshl_add_u64 v[18:19], v[12:13], 1, v[18:19]
	v_perm_b32 v41, v42, v41, s25
	global_store_dword v[18:19], v40, off
	global_store_dword v[18:19], v41, off offset:2048
	v_lshlrev_b32_e32 v40, 16, v142
	v_mul_f32_e32 v41, 0xbfb8aa3b, v40
	v_exp_f32_e32 v41, v41
	v_mul_f32_e32 v37, v14, v37
	v_mul_f32_e32 v38, v38, v54
	v_mul_f32_e32 v38, v14, v38
	v_add_f32_e32 v41, 1.0, v41
	v_rcp_f32_e32 v41, v41
	v_mul_f32_e32 v39, v39, v56
	v_mul_f32_e32 v39, v14, v39
	v_mul_f32_e32 v40, v41, v40
	v_mul_f32_e32 v36, v40, v36
	v_lshlrev_b32_e32 v40, 16, v141
	v_mul_f32_e32 v41, 0xbfb8aa3b, v40
	v_exp_f32_e32 v41, v41
	s_nop 0
	v_add_f32_e32 v41, 1.0, v41
	v_rcp_f32_e32 v41, v41
	s_nop 0
	v_mul_f32_e32 v40, v41, v40
	v_mul_f32_e32 v37, v40, v37
	v_lshlrev_b32_e32 v40, 16, v140
	v_mul_f32_e32 v41, 0xbfb8aa3b, v40
	v_exp_f32_e32 v41, v41
	s_nop 0
	v_add_f32_e32 v41, 1.0, v41
	v_rcp_f32_e32 v41, v41
	s_nop 0
	v_mul_f32_e32 v40, v41, v40
	v_mul_f32_e32 v38, v40, v38
	v_lshlrev_b32_e32 v40, 16, v139
	v_mul_f32_e32 v41, 0xbfb8aa3b, v40
	v_exp_f32_e32 v41, v41
	v_mov_b32_dpp v42, v38 quad_perm:[1,0,3,2] row_mask:0xf bank_mask:0xf bound_ctrl:1
	v_add_f32_e32 v41, 1.0, v41
	v_rcp_f32_e32 v41, v41
	s_nop 0
	v_mul_f32_e32 v40, v41, v40
	v_mul_f32_e32 v39, v40, v39
	s_nop 0
	v_mov_b32_dpp v40, v36 quad_perm:[1,0,3,2] row_mask:0xf bank_mask:0xf bound_ctrl:1
	v_cndmask_b32_e32 v38, v38, v40, vcc
	v_cndmask_b32_e32 v36, v42, v36, vcc
	v_mov_b32_dpp v41, v37 quad_perm:[1,0,3,2] row_mask:0xf bank_mask:0xf bound_ctrl:1
	v_mov_b32_dpp v43, v39 quad_perm:[1,0,3,2] row_mask:0xf bank_mask:0xf bound_ctrl:1
	v_add_u32_e32 v38, 0x8000, v38
	v_add_u32_e32 v36, 0x8000, v36
	v_perm_b32 v36, v38, v36, s25
	v_cndmask_b32_e32 v38, v39, v41, vcc
	v_cndmask_b32_e32 v37, v43, v37, vcc
	v_add_u32_e32 v38, 0x8000, v38
	v_add_u32_e32 v37, 0x8000, v37
	v_perm_b32 v37, v38, v37, s25
	global_store_dword v[18:19], v36, off offset:32
	global_store_dword v[18:19], v37, off offset:2080

; DEVINL ChunkInfo chunk_info(int item) {
;   ChunkInfo ci;
;   if (item < NCH_P) {
;     int bh = item / 33, c = item - bh * 33, b = bh >> 2;
;     ci.h = bh & 3;
;     if (c == 0) { ci.r0 = b * LP; ci.T = 16; }
;     else { ci.r0 = b * LP + 16 + 64 * (c - 1); ci.T = 64; }
;   } else {
;     int bh = item - NCH_P, b = bh >> 2;
;     ci.h = bh & 3; ci.r0 = MPROMPT + 8 * b; ci.T = 8;
;   }
;   return ci;
; }
; DEVINL void run_phase(const Params& p, char* smem, int ph) {
;     ...
;       for (int it = bid; it < NCH + S5A_BLK; it += nb) {
;         if (it < S5A_BLK) { __syncthreads(); s5_passA(p, smem, it); }
;         else gla_passA(p, smem, it - S5A_BLK);
.LBB0_539:
	s_or_b64 exec, exec, s[38:39]
	v_add_u32_e32 v64, v64, v104
	s_movk_i32 s0, 0x7df
	v_cmp_lt_i32_e32 vcc, s0, v64
	s_or_b64 s[66:67], vcc, s[66:67]
	s_andn2_b64 exec, exec, s[66:67]
	s_cbranch_execz .LBB0_737
.LBB0_540:
	s_movk_i32 s0, 0x1bf
	v_cmp_lt_i32_e32 vcc, s0, v64
	s_and_saveexec_b64 s[0:1], vcc
	s_xor_b64 s[90:91], exec, s[0:1]
	s_cbranch_execz .LBB0_710
	v_add_u32_e32 v66, 0xfffffe40, v64
	s_movk_i32 s0, 0x41f
	v_cmp_lt_u32_e32 vcc, s0, v66
	s_and_saveexec_b64 s[0:1], vcc
	s_xor_b64 s[0:1], exec, s[0:1]
	s_cbranch_execz .LBB0_543
	v_lshlrev_b32_e32 v1, 1, v66
	v_and_b32_e32 v1, 0xff8, v1
	s_nop 0
	v_add_u32_e32 v52, 0x3840, v1
.LBB0_543:
	s_or_saveexec_b64 s[0:1], s[0:1]
	v_mov_b32_e32 v72, 8
	v_mov_b32_e32 v1, v66
	s_xor_b64 exec, exec, s[0:1]
	s_cbranch_execz .LBB0_545
	v_mul_u32_u24_e32 v3, 0xf83f, v66
	v_lshrrev_b32_e32 v1, 21, v3
	s_movk_i32 s14, 0xffdf
	s_waitcnt lgkmcnt(0)
	v_mad_i32_i24 v4, v1, s14, v66
	v_lshrrev_b32_e32 v3, 23, v3
	v_cmp_eq_u32_e32 vcc, 0, v4
	v_mul_u32_u24_e32 v3, 0x810, v3
	v_lshlrev_b32_e32 v4, 6, v4
	s_movk_i32 s14, 0xffd0
	v_add3_u32 v4, v3, v4, s14
	v_cndmask_b32_e32 v52, v4, v3, vcc
	v_cndmask_b32_e64 v72, 64, 16, vcc
; DEVINL float logsigf_(float z) { return fminf(z, 0.f) - __logf(1.f + __expf(-fabsf(z))); }
; DEVINL void gla_prep(const Params& p, char* smem, int r0, int T, int h, float (&bcum)[16]) {
;     ...
;   const float* gk = (const float*)(p.ws + OFF_GK);
;   __syncthreads();
;   {
;     int t = tid >> 2, c4 = (tid & 3) * 4;
;     const float4 v = *(const float4*)(gk + (size_t)(r0 + t) * 16 + c4);
;     *(float4*)(gkl + t * 16 + c4) = v;
;   }
;   float wreg[16];
; #pragma unroll
;   for (int r = 0; r < 16; ++r) wreg[r] = p.w_gk2[r * 256 + h * 64 + lane];
;   const float bias = p.b_gk[h * 64 + lane];
;   __syncthreads();
;   float run = 0.f;
; #pragma unroll
;   for (int i = 0; i < 16; ++i) {
;     const int t = 16 * w + i;
;     float z = bias;
; #pragma unroll
;     for (int r4 = 0; r4 < 4; ++r4) {
;       float4 gv = *(const float4*)(gkl + t * 16 + r4 * 4);
;       z += gv.x * wreg[r4 * 4] + gv.y * wreg[r4 * 4 + 1] + gv.z * wreg[r4 * 4 + 2] + gv.w * wreg[r4 * 4 + 3];
;     }
;     float lg = (t < T) ? logsigf_(z) * (1.f / 16.f) : 0.f;
; DEVINL void gla_passA(const Params& p, char* smem, int item) {
;     ...
;   const u16* kT = (const u16*)(p.ws + OFF_KT); const u16* vT = (const u16*)(p.ws + OFF_VT);
;   bf16x8 kr[2][4], vb[2][2];
; #pragma unroll
;   for (int ks = 0; ks < 2; ++ks) {
;     const int tb = ks * 32 + 8 * (lane >> 4);
; #pragma unroll
;     for (int nf = 0; nf < 2; ++nf)
;       vb[ks][nf] = *(const bf16x8*)(vT + (size_t)(ci.h * 128 + 32 * w + nf * 16 + (lane & 15)) * LDT + ci.r0 + tb);
; #pragma unroll
;     for (int mf = 0; mf < 4; ++mf)
;       kr[ks][mf] = *(const bf16x8*)(kT + (size_t)(ci.h * 64 + mf * 16 + (lane & 15)) * LDT + ci.r0 + tb);
;   }
.LBB0_545:
	s_or_b64 exec, exec, s[0:1]
	s_nop 0
	v_and_b32_e32 v8, 3, v1
	v_mov_b32_e32 v1, v0
	v_ashrrev_i32_e32 v53, 31, v52
	s_waitcnt lgkmcnt(1)
	v_ashrrev_i32_e32 v74, 6, v1
	v_lshrrev_b32_e32 v3, 1, v1
	v_and_b32_e32 v73, 24, v3
	v_lshlrev_b32_e32 v3, 5, v74
	s_waitcnt lgkmcnt(0)
	v_lshl_add_u32 v4, v8, 7, v3
	v_and_b32_e32 v65, 15, v1
	v_readlane_b32 s0, v194, 35
	v_or_b32_e32 v14, v4, v65
	s_waitcnt lgkmcnt(0)
	v_lshlrev_b64 v[4:5], 1, v[52:53]
	v_readlane_b32 s1, v194, 36
	v_lshlrev_b32_e32 v10, 1, v73
	v_mov_b32_e32 v11, v2
	v_lshl_add_u64 v[6:7], s[0:1], 0, v[4:5]
	v_readlane_b32 s0, v194, 55
	v_lshlrev_b32_e32 v58, 6, v8
	v_readlane_b32 s1, v194, 56
	v_lshl_add_u64 v[6:7], v[6:7], 0, v[10:11]
	v_or_b32_e32 v8, v58, v65
	v_lshl_add_u64 v[4:5], s[0:1], 0, v[4:5]
	v_mad_i64_i32 v[12:13], s[0:1], v14, s88, v[6:7]
	v_or_b32_e32 v14, 16, v14
	v_mul_u32_u24_e32 v8, 0x8980, v8
	v_mov_b32_e32 v9, v2
	v_mad_i64_i32 v[14:15], s[0:1], v14, s88, v[6:7]
	v_lshl_add_u64 v[4:5], v[4:5], 0, v[10:11]
	v_lshl_add_u64 v[16:17], v[4:5], 0, v[8:9]
	s_mov_b32 s0, 0x89000
	v_add_co_u32_e32 v18, vcc, s0, v16
	s_mov_b32 s0, 0x113000
	s_nop 0
	v_addc_co_u32_e32 v19, vcc, 0, v17, vcc
	v_add_co_u32_e32 v54, vcc, s0, v16
	s_mov_b32 s0, 0x19c000
	s_nop 0
	v_addc_co_u32_e32 v55, vcc, 0, v17, vcc
	v_add_co_u32_e32 v56, vcc, s0, v16
	v_mov_b32_e32 v67, v0
	s_nop 0
	v_addc_co_u32_e32 v57, vcc, 0, v17, vcc
	v_readlane_b32 s0, v194, 57
	v_readlane_b32 s1, v194, 58
	v_ashrrev_i32_e32 v210, 2, v0
	v_add_u32_e32 v208, v210, v52
	v_ashrrev_i32_e32 v209, 31, v208
	v_lshlrev_b64 v[208:209], 6, v[208:209]
	v_lshlrev_b32_e32 v210, 4, v0
	v_and_b32_e32 v210, 48, v210
	v_mov_b32_e32 v211, 0
	v_lshl_add_u64 v[208:209], s[0:1], 0, v[208:209]
	v_lshl_add_u64 v[208:209], v[208:209], 0, v[210:211]
	global_load_dwordx4 v[204:207], v[208:209], off
	global_load_dwordx4 v[28:31], v[12:13], off
	global_load_dwordx4 v[32:35], v[14:15], off
	global_load_dwordx4 v[48:51], v[16:17], off
	global_load_dwordx4 v[44:47], v[18:19], off offset:2048
	global_load_dwordx4 v[40:43], v[54:55], off
	global_load_dwordx4 v[36:39], v[56:57], off offset:2048
	global_load_dwordx4 v[4:7], v[12:13], off offset:64
	global_load_dwordx4 v[8:11], v[14:15], off offset:64
	global_load_dwordx4 v[24:27], v[16:17], off offset:64
	global_load_dwordx4 v[20:23], v[18:19], off offset:2112
	s_nop 0
	global_load_dwordx4 v[16:19], v[54:55], off offset:64
	global_load_dwordx4 v[12:15], v[56:57], off offset:2112
	v_readlane_b32 s0, v194, 57
	v_ashrrev_i32_e32 v59, 2, v67
	v_add_u32_e32 v52, v59, v52
	v_ashrrev_i32_e32 v53, 31, v52
	v_lshlrev_b64 v[52:53], 6, v[52:53]
	v_readlane_b32 s1, v194, 58
	v_lshlrev_b32_e32 v54, 4, v67
	v_and_b32_e32 v56, 48, v54
	v_lshl_add_u64 v[52:53], s[0:1], 0, v[52:53]
	v_mov_b32_e32 v57, v2
	v_lshl_add_u64 v[52:53], v[52:53], 0, v[56:57]
	s_barrier
	v_and_b32_e32 v75, 63, v67
	v_lshl_or_b32 v56, v59, 6, v56
	v_mov_b32_e32 v79, v2
	s_movk_i32 s0, 0x1000
	v_mov_b32_e32 v80, 0
	s_waitcnt vmcnt(12)
	ds_write_b128 v56, v[204:207]
	v_or_b32_e32 v52, v75, v58
	v_lshlrev_b32_e32 v78, 2, v52
	v_lshl_add_u64 v[76:77], s[68:69], 0, v[78:79]
	v_add_co_u32_e32 v54, vcc, s0, v76
	s_movk_i32 s0, 0x2000
	s_nop 0
	v_addc_co_u32_e32 v55, vcc, 0, v77, vcc
	v_add_co_u32_e32 v70, vcc, s0, v76
	global_load_dword v62, v78, s[68:69]
	global_load_dword v68, v78, s[68:69] offset:1024
	global_load_dword v56, v78, s[68:69] offset:2048
	global_load_dword v52, v78, s[68:69] offset:3072
	v_addc_co_u32_e32 v71, vcc, 0, v77, vcc
	global_load_dword v63, v[70:71], off offset:-4096
	global_load_dword v69, v[54:55], off offset:1024
	global_load_dword v57, v[54:55], off offset:2048
	global_load_dword v53, v[54:55], off offset:3072
	global_load_dword v58, v[70:71], off
	global_load_dword v60, v[70:71], off offset:1024
	s_nop 0
	global_load_dword v54, v[70:71], off offset:2048
	s_nop 0
	global_load_dword v70, v[70:71], off offset:3072
	s_movk_i32 s0, 0x3000
	v_add_co_u32_e32 v76, vcc, s0, v76
	s_nop 1
	v_addc_co_u32_e32 v77, vcc, 0, v77, vcc
	global_load_dword v59, v[76:77], off
	global_load_dword v61, v[76:77], off offset:1024
	global_load_dword v55, v[76:77], off offset:2048
	global_load_dword v71, v[76:77], off offset:3072
	v_ashrrev_i32_e32 v76, 6, v67
	global_load_dword v78, v78, s[70:71]
	v_lshlrev_b32_e32 v81, 4, v76
	v_cmp_lt_i32_e32 vcc, v81, v72
	v_mov_b32_e32 v77, 0
	s_waitcnt lgkmcnt(0)
	s_barrier
	s_and_saveexec_b64 s[36:37], vcc
	s_cbranch_execz .LBB0_547
	v_lshlrev_b32_e32 v77, 10, v76
	ds_read_b128 v[82:85], v77
	ds_read_b128 v[86:89], v77 offset:16
	ds_read_b128 v[106:109], v77 offset:32
	ds_read_b128 v[110:113], v77 offset:48
	s_mov_b32 s0, 0xbfb8aa3b
	s_waitcnt lgkmcnt(3)
	v_mov_b32_e32 v90, v82
	s_waitcnt lgkmcnt(2)
	v_mov_b32_e32 v91, v86
	v_mov_b32_e32 v86, v83
	s_waitcnt vmcnt(11)
	v_pk_mul_f32 v[82:83], v[68:69], v[86:87]
	v_mov_b32_e32 v86, v84
	v_pk_fma_f32 v[82:83], v[62:63], v[90:91], v[82:83]
	v_mov_b32_e32 v87, v88
	s_waitcnt vmcnt(10)
	v_pk_fma_f32 v[82:83], v[56:57], v[86:87], v[82:83]
	v_mov_b32_e32 v88, v85
	s_waitcnt vmcnt(9)
	v_pk_fma_f32 v[82:83], v[52:53], v[88:89], v[82:83]
	s_waitcnt vmcnt(0)
	v_add_f32_e32 v77, v78, v82
	v_add_f32_e32 v77, v77, v83
	s_waitcnt lgkmcnt(0)
	v_mov_b32_e32 v83, v110
	v_mov_b32_e32 v110, v107
	v_mov_b32_e32 v82, v106
	v_pk_mul_f32 v[84:85], v[60:61], v[110:111]
	s_nop 0
	v_pk_fma_f32 v[82:83], v[58:59], v[82:83], v[84:85]
	v_mov_b32_e32 v84, v108
	v_mov_b32_e32 v85, v112
	v_pk_fma_f32 v[82:83], v[54:55], v[84:85], v[82:83]
	v_mov_b32_e32 v112, v109
	v_pk_fma_f32 v[82:83], v[70:71], v[112:113], v[82:83]
	s_nop 0
	v_add_f32_e32 v77, v77, v82
	v_add_f32_e32 v77, v77, v83
	v_mul_f32_e64 v79, |v77|, s0
	v_exp_f32_e32 v79, v79
	s_mov_b32 s0, 0x3f317217
	v_min_f32_e32 v77, 0, v77
	v_add_f32_e32 v79, 1.0, v79
	v_cmp_gt_f32_e32 vcc, s33, v79
	s_nop 1
	v_cndmask_b32_e64 v82, 0, 32, vcc
	v_ldexp_f32 v79, v79, v82
	v_log_f32_e32 v79, v79
	s_nop 0
	v_mul_f32_e32 v82, 0x3f317217, v79
	v_fma_f32 v82, v79, s0, -v82
	v_fmac_f32_e32 v82, 0x3377d1cf, v79
	s_mov_b32 s0, 0x7f800000
	v_fmac_f32_e32 v82, 0x3f317217, v79
	v_cmp_lt_f32_e64 s[34:35], |v79|, s0
	s_mov_b32 s0, 0x3d800000
	s_nop 0
	v_cndmask_b32_e64 v79, v79, v82, s[34:35]
	v_cndmask_b32_e32 v82, 0, v126, vcc
	v_sub_f32_e32 v79, v79, v82
	v_sub_f32_e32 v77, v77, v79
	v_fma_f32 v77, v77, s0, 0
